# dft16 phase rewritten: real-input symmetric 16-pt DFT (half the FMAs), lane = token index so LDS b16 writes are conflict-free, both units loads in flight
# baseline (speedup 1.0000x reference)
; __device__ __forceinline__ void dft16_phase(const Ctx& X, const bf16_t* HN, bf16_t* GT) {
;     ...
;     for (int unit = X.bx; unit < 512; unit += X.G) {
;         const int b = unit >> 6, bt = (unit >> 4) & 3, ct = unit & 15, b0 = bt * 64, ch0 = ct * 64;
;         const int i = X.tid >> 3, cchunk = X.tid & 7;
;         u32x4 xin[16];
; #pragma unroll
;         for (int a = 0; a < 16; ++a) xin[a] = *(const u32x4*)(HN + (size_t)(b * 4096 + 256 * a + b0 + i) * 1024 + ch0 + cchunk * 8);
;         const int bp = b0 + i;
; #pragma unroll 1
;         for (int kq = 0; kq < 3; ++kq) {
;             __syncthreads();
; #pragma unroll 1
;             for (int kl = 0; kl < 4; ++kl) { const int ka = kq * 4 + kl; if (ka > 8) break;
;                 const float tang = (float)(bp * ka) * (1.0f / 2048.0f); const float tc = cospif(tang), ts = -sinpif(tang);
.LBB0_1441:
	s_or_b64 exec, exec, s[0:1]
	v_mov_b32_e32 v14, v206
	s_waitcnt lgkmcnt(0)
	s_barrier
	v_readfirstlane_b32 s12, v206
	s_lshr_b32 s12, s12, 6
	v_and_b32_e32 v1, 63, v206
	v_lshlrev_b32_e32 v2, 11, v1
	s_mul_i32 s0, s12, 0x240
	v_lshl_add_u32 v3, v1, 1, s0
	v_add_u32_e32 v4, 0x9000, v3
	v_lshrrev_b32_e32 v10, 3, v206
	v_and_b32_e32 v11, 7, v206
	s_movk_i32 s0, 0x90
	v_mul_lo_u32 v12, v10, s0
	v_lshl_add_u32 v5, v11, 4, v12
	v_add_u32_e32 v6, 0x9000, v5
	v_and_b32_e32 v12, 31, v10
	v_lshrrev_b32_e32 v13, 2, v12
	v_and_b32_e32 v12, 3, v12
	v_lshl_add_u32 v12, v13, 3, v12
	v_lshlrev_b32_e32 v12, 10, v12
	v_lshrrev_b32_e32 v13, 8, v206
	v_and_b32_e32 v13, 1, v13
	v_lshl_add_u32 v12, v13, 9, v12
	v_lshl_add_u32 v7, v11, 4, v12
	s_add_u32 s0, s2, 0
	s_lshr_b32 s1, s0, 6
	s_bfe_u32 s6, s0, 0x20004
	s_and_b32 s7, s0, 15
	s_lshl_b32 s28, s6, 6
	s_lshl_b32 s8, s1, 23
	s_lshl_b32 s9, s28, 11
	s_add_u32 s8, s8, s9
	s_lshl_b32 s9, s7, 7
	s_add_u32 s8, s8, s9
	s_lshl_b32 s9, s12, 4
	s_add_u32 s8, s8, s9
	s_add_u32 s24, s88, s8
	s_addc_u32 s25, s89, 0
	s_add_u32 s24, s24, 0x13000000
	s_addc_u32 s25, s25, 0
	s_mul_i32 s8, s1, 0x900000
	s_lshl_b32 s9, s7, 16
	s_add_u32 s8, s8, s9
	s_lshl_b32 s9, s28, 1
	s_add_u32 s8, s8, s9
	s_add_u32 s26, s88, s8
	s_addc_u32 s27, s89, 0
	s_add_u32 s26, s26, 0x7500000
	s_addc_u32 s27, s27, 0
	s_add_u32 s0, s2, 256
	s_lshr_b32 s1, s0, 6
	s_bfe_u32 s6, s0, 0x20004
	s_and_b32 s7, s0, 15
	s_lshl_b32 s38, s6, 6
	s_lshl_b32 s8, s1, 23
	s_lshl_b32 s9, s38, 11
	s_add_u32 s8, s8, s9
	s_lshl_b32 s9, s7, 7
	s_add_u32 s8, s8, s9
	s_lshl_b32 s9, s12, 4
	s_add_u32 s8, s8, s9
	s_add_u32 s34, s88, s8
	s_addc_u32 s35, s89, 0
	s_add_u32 s34, s34, 0x13000000
	s_addc_u32 s35, s35, 0
	s_mul_i32 s8, s1, 0x900000
	s_lshl_b32 s9, s7, 16
	s_add_u32 s8, s8, s9
	s_lshl_b32 s9, s38, 1
	s_add_u32 s8, s8, s9
	s_add_u32 s36, s88, s8
	s_addc_u32 s37, s89, 0
	s_add_u32 s36, s36, 0x7500000
	s_addc_u32 s37, s37, 0
	s_mov_b64 s[8:9], s[24:25]
	global_load_dwordx4 v[64:67], v2, s[8:9]
	s_add_u32 s8, s8, 0x80000
	s_addc_u32 s9, s9, 0
	global_load_dwordx4 v[68:71], v2, s[8:9]
	s_add_u32 s8, s8, 0x80000
	s_addc_u32 s9, s9, 0
	global_load_dwordx4 v[72:75], v2, s[8:9]
	s_add_u32 s8, s8, 0x80000
	s_addc_u32 s9, s9, 0
	global_load_dwordx4 v[76:79], v2, s[8:9]
	s_add_u32 s8, s8, 0x80000
	s_addc_u32 s9, s9, 0
	global_load_dwordx4 v[80:83], v2, s[8:9]
	s_add_u32 s8, s8, 0x80000
	s_addc_u32 s9, s9, 0
	global_load_dwordx4 v[84:87], v2, s[8:9]
	s_add_u32 s8, s8, 0x80000
	s_addc_u32 s9, s9, 0
	global_load_dwordx4 v[88:91], v2, s[8:9]
	s_add_u32 s8, s8, 0x80000
	s_addc_u32 s9, s9, 0
	global_load_dwordx4 v[92:95], v2, s[8:9]
	s_add_u32 s8, s8, 0x80000
	s_addc_u32 s9, s9, 0
	global_load_dwordx4 v[96:99], v2, s[8:9]
	s_add_u32 s8, s8, 0x80000
	s_addc_u32 s9, s9, 0
	global_load_dwordx4 v[100:103], v2, s[8:9]
	s_add_u32 s8, s8, 0x80000
	s_addc_u32 s9, s9, 0
	global_load_dwordx4 v[104:107], v2, s[8:9]
	s_add_u32 s8, s8, 0x80000
	s_addc_u32 s9, s9, 0
	global_load_dwordx4 v[108:111], v2, s[8:9]
	s_add_u32 s8, s8, 0x80000
	s_addc_u32 s9, s9, 0
	global_load_dwordx4 v[112:115], v2, s[8:9]
	s_add_u32 s8, s8, 0x80000
	s_addc_u32 s9, s9, 0
	global_load_dwordx4 v[116:119], v2, s[8:9]
	s_add_u32 s8, s8, 0x80000
	s_addc_u32 s9, s9, 0
	global_load_dwordx4 v[120:123], v2, s[8:9]
	s_add_u32 s8, s8, 0x80000
	s_addc_u32 s9, s9, 0
	global_load_dwordx4 v[124:127], v2, s[8:9]
	s_mov_b64 s[8:9], s[34:35]
	global_load_dwordx4 v[128:131], v2, s[8:9]
	s_add_u32 s8, s8, 0x80000
	s_addc_u32 s9, s9, 0
	global_load_dwordx4 v[132:135], v2, s[8:9]
	s_add_u32 s8, s8, 0x80000
	s_addc_u32 s9, s9, 0
	global_load_dwordx4 v[136:139], v2, s[8:9]
	s_add_u32 s8, s8, 0x80000
	s_addc_u32 s9, s9, 0
	global_load_dwordx4 v[140:143], v2, s[8:9]
	s_add_u32 s8, s8, 0x80000
	s_addc_u32 s9, s9, 0
	global_load_dwordx4 v[144:147], v2, s[8:9]
	s_add_u32 s8, s8, 0x80000
	s_addc_u32 s9, s9, 0
	global_load_dwordx4 v[148:151], v2, s[8:9]
	s_add_u32 s8, s8, 0x80000
	s_addc_u32 s9, s9, 0
	global_load_dwordx4 v[152:155], v2, s[8:9]
	s_add_u32 s8, s8, 0x80000
	s_addc_u32 s9, s9, 0
	global_load_dwordx4 v[156:159], v2, s[8:9]
	s_add_u32 s8, s8, 0x80000
	s_addc_u32 s9, s9, 0
	global_load_dwordx4 v[160:163], v2, s[8:9]
	s_add_u32 s8, s8, 0x80000
	s_addc_u32 s9, s9, 0
	global_load_dwordx4 v[164:167], v2, s[8:9]
	s_add_u32 s8, s8, 0x80000
	s_addc_u32 s9, s9, 0
	global_load_dwordx4 v[168:171], v2, s[8:9]
	s_add_u32 s8, s8, 0x80000
	s_addc_u32 s9, s9, 0
	global_load_dwordx4 v[172:175], v2, s[8:9]
	s_add_u32 s8, s8, 0x80000
	s_addc_u32 s9, s9, 0
	global_load_dwordx4 v[176:179], v2, s[8:9]
	s_add_u32 s8, s8, 0x80000
	s_addc_u32 s9, s9, 0
	global_load_dwordx4 v[180:183], v2, s[8:9]
	s_add_u32 s8, s8, 0x80000
	s_addc_u32 s9, s9, 0
	global_load_dwordx4 v[184:187], v2, s[8:9]
	s_add_u32 s8, s8, 0x80000
	s_addc_u32 s9, s9, 0
	global_load_dwordx4 v[188:191], v2, s[8:9]
	s_waitcnt vmcnt(16)
	v_add_u32_e32 v10, s28, v1
	v_cvt_f32_u32_e32 v10, v10
	v_mul_f32_e32 v11, 0x39800000, v10
	v_cos_f32_e32 v208, v11
	v_sin_f32_e32 v216, v11
	v_mul_f32_e32 v11, 0x3a000000, v10
	v_cos_f32_e32 v209, v11
	v_sin_f32_e32 v217, v11
	v_mul_f32_e32 v11, 0x3a400000, v10
	v_cos_f32_e32 v210, v11
	v_sin_f32_e32 v218, v11
	v_mul_f32_e32 v11, 0x3a800000, v10
	v_cos_f32_e32 v211, v11
	v_sin_f32_e32 v219, v11
	v_mul_f32_e32 v11, 0x3aa00000, v10
	v_cos_f32_e32 v212, v11
	v_sin_f32_e32 v220, v11
	v_mul_f32_e32 v11, 0x3ac00000, v10
	v_cos_f32_e32 v213, v11
	v_sin_f32_e32 v221, v11
	v_mul_f32_e32 v11, 0x3ae00000, v10
	v_cos_f32_e32 v214, v11
	v_sin_f32_e32 v222, v11
	v_mul_f32_e32 v11, 0x3b000000, v10
	v_cos_f32_e32 v215, v11
	v_sin_f32_e32 v223, v11
	s_barrier
; __device__ __forceinline__ bf16_t f2bf(float f) { return (bf16_t)(cvt_pk_bf16(f, 0.f) & 0xffffu); }
; __device__ __forceinline__ void dft16_phase(const Ctx& X, const bf16_t* HN, bf16_t* GT) {
;     ...
;                 for (int a = 0; a < 16; ++a) { const int m = (a * ka) & 15; cw[a] = T16[m]; sw[a] = T16[16 + m]; }
; #pragma unroll
;                 for (int e = 0; e < 8; ++e) { float re = 0.f, im = 0.f;
; #pragma unroll
;                     for (int a = 0; a < 16; ++a) { const unsigned wv = xin[a][e >> 1]; const float x = (e & 1) ? bf2f(wv >> 16) : bf2f(wv & 0xffffu); re += x * cw[a]; im -= x * sw[a]; }
;                     const float orr = re * tc - im * ts, oi = re * ts + im * tc;
;                     tile[((kl * 2 + 0) * 64 + cchunk * 8 + e) * 72 + i] = f2bf(orr); tile[((kl * 2 + 1) * 64 + cchunk * 8 + e) * 72 + i] = f2bf(oi); } }
	v_lshlrev_b32_e32 v16, 16, v64
	v_lshlrev_b32_e32 v17, 16, v68
	v_lshlrev_b32_e32 v18, 16, v72
	v_lshlrev_b32_e32 v19, 16, v76
	v_lshlrev_b32_e32 v20, 16, v80
	v_lshlrev_b32_e32 v21, 16, v84
	v_lshlrev_b32_e32 v22, 16, v88
	v_lshlrev_b32_e32 v23, 16, v92
	v_lshlrev_b32_e32 v24, 16, v96
	v_lshlrev_b32_e32 v25, 16, v100
	v_lshlrev_b32_e32 v26, 16, v104
	v_lshlrev_b32_e32 v27, 16, v108
	v_lshlrev_b32_e32 v28, 16, v112
	v_lshlrev_b32_e32 v29, 16, v116
	v_lshlrev_b32_e32 v30, 16, v120
	v_lshlrev_b32_e32 v31, 16, v124
	v_add_f32_e32 v32, v17, v31
	v_sub_f32_e32 v40, v17, v31
	v_add_f32_e32 v33, v18, v30
	v_sub_f32_e32 v41, v18, v30
	v_add_f32_e32 v34, v19, v29
	v_sub_f32_e32 v42, v19, v29
	v_add_f32_e32 v35, v20, v28
	v_sub_f32_e32 v43, v20, v28
	v_add_f32_e32 v36, v21, v27
	v_sub_f32_e32 v44, v21, v27
	v_add_f32_e32 v37, v22, v26
	v_sub_f32_e32 v45, v22, v26
	v_add_f32_e32 v38, v23, v25
	v_sub_f32_e32 v46, v23, v25
	v_add_f32_e32 v48, v16, v24
	v_add_f32_e32 v48, v48, v32
	v_add_f32_e32 v48, v48, v33
	v_add_f32_e32 v48, v48, v34
	v_add_f32_e32 v48, v48, v35
	v_add_f32_e32 v48, v48, v36
	v_add_f32_e32 v48, v48, v37
	v_add_f32_e32 v48, v48, v38
	v_cvt_pk_bf16_f32 v52, v48, 0
	ds_write_b16 v3, v52 offset:0
	ds_write_b16_d16_hi v3, v52 offset:4608
	v_sub_f32_e32 v48, v16, v24
	v_fmac_f32_e32 v48, 0x3f6c835e, v32
	v_fmac_f32_e32 v48, 0x3f3504f3, v33
	v_fmac_f32_e32 v48, 0x3ec3ef15, v34
	v_fmac_f32_e32 v48, 0xbec3ef15, v36
	v_fmac_f32_e32 v48, 0xbf3504f3, v37
	v_fmac_f32_e32 v48, 0xbf6c835e, v38
	v_mul_f32_e32 v49, 0xbec3ef15, v40
	v_fmac_f32_e32 v49, 0xbf3504f3, v41
	v_fmac_f32_e32 v49, 0xbf6c835e, v42
	v_sub_f32_e32 v49, v49, v43
	v_fmac_f32_e32 v49, 0xbf6c835e, v44
	v_fmac_f32_e32 v49, 0xbf3504f3, v45
	v_fmac_f32_e32 v49, 0xbec3ef15, v46
	v_mul_f32_e32 v50, v49, v216
	v_fmac_f32_e32 v50, v48, v208
	v_mul_f32_e32 v51, v48, v216
	v_fma_f32 v51, v49, v208, -v51
	v_cvt_pk_bf16_f32 v52, v50, v51
	ds_write_b16 v3, v52 offset:9216
	ds_write_b16_d16_hi v3, v52 offset:13824
	v_add_f32_e32 v48, v16, v24
	v_fmac_f32_e32 v48, 0x3f3504f3, v32
	v_fmac_f32_e32 v48, 0xbf3504f3, v34
	v_sub_f32_e32 v48, v48, v35
	v_fmac_f32_e32 v48, 0xbf3504f3, v36
	v_fmac_f32_e32 v48, 0x3f3504f3, v38
	v_mul_f32_e32 v49, 0xbf3504f3, v40
	v_sub_f32_e32 v49, v49, v41
	v_fmac_f32_e32 v49, 0xbf3504f3, v42
	v_fmac_f32_e32 v49, 0x3f3504f3, v44
	v_add_f32_e32 v49, v49, v45
	v_fmac_f32_e32 v49, 0x3f3504f3, v46
	v_mul_f32_e32 v50, v49, v217
	v_fmac_f32_e32 v50, v48, v209
	v_mul_f32_e32 v51, v48, v217
	v_fma_f32 v51, v49, v209, -v51
	v_cvt_pk_bf16_f32 v52, v50, v51
	ds_write_b16 v3, v52 offset:18432
	ds_write_b16_d16_hi v3, v52 offset:23040
	v_sub_f32_e32 v48, v16, v24
	v_fmac_f32_e32 v48, 0x3ec3ef15, v32
	v_fmac_f32_e32 v48, 0xbf3504f3, v33
	v_fmac_f32_e32 v48, 0xbf6c835e, v34
	v_fmac_f32_e32 v48, 0x3f6c835e, v36
	v_fmac_f32_e32 v48, 0x3f3504f3, v37
	v_fmac_f32_e32 v48, 0xbec3ef15, v38
	v_mul_f32_e32 v49, 0xbf6c835e, v40
	v_fmac_f32_e32 v49, 0xbf3504f3, v41
	v_fmac_f32_e32 v49, 0x3ec3ef15, v42
	v_add_f32_e32 v49, v49, v43
	v_fmac_f32_e32 v49, 0x3ec3ef15, v44
	v_fmac_f32_e32 v49, 0xbf3504f3, v45
	v_fmac_f32_e32 v49, 0xbf6c835e, v46
	v_mul_f32_e32 v50, v49, v218
	v_fmac_f32_e32 v50, v48, v210
	v_mul_f32_e32 v51, v48, v218
	v_fma_f32 v51, v49, v210, -v51
	v_cvt_pk_bf16_f32 v52, v50, v51
	ds_write_b16 v3, v52 offset:27648
	ds_write_b16_d16_hi v3, v52 offset:32256
	v_add_f32_e32 v48, v16, v24
	v_sub_f32_e32 v48, v48, v33
	v_add_f32_e32 v48, v48, v35
	v_sub_f32_e32 v48, v48, v37
	v_sub_f32_e32 v49, 0, v40
	v_add_f32_e32 v49, v49, v42
	v_sub_f32_e32 v49, v49, v44
	v_add_f32_e32 v49, v49, v46
	v_mul_f32_e32 v50, v49, v219
	v_fmac_f32_e32 v50, v48, v211
	v_mul_f32_e32 v51, v48, v219
	v_fma_f32 v51, v49, v211, -v51
	v_cvt_pk_bf16_f32 v52, v50, v51
	ds_write_b16 v4, v52 offset:0
	ds_write_b16_d16_hi v4, v52 offset:4608
	v_sub_f32_e32 v48, v16, v24
	v_fmac_f32_e32 v48, 0xbec3ef15, v32
	v_fmac_f32_e32 v48, 0xbf3504f3, v33
	v_fmac_f32_e32 v48, 0x3f6c835e, v34
	v_fmac_f32_e32 v48, 0xbf6c835e, v36
	v_fmac_f32_e32 v48, 0x3f3504f3, v37
	v_fmac_f32_e32 v48, 0x3ec3ef15, v38
	v_mul_f32_e32 v49, 0xbf6c835e, v40
	v_fmac_f32_e32 v49, 0x3f3504f3, v41
	v_fmac_f32_e32 v49, 0x3ec3ef15, v42
	v_sub_f32_e32 v49, v49, v43
	v_fmac_f32_e32 v49, 0x3ec3ef15, v44
	v_fmac_f32_e32 v49, 0x3f3504f3, v45
	v_fmac_f32_e32 v49, 0xbf6c835e, v46
	v_mul_f32_e32 v50, v49, v220
	v_fmac_f32_e32 v50, v48, v212
	v_mul_f32_e32 v51, v48, v220
	v_fma_f32 v51, v49, v212, -v51
	v_cvt_pk_bf16_f32 v52, v50, v51
	ds_write_b16 v4, v52 offset:9216
	ds_write_b16_d16_hi v4, v52 offset:13824
	v_add_f32_e32 v48, v16, v24
	v_fmac_f32_e32 v48, 0xbf3504f3, v32
	v_fmac_f32_e32 v48, 0x3f3504f3, v34
	v_sub_f32_e32 v48, v48, v35
	v_fmac_f32_e32 v48, 0x3f3504f3, v36
	v_fmac_f32_e32 v48, 0xbf3504f3, v38
	v_mul_f32_e32 v49, 0xbf3504f3, v40
	v_add_f32_e32 v49, v49, v41
	v_fmac_f32_e32 v49, 0xbf3504f3, v42
	v_fmac_f32_e32 v49, 0x3f3504f3, v44
	v_sub_f32_e32 v49, v49, v45
	v_fmac_f32_e32 v49, 0x3f3504f3, v46
	v_mul_f32_e32 v50, v49, v221
	v_fmac_f32_e32 v50, v48, v213
	v_mul_f32_e32 v51, v48, v221
	v_fma_f32 v51, v49, v213, -v51
	v_cvt_pk_bf16_f32 v52, v50, v51
	ds_write_b16 v4, v52 offset:18432
	ds_write_b16_d16_hi v4, v52 offset:23040
	v_sub_f32_e32 v48, v16, v24
	v_fmac_f32_e32 v48, 0xbf6c835e, v32
	v_fmac_f32_e32 v48, 0x3f3504f3, v33
	v_fmac_f32_e32 v48, 0xbec3ef15, v34
	v_fmac_f32_e32 v48, 0x3ec3ef15, v36
	v_fmac_f32_e32 v48, 0xbf3504f3, v37
	v_fmac_f32_e32 v48, 0x3f6c835e, v38
	v_mul_f32_e32 v49, 0xbec3ef15, v40
	v_fmac_f32_e32 v49, 0x3f3504f3, v41
	v_fmac_f32_e32 v49, 0xbf6c835e, v42
	v_add_f32_e32 v49, v49, v43
	v_fmac_f32_e32 v49, 0xbf6c835e, v44
; __device__ __forceinline__ bf16_t f2bf(float f) { return (bf16_t)(cvt_pk_bf16(f, 0.f) & 0xffffu); }
; __device__ __forceinline__ void dft16_phase(const Ctx& X, const bf16_t* HN, bf16_t* GT) {
;     ...
;                 for (int e = 0; e < 8; ++e) { float re = 0.f, im = 0.f;
; #pragma unroll
;                     for (int a = 0; a < 16; ++a) { const unsigned wv = xin[a][e >> 1]; const float x = (e & 1) ? bf2f(wv >> 16) : bf2f(wv & 0xffffu); re += x * cw[a]; im -= x * sw[a]; }
;                     const float orr = re * tc - im * ts, oi = re * ts + im * tc;
;                     tile[((kl * 2 + 0) * 64 + cchunk * 8 + e) * 72 + i] = f2bf(orr); tile[((kl * 2 + 1) * 64 + cchunk * 8 + e) * 72 + i] = f2bf(oi); } }
	v_fmac_f32_e32 v49, 0x3f3504f3, v45
	v_fmac_f32_e32 v49, 0xbec3ef15, v46
	v_mul_f32_e32 v50, v49, v222
	v_fmac_f32_e32 v50, v48, v214
	v_mul_f32_e32 v51, v48, v222
	v_fma_f32 v51, v49, v214, -v51
	v_cvt_pk_bf16_f32 v52, v50, v51
	ds_write_b16 v4, v52 offset:27648
	ds_write_b16_d16_hi v4, v52 offset:32256
	v_add_f32_e32 v48, v16, v24
	v_sub_f32_e32 v48, v48, v32
	v_add_f32_e32 v48, v48, v33
	v_sub_f32_e32 v48, v48, v34
	v_add_f32_e32 v48, v48, v35
	v_sub_f32_e32 v48, v48, v36
	v_add_f32_e32 v48, v48, v37
	v_sub_f32_e32 v48, v48, v38
	v_mul_f32_e32 v50, v48, v215
	v_mul_f32_e32 v51, v48, v223
	v_sub_f32_e32 v51, 0, v51
	v_cvt_pk_bf16_f32 v52, v50, v51
	ds_write_b16 v4, v52 offset:36864
	ds_write_b16_d16_hi v4, v52 offset:41472
	v_and_b32_e32 v16, 0xffff0000, v64
	v_and_b32_e32 v17, 0xffff0000, v68
	v_and_b32_e32 v18, 0xffff0000, v72
	v_and_b32_e32 v19, 0xffff0000, v76
	v_and_b32_e32 v20, 0xffff0000, v80
	v_and_b32_e32 v21, 0xffff0000, v84
	v_and_b32_e32 v22, 0xffff0000, v88
	v_and_b32_e32 v23, 0xffff0000, v92
	v_and_b32_e32 v24, 0xffff0000, v96
	v_and_b32_e32 v25, 0xffff0000, v100
	v_and_b32_e32 v26, 0xffff0000, v104
	v_and_b32_e32 v27, 0xffff0000, v108
	v_and_b32_e32 v28, 0xffff0000, v112
	v_and_b32_e32 v29, 0xffff0000, v116
	v_and_b32_e32 v30, 0xffff0000, v120
	v_and_b32_e32 v31, 0xffff0000, v124
	v_add_f32_e32 v32, v17, v31
	v_sub_f32_e32 v40, v17, v31
	v_add_f32_e32 v33, v18, v30
	v_sub_f32_e32 v41, v18, v30
	v_add_f32_e32 v34, v19, v29
	v_sub_f32_e32 v42, v19, v29
	v_add_f32_e32 v35, v20, v28
	v_sub_f32_e32 v43, v20, v28
	v_add_f32_e32 v36, v21, v27
	v_sub_f32_e32 v44, v21, v27
	v_add_f32_e32 v37, v22, v26
	v_sub_f32_e32 v45, v22, v26
	v_add_f32_e32 v38, v23, v25
	v_sub_f32_e32 v46, v23, v25
	v_add_f32_e32 v48, v16, v24
	v_add_f32_e32 v48, v48, v32
	v_add_f32_e32 v48, v48, v33
	v_add_f32_e32 v48, v48, v34
	v_add_f32_e32 v48, v48, v35
	v_add_f32_e32 v48, v48, v36
	v_add_f32_e32 v48, v48, v37
	v_add_f32_e32 v48, v48, v38
	v_cvt_pk_bf16_f32 v52, v48, 0
	ds_write_b16 v3, v52 offset:144
	ds_write_b16_d16_hi v3, v52 offset:4752
	v_sub_f32_e32 v48, v16, v24
	v_fmac_f32_e32 v48, 0x3f6c835e, v32
	v_fmac_f32_e32 v48, 0x3f3504f3, v33
	v_fmac_f32_e32 v48, 0x3ec3ef15, v34
	v_fmac_f32_e32 v48, 0xbec3ef15, v36
	v_fmac_f32_e32 v48, 0xbf3504f3, v37
	v_fmac_f32_e32 v48, 0xbf6c835e, v38
	v_mul_f32_e32 v49, 0xbec3ef15, v40
	v_fmac_f32_e32 v49, 0xbf3504f3, v41
	v_fmac_f32_e32 v49, 0xbf6c835e, v42
	v_sub_f32_e32 v49, v49, v43
	v_fmac_f32_e32 v49, 0xbf6c835e, v44
	v_fmac_f32_e32 v49, 0xbf3504f3, v45
	v_fmac_f32_e32 v49, 0xbec3ef15, v46
	v_mul_f32_e32 v50, v49, v216
	v_fmac_f32_e32 v50, v48, v208
	v_mul_f32_e32 v51, v48, v216
	v_fma_f32 v51, v49, v208, -v51
	v_cvt_pk_bf16_f32 v52, v50, v51
	ds_write_b16 v3, v52 offset:9360
	ds_write_b16_d16_hi v3, v52 offset:13968
	v_add_f32_e32 v48, v16, v24
	v_fmac_f32_e32 v48, 0x3f3504f3, v32
	v_fmac_f32_e32 v48, 0xbf3504f3, v34
	v_sub_f32_e32 v48, v48, v35
	v_fmac_f32_e32 v48, 0xbf3504f3, v36
	v_fmac_f32_e32 v48, 0x3f3504f3, v38
	v_mul_f32_e32 v49, 0xbf3504f3, v40
	v_sub_f32_e32 v49, v49, v41
	v_fmac_f32_e32 v49, 0xbf3504f3, v42
	v_fmac_f32_e32 v49, 0x3f3504f3, v44
	v_add_f32_e32 v49, v49, v45
	v_fmac_f32_e32 v49, 0x3f3504f3, v46
	v_mul_f32_e32 v50, v49, v217
	v_fmac_f32_e32 v50, v48, v209
	v_mul_f32_e32 v51, v48, v217
	v_fma_f32 v51, v49, v209, -v51
	v_cvt_pk_bf16_f32 v52, v50, v51
	ds_write_b16 v3, v52 offset:18576
	ds_write_b16_d16_hi v3, v52 offset:23184
	v_sub_f32_e32 v48, v16, v24
	v_fmac_f32_e32 v48, 0x3ec3ef15, v32
	v_fmac_f32_e32 v48, 0xbf3504f3, v33
	v_fmac_f32_e32 v48, 0xbf6c835e, v34
	v_fmac_f32_e32 v48, 0x3f6c835e, v36
	v_fmac_f32_e32 v48, 0x3f3504f3, v37
	v_fmac_f32_e32 v48, 0xbec3ef15, v38
	v_mul_f32_e32 v49, 0xbf6c835e, v40
	v_fmac_f32_e32 v49, 0xbf3504f3, v41
	v_fmac_f32_e32 v49, 0x3ec3ef15, v42
	v_add_f32_e32 v49, v49, v43
	v_fmac_f32_e32 v49, 0x3ec3ef15, v44
	v_fmac_f32_e32 v49, 0xbf3504f3, v45
	v_fmac_f32_e32 v49, 0xbf6c835e, v46
	v_mul_f32_e32 v50, v49, v218
	v_fmac_f32_e32 v50, v48, v210
	v_mul_f32_e32 v51, v48, v218
	v_fma_f32 v51, v49, v210, -v51
	v_cvt_pk_bf16_f32 v52, v50, v51
	ds_write_b16 v3, v52 offset:27792
	ds_write_b16_d16_hi v3, v52 offset:32400
	v_add_f32_e32 v48, v16, v24
	v_sub_f32_e32 v48, v48, v33
	v_add_f32_e32 v48, v48, v35
	v_sub_f32_e32 v48, v48, v37
	v_sub_f32_e32 v49, 0, v40
	v_add_f32_e32 v49, v49, v42
	v_sub_f32_e32 v49, v49, v44
	v_add_f32_e32 v49, v49, v46
	v_mul_f32_e32 v50, v49, v219
	v_fmac_f32_e32 v50, v48, v211
	v_mul_f32_e32 v51, v48, v219
	v_fma_f32 v51, v49, v211, -v51
	v_cvt_pk_bf16_f32 v52, v50, v51
	ds_write_b16 v4, v52 offset:144
	ds_write_b16_d16_hi v4, v52 offset:4752
	v_sub_f32_e32 v48, v16, v24
	v_fmac_f32_e32 v48, 0xbec3ef15, v32
	v_fmac_f32_e32 v48, 0xbf3504f3, v33
	v_fmac_f32_e32 v48, 0x3f6c835e, v34
	v_fmac_f32_e32 v48, 0xbf6c835e, v36
	v_fmac_f32_e32 v48, 0x3f3504f3, v37
	v_fmac_f32_e32 v48, 0x3ec3ef15, v38
	v_mul_f32_e32 v49, 0xbf6c835e, v40
	v_fmac_f32_e32 v49, 0x3f3504f3, v41
	v_fmac_f32_e32 v49, 0x3ec3ef15, v42
	v_sub_f32_e32 v49, v49, v43
	v_fmac_f32_e32 v49, 0x3ec3ef15, v44
	v_fmac_f32_e32 v49, 0x3f3504f3, v45
	v_fmac_f32_e32 v49, 0xbf6c835e, v46
	v_mul_f32_e32 v50, v49, v220
	v_fmac_f32_e32 v50, v48, v212
	v_mul_f32_e32 v51, v48, v220
	v_fma_f32 v51, v49, v212, -v51
	v_cvt_pk_bf16_f32 v52, v50, v51
	ds_write_b16 v4, v52 offset:9360
	ds_write_b16_d16_hi v4, v52 offset:13968
	v_add_f32_e32 v48, v16, v24
	v_fmac_f32_e32 v48, 0xbf3504f3, v32
	v_fmac_f32_e32 v48, 0x3f3504f3, v34
	v_sub_f32_e32 v48, v48, v35
	v_fmac_f32_e32 v48, 0x3f3504f3, v36
	v_fmac_f32_e32 v48, 0xbf3504f3, v38
	v_mul_f32_e32 v49, 0xbf3504f3, v40
	v_add_f32_e32 v49, v49, v41
; __device__ __forceinline__ bf16_t f2bf(float f) { return (bf16_t)(cvt_pk_bf16(f, 0.f) & 0xffffu); }
; __device__ __forceinline__ void dft16_phase(const Ctx& X, const bf16_t* HN, bf16_t* GT) {
;     ...
;                 for (int e = 0; e < 8; ++e) { float re = 0.f, im = 0.f;
; #pragma unroll
;                     for (int a = 0; a < 16; ++a) { const unsigned wv = xin[a][e >> 1]; const float x = (e & 1) ? bf2f(wv >> 16) : bf2f(wv & 0xffffu); re += x * cw[a]; im -= x * sw[a]; }
;                     const float orr = re * tc - im * ts, oi = re * ts + im * tc;
;                     tile[((kl * 2 + 0) * 64 + cchunk * 8 + e) * 72 + i] = f2bf(orr); tile[((kl * 2 + 1) * 64 + cchunk * 8 + e) * 72 + i] = f2bf(oi); } }
	v_fmac_f32_e32 v49, 0xbf3504f3, v42
	v_fmac_f32_e32 v49, 0x3f3504f3, v44
	v_sub_f32_e32 v49, v49, v45
	v_fmac_f32_e32 v49, 0x3f3504f3, v46
	v_mul_f32_e32 v50, v49, v221
	v_fmac_f32_e32 v50, v48, v213
	v_mul_f32_e32 v51, v48, v221
	v_fma_f32 v51, v49, v213, -v51
	v_cvt_pk_bf16_f32 v52, v50, v51
	ds_write_b16 v4, v52 offset:18576
	ds_write_b16_d16_hi v4, v52 offset:23184
	v_sub_f32_e32 v48, v16, v24
	v_fmac_f32_e32 v48, 0xbf6c835e, v32
	v_fmac_f32_e32 v48, 0x3f3504f3, v33
	v_fmac_f32_e32 v48, 0xbec3ef15, v34
	v_fmac_f32_e32 v48, 0x3ec3ef15, v36
	v_fmac_f32_e32 v48, 0xbf3504f3, v37
	v_fmac_f32_e32 v48, 0x3f6c835e, v38
	v_mul_f32_e32 v49, 0xbec3ef15, v40
	v_fmac_f32_e32 v49, 0x3f3504f3, v41
	v_fmac_f32_e32 v49, 0xbf6c835e, v42
	v_add_f32_e32 v49, v49, v43
	v_fmac_f32_e32 v49, 0xbf6c835e, v44
	v_fmac_f32_e32 v49, 0x3f3504f3, v45
	v_fmac_f32_e32 v49, 0xbec3ef15, v46
	v_mul_f32_e32 v50, v49, v222
	v_fmac_f32_e32 v50, v48, v214
	v_mul_f32_e32 v51, v48, v222
	v_fma_f32 v51, v49, v214, -v51
	v_cvt_pk_bf16_f32 v52, v50, v51
	ds_write_b16 v4, v52 offset:27792
	ds_write_b16_d16_hi v4, v52 offset:32400
	v_add_f32_e32 v48, v16, v24
	v_sub_f32_e32 v48, v48, v32
	v_add_f32_e32 v48, v48, v33
	v_sub_f32_e32 v48, v48, v34
	v_add_f32_e32 v48, v48, v35
	v_sub_f32_e32 v48, v48, v36
	v_add_f32_e32 v48, v48, v37
	v_sub_f32_e32 v48, v48, v38
	v_mul_f32_e32 v50, v48, v215
	v_mul_f32_e32 v51, v48, v223
	v_sub_f32_e32 v51, 0, v51
	v_cvt_pk_bf16_f32 v52, v50, v51
	ds_write_b16 v4, v52 offset:37008
	ds_write_b16_d16_hi v4, v52 offset:41616
	v_lshlrev_b32_e32 v16, 16, v65
	v_lshlrev_b32_e32 v17, 16, v69
	v_lshlrev_b32_e32 v18, 16, v73
	v_lshlrev_b32_e32 v19, 16, v77
	v_lshlrev_b32_e32 v20, 16, v81
	v_lshlrev_b32_e32 v21, 16, v85
	v_lshlrev_b32_e32 v22, 16, v89
	v_lshlrev_b32_e32 v23, 16, v93
	v_lshlrev_b32_e32 v24, 16, v97
	v_lshlrev_b32_e32 v25, 16, v101
	v_lshlrev_b32_e32 v26, 16, v105
	v_lshlrev_b32_e32 v27, 16, v109
	v_lshlrev_b32_e32 v28, 16, v113
	v_lshlrev_b32_e32 v29, 16, v117
	v_lshlrev_b32_e32 v30, 16, v121
	v_lshlrev_b32_e32 v31, 16, v125
	v_add_f32_e32 v32, v17, v31
	v_sub_f32_e32 v40, v17, v31
	v_add_f32_e32 v33, v18, v30
	v_sub_f32_e32 v41, v18, v30
	v_add_f32_e32 v34, v19, v29
	v_sub_f32_e32 v42, v19, v29
	v_add_f32_e32 v35, v20, v28
	v_sub_f32_e32 v43, v20, v28
	v_add_f32_e32 v36, v21, v27
	v_sub_f32_e32 v44, v21, v27
	v_add_f32_e32 v37, v22, v26
	v_sub_f32_e32 v45, v22, v26
	v_add_f32_e32 v38, v23, v25
	v_sub_f32_e32 v46, v23, v25
	v_add_f32_e32 v48, v16, v24
	v_add_f32_e32 v48, v48, v32
	v_add_f32_e32 v48, v48, v33
	v_add_f32_e32 v48, v48, v34
	v_add_f32_e32 v48, v48, v35
	v_add_f32_e32 v48, v48, v36
	v_add_f32_e32 v48, v48, v37
	v_add_f32_e32 v48, v48, v38
	v_cvt_pk_bf16_f32 v52, v48, 0
	ds_write_b16 v3, v52 offset:288
	ds_write_b16_d16_hi v3, v52 offset:4896
	v_sub_f32_e32 v48, v16, v24
	v_fmac_f32_e32 v48, 0x3f6c835e, v32
	v_fmac_f32_e32 v48, 0x3f3504f3, v33
	v_fmac_f32_e32 v48, 0x3ec3ef15, v34
	v_fmac_f32_e32 v48, 0xbec3ef15, v36
	v_fmac_f32_e32 v48, 0xbf3504f3, v37
	v_fmac_f32_e32 v48, 0xbf6c835e, v38
	v_mul_f32_e32 v49, 0xbec3ef15, v40
	v_fmac_f32_e32 v49, 0xbf3504f3, v41
	v_fmac_f32_e32 v49, 0xbf6c835e, v42
	v_sub_f32_e32 v49, v49, v43
	v_fmac_f32_e32 v49, 0xbf6c835e, v44
	v_fmac_f32_e32 v49, 0xbf3504f3, v45
	v_fmac_f32_e32 v49, 0xbec3ef15, v46
	v_mul_f32_e32 v50, v49, v216
	v_fmac_f32_e32 v50, v48, v208
	v_mul_f32_e32 v51, v48, v216
	v_fma_f32 v51, v49, v208, -v51
	v_cvt_pk_bf16_f32 v52, v50, v51
	ds_write_b16 v3, v52 offset:9504
	ds_write_b16_d16_hi v3, v52 offset:14112
	v_add_f32_e32 v48, v16, v24
	v_fmac_f32_e32 v48, 0x3f3504f3, v32
	v_fmac_f32_e32 v48, 0xbf3504f3, v34
	v_sub_f32_e32 v48, v48, v35
	v_fmac_f32_e32 v48, 0xbf3504f3, v36
	v_fmac_f32_e32 v48, 0x3f3504f3, v38
	v_mul_f32_e32 v49, 0xbf3504f3, v40
	v_sub_f32_e32 v49, v49, v41
	v_fmac_f32_e32 v49, 0xbf3504f3, v42
	v_fmac_f32_e32 v49, 0x3f3504f3, v44
	v_add_f32_e32 v49, v49, v45
	v_fmac_f32_e32 v49, 0x3f3504f3, v46
	v_mul_f32_e32 v50, v49, v217
	v_fmac_f32_e32 v50, v48, v209
	v_mul_f32_e32 v51, v48, v217
	v_fma_f32 v51, v49, v209, -v51
	v_cvt_pk_bf16_f32 v52, v50, v51
	ds_write_b16 v3, v52 offset:18720
	ds_write_b16_d16_hi v3, v52 offset:23328
	v_sub_f32_e32 v48, v16, v24
	v_fmac_f32_e32 v48, 0x3ec3ef15, v32
	v_fmac_f32_e32 v48, 0xbf3504f3, v33
	v_fmac_f32_e32 v48, 0xbf6c835e, v34
	v_fmac_f32_e32 v48, 0x3f6c835e, v36
	v_fmac_f32_e32 v48, 0x3f3504f3, v37
	v_fmac_f32_e32 v48, 0xbec3ef15, v38
	v_mul_f32_e32 v49, 0xbf6c835e, v40
	v_fmac_f32_e32 v49, 0xbf3504f3, v41
	v_fmac_f32_e32 v49, 0x3ec3ef15, v42
	v_add_f32_e32 v49, v49, v43
	v_fmac_f32_e32 v49, 0x3ec3ef15, v44
	v_fmac_f32_e32 v49, 0xbf3504f3, v45
	v_fmac_f32_e32 v49, 0xbf6c835e, v46
	v_mul_f32_e32 v50, v49, v218
	v_fmac_f32_e32 v50, v48, v210
	v_mul_f32_e32 v51, v48, v218
	v_fma_f32 v51, v49, v210, -v51
	v_cvt_pk_bf16_f32 v52, v50, v51
	ds_write_b16 v3, v52 offset:27936
	ds_write_b16_d16_hi v3, v52 offset:32544
	v_add_f32_e32 v48, v16, v24
	v_sub_f32_e32 v48, v48, v33
	v_add_f32_e32 v48, v48, v35
	v_sub_f32_e32 v48, v48, v37
	v_sub_f32_e32 v49, 0, v40
	v_add_f32_e32 v49, v49, v42
	v_sub_f32_e32 v49, v49, v44
	v_add_f32_e32 v49, v49, v46
	v_mul_f32_e32 v50, v49, v219
	v_fmac_f32_e32 v50, v48, v211
	v_mul_f32_e32 v51, v48, v219
	v_fma_f32 v51, v49, v211, -v51
	v_cvt_pk_bf16_f32 v52, v50, v51
	ds_write_b16 v4, v52 offset:288
	ds_write_b16_d16_hi v4, v52 offset:4896
	v_sub_f32_e32 v48, v16, v24
	v_fmac_f32_e32 v48, 0xbec3ef15, v32
	v_fmac_f32_e32 v48, 0xbf3504f3, v33
	v_fmac_f32_e32 v48, 0x3f6c835e, v34
	v_fmac_f32_e32 v48, 0xbf6c835e, v36
	v_fmac_f32_e32 v48, 0x3f3504f3, v37
	v_fmac_f32_e32 v48, 0x3ec3ef15, v38
	v_mul_f32_e32 v49, 0xbf6c835e, v40
; __device__ __forceinline__ bf16_t f2bf(float f) { return (bf16_t)(cvt_pk_bf16(f, 0.f) & 0xffffu); }
; __device__ __forceinline__ void dft16_phase(const Ctx& X, const bf16_t* HN, bf16_t* GT) {
;     ...
;                 for (int e = 0; e < 8; ++e) { float re = 0.f, im = 0.f;
; #pragma unroll
;                     for (int a = 0; a < 16; ++a) { const unsigned wv = xin[a][e >> 1]; const float x = (e & 1) ? bf2f(wv >> 16) : bf2f(wv & 0xffffu); re += x * cw[a]; im -= x * sw[a]; }
;                     const float orr = re * tc - im * ts, oi = re * ts + im * tc;
;                     tile[((kl * 2 + 0) * 64 + cchunk * 8 + e) * 72 + i] = f2bf(orr); tile[((kl * 2 + 1) * 64 + cchunk * 8 + e) * 72 + i] = f2bf(oi); } }
	v_fmac_f32_e32 v49, 0x3f3504f3, v41
	v_fmac_f32_e32 v49, 0x3ec3ef15, v42
	v_sub_f32_e32 v49, v49, v43
	v_fmac_f32_e32 v49, 0x3ec3ef15, v44
	v_fmac_f32_e32 v49, 0x3f3504f3, v45
	v_fmac_f32_e32 v49, 0xbf6c835e, v46
	v_mul_f32_e32 v50, v49, v220
	v_fmac_f32_e32 v50, v48, v212
	v_mul_f32_e32 v51, v48, v220
	v_fma_f32 v51, v49, v212, -v51
	v_cvt_pk_bf16_f32 v52, v50, v51
	ds_write_b16 v4, v52 offset:9504
	ds_write_b16_d16_hi v4, v52 offset:14112
	v_add_f32_e32 v48, v16, v24
	v_fmac_f32_e32 v48, 0xbf3504f3, v32
	v_fmac_f32_e32 v48, 0x3f3504f3, v34
	v_sub_f32_e32 v48, v48, v35
	v_fmac_f32_e32 v48, 0x3f3504f3, v36
	v_fmac_f32_e32 v48, 0xbf3504f3, v38
	v_mul_f32_e32 v49, 0xbf3504f3, v40
	v_add_f32_e32 v49, v49, v41
	v_fmac_f32_e32 v49, 0xbf3504f3, v42
	v_fmac_f32_e32 v49, 0x3f3504f3, v44
	v_sub_f32_e32 v49, v49, v45
	v_fmac_f32_e32 v49, 0x3f3504f3, v46
	v_mul_f32_e32 v50, v49, v221
	v_fmac_f32_e32 v50, v48, v213
	v_mul_f32_e32 v51, v48, v221
	v_fma_f32 v51, v49, v213, -v51
	v_cvt_pk_bf16_f32 v52, v50, v51
	ds_write_b16 v4, v52 offset:18720
	ds_write_b16_d16_hi v4, v52 offset:23328
	v_sub_f32_e32 v48, v16, v24
	v_fmac_f32_e32 v48, 0xbf6c835e, v32
	v_fmac_f32_e32 v48, 0x3f3504f3, v33
	v_fmac_f32_e32 v48, 0xbec3ef15, v34
	v_fmac_f32_e32 v48, 0x3ec3ef15, v36
	v_fmac_f32_e32 v48, 0xbf3504f3, v37
	v_fmac_f32_e32 v48, 0x3f6c835e, v38
	v_mul_f32_e32 v49, 0xbec3ef15, v40
	v_fmac_f32_e32 v49, 0x3f3504f3, v41
	v_fmac_f32_e32 v49, 0xbf6c835e, v42
	v_add_f32_e32 v49, v49, v43
	v_fmac_f32_e32 v49, 0xbf6c835e, v44
	v_fmac_f32_e32 v49, 0x3f3504f3, v45
	v_fmac_f32_e32 v49, 0xbec3ef15, v46
	v_mul_f32_e32 v50, v49, v222
	v_fmac_f32_e32 v50, v48, v214
	v_mul_f32_e32 v51, v48, v222
	v_fma_f32 v51, v49, v214, -v51
	v_cvt_pk_bf16_f32 v52, v50, v51
	ds_write_b16 v4, v52 offset:27936
	ds_write_b16_d16_hi v4, v52 offset:32544
	v_add_f32_e32 v48, v16, v24
	v_sub_f32_e32 v48, v48, v32
	v_add_f32_e32 v48, v48, v33
	v_sub_f32_e32 v48, v48, v34
	v_add_f32_e32 v48, v48, v35
	v_sub_f32_e32 v48, v48, v36
	v_add_f32_e32 v48, v48, v37
	v_sub_f32_e32 v48, v48, v38
	v_mul_f32_e32 v50, v48, v215
	v_mul_f32_e32 v51, v48, v223
	v_sub_f32_e32 v51, 0, v51
	v_cvt_pk_bf16_f32 v52, v50, v51
	ds_write_b16 v4, v52 offset:37152
	ds_write_b16_d16_hi v4, v52 offset:41760
	v_and_b32_e32 v16, 0xffff0000, v65
	v_and_b32_e32 v17, 0xffff0000, v69
	v_and_b32_e32 v18, 0xffff0000, v73
	v_and_b32_e32 v19, 0xffff0000, v77
	v_and_b32_e32 v20, 0xffff0000, v81
	v_and_b32_e32 v21, 0xffff0000, v85
	v_and_b32_e32 v22, 0xffff0000, v89
	v_and_b32_e32 v23, 0xffff0000, v93
	v_and_b32_e32 v24, 0xffff0000, v97
	v_and_b32_e32 v25, 0xffff0000, v101
	v_and_b32_e32 v26, 0xffff0000, v105
	v_and_b32_e32 v27, 0xffff0000, v109
	v_and_b32_e32 v28, 0xffff0000, v113
	v_and_b32_e32 v29, 0xffff0000, v117
	v_and_b32_e32 v30, 0xffff0000, v121
	v_and_b32_e32 v31, 0xffff0000, v125
	v_add_f32_e32 v32, v17, v31
	v_sub_f32_e32 v40, v17, v31
	v_add_f32_e32 v33, v18, v30
	v_sub_f32_e32 v41, v18, v30
	v_add_f32_e32 v34, v19, v29
	v_sub_f32_e32 v42, v19, v29
	v_add_f32_e32 v35, v20, v28
	v_sub_f32_e32 v43, v20, v28
	v_add_f32_e32 v36, v21, v27
	v_sub_f32_e32 v44, v21, v27
	v_add_f32_e32 v37, v22, v26
	v_sub_f32_e32 v45, v22, v26
	v_add_f32_e32 v38, v23, v25
	v_sub_f32_e32 v46, v23, v25
	v_add_f32_e32 v48, v16, v24
	v_add_f32_e32 v48, v48, v32
	v_add_f32_e32 v48, v48, v33
	v_add_f32_e32 v48, v48, v34
	v_add_f32_e32 v48, v48, v35
	v_add_f32_e32 v48, v48, v36
	v_add_f32_e32 v48, v48, v37
	v_add_f32_e32 v48, v48, v38
	v_cvt_pk_bf16_f32 v52, v48, 0
	ds_write_b16 v3, v52 offset:432
	ds_write_b16_d16_hi v3, v52 offset:5040
	v_sub_f32_e32 v48, v16, v24
	v_fmac_f32_e32 v48, 0x3f6c835e, v32
	v_fmac_f32_e32 v48, 0x3f3504f3, v33
	v_fmac_f32_e32 v48, 0x3ec3ef15, v34
	v_fmac_f32_e32 v48, 0xbec3ef15, v36
	v_fmac_f32_e32 v48, 0xbf3504f3, v37
	v_fmac_f32_e32 v48, 0xbf6c835e, v38
	v_mul_f32_e32 v49, 0xbec3ef15, v40
	v_fmac_f32_e32 v49, 0xbf3504f3, v41
	v_fmac_f32_e32 v49, 0xbf6c835e, v42
	v_sub_f32_e32 v49, v49, v43
	v_fmac_f32_e32 v49, 0xbf6c835e, v44
	v_fmac_f32_e32 v49, 0xbf3504f3, v45
	v_fmac_f32_e32 v49, 0xbec3ef15, v46
	v_mul_f32_e32 v50, v49, v216
	v_fmac_f32_e32 v50, v48, v208
	v_mul_f32_e32 v51, v48, v216
	v_fma_f32 v51, v49, v208, -v51
	v_cvt_pk_bf16_f32 v52, v50, v51
	ds_write_b16 v3, v52 offset:9648
	ds_write_b16_d16_hi v3, v52 offset:14256
	v_add_f32_e32 v48, v16, v24
	v_fmac_f32_e32 v48, 0x3f3504f3, v32
	v_fmac_f32_e32 v48, 0xbf3504f3, v34
	v_sub_f32_e32 v48, v48, v35
	v_fmac_f32_e32 v48, 0xbf3504f3, v36
	v_fmac_f32_e32 v48, 0x3f3504f3, v38
	v_mul_f32_e32 v49, 0xbf3504f3, v40
	v_sub_f32_e32 v49, v49, v41
	v_fmac_f32_e32 v49, 0xbf3504f3, v42
	v_fmac_f32_e32 v49, 0x3f3504f3, v44
	v_add_f32_e32 v49, v49, v45
	v_fmac_f32_e32 v49, 0x3f3504f3, v46
	v_mul_f32_e32 v50, v49, v217
	v_fmac_f32_e32 v50, v48, v209
	v_mul_f32_e32 v51, v48, v217
	v_fma_f32 v51, v49, v209, -v51
	v_cvt_pk_bf16_f32 v52, v50, v51
	ds_write_b16 v3, v52 offset:18864
	ds_write_b16_d16_hi v3, v52 offset:23472
	v_sub_f32_e32 v48, v16, v24
	v_fmac_f32_e32 v48, 0x3ec3ef15, v32
	v_fmac_f32_e32 v48, 0xbf3504f3, v33
	v_fmac_f32_e32 v48, 0xbf6c835e, v34
	v_fmac_f32_e32 v48, 0x3f6c835e, v36
	v_fmac_f32_e32 v48, 0x3f3504f3, v37
	v_fmac_f32_e32 v48, 0xbec3ef15, v38
	v_mul_f32_e32 v49, 0xbf6c835e, v40
	v_fmac_f32_e32 v49, 0xbf3504f3, v41
	v_fmac_f32_e32 v49, 0x3ec3ef15, v42
	v_add_f32_e32 v49, v49, v43
	v_fmac_f32_e32 v49, 0x3ec3ef15, v44
	v_fmac_f32_e32 v49, 0xbf3504f3, v45
	v_fmac_f32_e32 v49, 0xbf6c835e, v46
	v_mul_f32_e32 v50, v49, v218
	v_fmac_f32_e32 v50, v48, v210
	v_mul_f32_e32 v51, v48, v218
	v_fma_f32 v51, v49, v210, -v51
	v_cvt_pk_bf16_f32 v52, v50, v51
	ds_write_b16 v3, v52 offset:28080
; __device__ __forceinline__ bf16_t f2bf(float f) { return (bf16_t)(cvt_pk_bf16(f, 0.f) & 0xffffu); }
; __device__ __forceinline__ void dft16_phase(const Ctx& X, const bf16_t* HN, bf16_t* GT) {
;     ...
;                 for (int e = 0; e < 8; ++e) { float re = 0.f, im = 0.f;
; #pragma unroll
;                     for (int a = 0; a < 16; ++a) { const unsigned wv = xin[a][e >> 1]; const float x = (e & 1) ? bf2f(wv >> 16) : bf2f(wv & 0xffffu); re += x * cw[a]; im -= x * sw[a]; }
;                     const float orr = re * tc - im * ts, oi = re * ts + im * tc;
;                     tile[((kl * 2 + 0) * 64 + cchunk * 8 + e) * 72 + i] = f2bf(orr); tile[((kl * 2 + 1) * 64 + cchunk * 8 + e) * 72 + i] = f2bf(oi); } }
;             __syncthreads();
; #pragma unroll
;             for (int q = 0; q < 8; ++q) { const int cid = q * 512 + X.tid, row = cid >> 3, c8 = cid & 7, kl = row >> 7, ri = (row >> 6) & 1, ch = row & 63;
;                 if (kq * 4 + kl > 8) continue;
;                 const u32x4 v = *(const u32x4*)(tile + row * 72 + c8 * 8);
;                 *(u32x4*)(GT + ((size_t)(b * 9 + kq * 4 + kl) * 1024 + ch0 + ch) * 512 + ri * 256 + b0 + c8 * 8) = v; }
	ds_write_b16_d16_hi v3, v52 offset:32688
	v_add_f32_e32 v48, v16, v24
	v_sub_f32_e32 v48, v48, v33
	v_add_f32_e32 v48, v48, v35
	v_sub_f32_e32 v48, v48, v37
	v_sub_f32_e32 v49, 0, v40
	v_add_f32_e32 v49, v49, v42
	v_sub_f32_e32 v49, v49, v44
	v_add_f32_e32 v49, v49, v46
	v_mul_f32_e32 v50, v49, v219
	v_fmac_f32_e32 v50, v48, v211
	v_mul_f32_e32 v51, v48, v219
	v_fma_f32 v51, v49, v211, -v51
	v_cvt_pk_bf16_f32 v52, v50, v51
	ds_write_b16 v4, v52 offset:432
	ds_write_b16_d16_hi v4, v52 offset:5040
	v_sub_f32_e32 v48, v16, v24
	v_fmac_f32_e32 v48, 0xbec3ef15, v32
	v_fmac_f32_e32 v48, 0xbf3504f3, v33
	v_fmac_f32_e32 v48, 0x3f6c835e, v34
	v_fmac_f32_e32 v48, 0xbf6c835e, v36
	v_fmac_f32_e32 v48, 0x3f3504f3, v37
	v_fmac_f32_e32 v48, 0x3ec3ef15, v38
	v_mul_f32_e32 v49, 0xbf6c835e, v40
	v_fmac_f32_e32 v49, 0x3f3504f3, v41
	v_fmac_f32_e32 v49, 0x3ec3ef15, v42
	v_sub_f32_e32 v49, v49, v43
	v_fmac_f32_e32 v49, 0x3ec3ef15, v44
	v_fmac_f32_e32 v49, 0x3f3504f3, v45
	v_fmac_f32_e32 v49, 0xbf6c835e, v46
	v_mul_f32_e32 v50, v49, v220
	v_fmac_f32_e32 v50, v48, v212
	v_mul_f32_e32 v51, v48, v220
	v_fma_f32 v51, v49, v212, -v51
	v_cvt_pk_bf16_f32 v52, v50, v51
	ds_write_b16 v4, v52 offset:9648
	ds_write_b16_d16_hi v4, v52 offset:14256
	v_add_f32_e32 v48, v16, v24
	v_fmac_f32_e32 v48, 0xbf3504f3, v32
	v_fmac_f32_e32 v48, 0x3f3504f3, v34
	v_sub_f32_e32 v48, v48, v35
	v_fmac_f32_e32 v48, 0x3f3504f3, v36
	v_fmac_f32_e32 v48, 0xbf3504f3, v38
	v_mul_f32_e32 v49, 0xbf3504f3, v40
	v_add_f32_e32 v49, v49, v41
	v_fmac_f32_e32 v49, 0xbf3504f3, v42
	v_fmac_f32_e32 v49, 0x3f3504f3, v44
	v_sub_f32_e32 v49, v49, v45
	v_fmac_f32_e32 v49, 0x3f3504f3, v46
	v_mul_f32_e32 v50, v49, v221
	v_fmac_f32_e32 v50, v48, v213
	v_mul_f32_e32 v51, v48, v221
	v_fma_f32 v51, v49, v213, -v51
	v_cvt_pk_bf16_f32 v52, v50, v51
	ds_write_b16 v4, v52 offset:18864
	ds_write_b16_d16_hi v4, v52 offset:23472
	v_sub_f32_e32 v48, v16, v24
	v_fmac_f32_e32 v48, 0xbf6c835e, v32
	v_fmac_f32_e32 v48, 0x3f3504f3, v33
	v_fmac_f32_e32 v48, 0xbec3ef15, v34
	v_fmac_f32_e32 v48, 0x3ec3ef15, v36
	v_fmac_f32_e32 v48, 0xbf3504f3, v37
	v_fmac_f32_e32 v48, 0x3f6c835e, v38
	v_mul_f32_e32 v49, 0xbec3ef15, v40
	v_fmac_f32_e32 v49, 0x3f3504f3, v41
	v_fmac_f32_e32 v49, 0xbf6c835e, v42
	v_add_f32_e32 v49, v49, v43
	v_fmac_f32_e32 v49, 0xbf6c835e, v44
	v_fmac_f32_e32 v49, 0x3f3504f3, v45
	v_fmac_f32_e32 v49, 0xbec3ef15, v46
	v_mul_f32_e32 v50, v49, v222
	v_fmac_f32_e32 v50, v48, v214
	v_mul_f32_e32 v51, v48, v222
	v_fma_f32 v51, v49, v214, -v51
	v_cvt_pk_bf16_f32 v52, v50, v51
	ds_write_b16 v4, v52 offset:28080
	ds_write_b16_d16_hi v4, v52 offset:32688
	v_add_f32_e32 v48, v16, v24
	v_sub_f32_e32 v48, v48, v32
	v_add_f32_e32 v48, v48, v33
	v_sub_f32_e32 v48, v48, v34
	v_add_f32_e32 v48, v48, v35
	v_sub_f32_e32 v48, v48, v36
	v_add_f32_e32 v48, v48, v37
	v_sub_f32_e32 v48, v48, v38
	v_mul_f32_e32 v50, v48, v215
	v_mul_f32_e32 v51, v48, v223
	v_sub_f32_e32 v51, 0, v51
	v_cvt_pk_bf16_f32 v52, v50, v51
	ds_write_b16 v4, v52 offset:37296
	ds_write_b16_d16_hi v4, v52 offset:41904
	s_waitcnt lgkmcnt(0)
	s_barrier
	s_add_u32 s8, s26, 0
	s_addc_u32 s9, s27, 0
	ds_read_b128 v[20:23], v5 offset:0
	s_waitcnt lgkmcnt(0)
	global_store_dwordx4 v7, v[20:23], s[8:9]
	s_add_u32 s8, s8, 0x100000
	s_addc_u32 s9, s9, 0
	ds_read_b128 v[24:27], v5 offset:9216
	s_waitcnt lgkmcnt(0)
	global_store_dwordx4 v7, v[24:27], s[8:9]
	s_add_u32 s8, s8, 0x100000
	s_addc_u32 s9, s9, 0
	ds_read_b128 v[28:31], v5 offset:18432
	s_waitcnt lgkmcnt(0)
	global_store_dwordx4 v7, v[28:31], s[8:9]
	s_add_u32 s8, s8, 0x100000
	s_addc_u32 s9, s9, 0
	ds_read_b128 v[32:35], v5 offset:27648
	s_waitcnt lgkmcnt(0)
	global_store_dwordx4 v7, v[32:35], s[8:9]
	s_add_u32 s8, s8, 0x100000
	s_addc_u32 s9, s9, 0
	ds_read_b128 v[20:23], v6 offset:0
	s_waitcnt lgkmcnt(0)
	global_store_dwordx4 v7, v[20:23], s[8:9]
	s_add_u32 s8, s8, 0x100000
	s_addc_u32 s9, s9, 0
	ds_read_b128 v[24:27], v6 offset:9216
	s_waitcnt lgkmcnt(0)
	global_store_dwordx4 v7, v[24:27], s[8:9]
	s_add_u32 s8, s8, 0x100000
	s_addc_u32 s9, s9, 0
	ds_read_b128 v[28:31], v6 offset:18432
	s_waitcnt lgkmcnt(0)
	global_store_dwordx4 v7, v[28:31], s[8:9]
	s_add_u32 s8, s8, 0x100000
	s_addc_u32 s9, s9, 0
	ds_read_b128 v[32:35], v6 offset:27648
	s_waitcnt lgkmcnt(0)
	global_store_dwordx4 v7, v[32:35], s[8:9]
	s_add_u32 s8, s8, 0x100000
	s_addc_u32 s9, s9, 0
	ds_read_b128 v[20:23], v6 offset:36864
	s_waitcnt lgkmcnt(0)
	global_store_dwordx4 v7, v[20:23], s[8:9]
	s_barrier
; __device__ __forceinline__ bf16_t f2bf(float f) { return (bf16_t)(cvt_pk_bf16(f, 0.f) & 0xffffu); }
; __device__ __forceinline__ void dft16_phase(const Ctx& X, const bf16_t* HN, bf16_t* GT) {
;     ...
;                 for (int a = 0; a < 16; ++a) { const int m = (a * ka) & 15; cw[a] = T16[m]; sw[a] = T16[16 + m]; }
; #pragma unroll
;                 for (int e = 0; e < 8; ++e) { float re = 0.f, im = 0.f;
; #pragma unroll
;                     for (int a = 0; a < 16; ++a) { const unsigned wv = xin[a][e >> 1]; const float x = (e & 1) ? bf2f(wv >> 16) : bf2f(wv & 0xffffu); re += x * cw[a]; im -= x * sw[a]; }
;                     const float orr = re * tc - im * ts, oi = re * ts + im * tc;
;                     tile[((kl * 2 + 0) * 64 + cchunk * 8 + e) * 72 + i] = f2bf(orr); tile[((kl * 2 + 1) * 64 + cchunk * 8 + e) * 72 + i] = f2bf(oi); } }
	v_lshlrev_b32_e32 v16, 16, v66
	v_lshlrev_b32_e32 v17, 16, v70
	v_lshlrev_b32_e32 v18, 16, v74
	v_lshlrev_b32_e32 v19, 16, v78
	v_lshlrev_b32_e32 v20, 16, v82
	v_lshlrev_b32_e32 v21, 16, v86
	v_lshlrev_b32_e32 v22, 16, v90
	v_lshlrev_b32_e32 v23, 16, v94
	v_lshlrev_b32_e32 v24, 16, v98
	v_lshlrev_b32_e32 v25, 16, v102
	v_lshlrev_b32_e32 v26, 16, v106
	v_lshlrev_b32_e32 v27, 16, v110
	v_lshlrev_b32_e32 v28, 16, v114
	v_lshlrev_b32_e32 v29, 16, v118
	v_lshlrev_b32_e32 v30, 16, v122
	v_lshlrev_b32_e32 v31, 16, v126
	v_add_f32_e32 v32, v17, v31
	v_sub_f32_e32 v40, v17, v31
	v_add_f32_e32 v33, v18, v30
	v_sub_f32_e32 v41, v18, v30
	v_add_f32_e32 v34, v19, v29
	v_sub_f32_e32 v42, v19, v29
	v_add_f32_e32 v35, v20, v28
	v_sub_f32_e32 v43, v20, v28
	v_add_f32_e32 v36, v21, v27
	v_sub_f32_e32 v44, v21, v27
	v_add_f32_e32 v37, v22, v26
	v_sub_f32_e32 v45, v22, v26
	v_add_f32_e32 v38, v23, v25
	v_sub_f32_e32 v46, v23, v25
	v_add_f32_e32 v48, v16, v24
	v_add_f32_e32 v48, v48, v32
	v_add_f32_e32 v48, v48, v33
	v_add_f32_e32 v48, v48, v34
	v_add_f32_e32 v48, v48, v35
	v_add_f32_e32 v48, v48, v36
	v_add_f32_e32 v48, v48, v37
	v_add_f32_e32 v48, v48, v38
	v_cvt_pk_bf16_f32 v52, v48, 0
	ds_write_b16 v3, v52 offset:0
	ds_write_b16_d16_hi v3, v52 offset:4608
	v_sub_f32_e32 v48, v16, v24
	v_fmac_f32_e32 v48, 0x3f6c835e, v32
	v_fmac_f32_e32 v48, 0x3f3504f3, v33
	v_fmac_f32_e32 v48, 0x3ec3ef15, v34
	v_fmac_f32_e32 v48, 0xbec3ef15, v36
	v_fmac_f32_e32 v48, 0xbf3504f3, v37
	v_fmac_f32_e32 v48, 0xbf6c835e, v38
	v_mul_f32_e32 v49, 0xbec3ef15, v40
	v_fmac_f32_e32 v49, 0xbf3504f3, v41
	v_fmac_f32_e32 v49, 0xbf6c835e, v42
	v_sub_f32_e32 v49, v49, v43
	v_fmac_f32_e32 v49, 0xbf6c835e, v44
	v_fmac_f32_e32 v49, 0xbf3504f3, v45
	v_fmac_f32_e32 v49, 0xbec3ef15, v46
	v_mul_f32_e32 v50, v49, v216
	v_fmac_f32_e32 v50, v48, v208
	v_mul_f32_e32 v51, v48, v216
	v_fma_f32 v51, v49, v208, -v51
	v_cvt_pk_bf16_f32 v52, v50, v51
	ds_write_b16 v3, v52 offset:9216
	ds_write_b16_d16_hi v3, v52 offset:13824
	v_add_f32_e32 v48, v16, v24
	v_fmac_f32_e32 v48, 0x3f3504f3, v32
	v_fmac_f32_e32 v48, 0xbf3504f3, v34
	v_sub_f32_e32 v48, v48, v35
	v_fmac_f32_e32 v48, 0xbf3504f3, v36
	v_fmac_f32_e32 v48, 0x3f3504f3, v38
	v_mul_f32_e32 v49, 0xbf3504f3, v40
	v_sub_f32_e32 v49, v49, v41
	v_fmac_f32_e32 v49, 0xbf3504f3, v42
	v_fmac_f32_e32 v49, 0x3f3504f3, v44
	v_add_f32_e32 v49, v49, v45
	v_fmac_f32_e32 v49, 0x3f3504f3, v46
	v_mul_f32_e32 v50, v49, v217
	v_fmac_f32_e32 v50, v48, v209
	v_mul_f32_e32 v51, v48, v217
	v_fma_f32 v51, v49, v209, -v51
	v_cvt_pk_bf16_f32 v52, v50, v51
	ds_write_b16 v3, v52 offset:18432
	ds_write_b16_d16_hi v3, v52 offset:23040
	v_sub_f32_e32 v48, v16, v24
	v_fmac_f32_e32 v48, 0x3ec3ef15, v32
	v_fmac_f32_e32 v48, 0xbf3504f3, v33
	v_fmac_f32_e32 v48, 0xbf6c835e, v34
	v_fmac_f32_e32 v48, 0x3f6c835e, v36
	v_fmac_f32_e32 v48, 0x3f3504f3, v37
	v_fmac_f32_e32 v48, 0xbec3ef15, v38
	v_mul_f32_e32 v49, 0xbf6c835e, v40
	v_fmac_f32_e32 v49, 0xbf3504f3, v41
	v_fmac_f32_e32 v49, 0x3ec3ef15, v42
	v_add_f32_e32 v49, v49, v43
	v_fmac_f32_e32 v49, 0x3ec3ef15, v44
	v_fmac_f32_e32 v49, 0xbf3504f3, v45
	v_fmac_f32_e32 v49, 0xbf6c835e, v46
	v_mul_f32_e32 v50, v49, v218
	v_fmac_f32_e32 v50, v48, v210
	v_mul_f32_e32 v51, v48, v218
	v_fma_f32 v51, v49, v210, -v51
	v_cvt_pk_bf16_f32 v52, v50, v51
	ds_write_b16 v3, v52 offset:27648
	ds_write_b16_d16_hi v3, v52 offset:32256
	v_add_f32_e32 v48, v16, v24
	v_sub_f32_e32 v48, v48, v33
	v_add_f32_e32 v48, v48, v35
	v_sub_f32_e32 v48, v48, v37
	v_sub_f32_e32 v49, 0, v40
	v_add_f32_e32 v49, v49, v42
	v_sub_f32_e32 v49, v49, v44
	v_add_f32_e32 v49, v49, v46
	v_mul_f32_e32 v50, v49, v219
	v_fmac_f32_e32 v50, v48, v211
	v_mul_f32_e32 v51, v48, v219
	v_fma_f32 v51, v49, v211, -v51
	v_cvt_pk_bf16_f32 v52, v50, v51
	ds_write_b16 v4, v52 offset:0
	ds_write_b16_d16_hi v4, v52 offset:4608
	v_sub_f32_e32 v48, v16, v24
	v_fmac_f32_e32 v48, 0xbec3ef15, v32
	v_fmac_f32_e32 v48, 0xbf3504f3, v33
	v_fmac_f32_e32 v48, 0x3f6c835e, v34
	v_fmac_f32_e32 v48, 0xbf6c835e, v36
	v_fmac_f32_e32 v48, 0x3f3504f3, v37
	v_fmac_f32_e32 v48, 0x3ec3ef15, v38
	v_mul_f32_e32 v49, 0xbf6c835e, v40
	v_fmac_f32_e32 v49, 0x3f3504f3, v41
	v_fmac_f32_e32 v49, 0x3ec3ef15, v42
	v_sub_f32_e32 v49, v49, v43
	v_fmac_f32_e32 v49, 0x3ec3ef15, v44
	v_fmac_f32_e32 v49, 0x3f3504f3, v45
	v_fmac_f32_e32 v49, 0xbf6c835e, v46
	v_mul_f32_e32 v50, v49, v220
	v_fmac_f32_e32 v50, v48, v212
	v_mul_f32_e32 v51, v48, v220
	v_fma_f32 v51, v49, v212, -v51
	v_cvt_pk_bf16_f32 v52, v50, v51
	ds_write_b16 v4, v52 offset:9216
	ds_write_b16_d16_hi v4, v52 offset:13824
	v_add_f32_e32 v48, v16, v24
	v_fmac_f32_e32 v48, 0xbf3504f3, v32
	v_fmac_f32_e32 v48, 0x3f3504f3, v34
	v_sub_f32_e32 v48, v48, v35
	v_fmac_f32_e32 v48, 0x3f3504f3, v36
	v_fmac_f32_e32 v48, 0xbf3504f3, v38
	v_mul_f32_e32 v49, 0xbf3504f3, v40
	v_add_f32_e32 v49, v49, v41
	v_fmac_f32_e32 v49, 0xbf3504f3, v42
	v_fmac_f32_e32 v49, 0x3f3504f3, v44
	v_sub_f32_e32 v49, v49, v45
	v_fmac_f32_e32 v49, 0x3f3504f3, v46
	v_mul_f32_e32 v50, v49, v221
	v_fmac_f32_e32 v50, v48, v213
	v_mul_f32_e32 v51, v48, v221
	v_fma_f32 v51, v49, v213, -v51
	v_cvt_pk_bf16_f32 v52, v50, v51
	ds_write_b16 v4, v52 offset:18432
	ds_write_b16_d16_hi v4, v52 offset:23040
	v_sub_f32_e32 v48, v16, v24
	v_fmac_f32_e32 v48, 0xbf6c835e, v32
	v_fmac_f32_e32 v48, 0x3f3504f3, v33
	v_fmac_f32_e32 v48, 0xbec3ef15, v34
	v_fmac_f32_e32 v48, 0x3ec3ef15, v36
	v_fmac_f32_e32 v48, 0xbf3504f3, v37
	v_fmac_f32_e32 v48, 0x3f6c835e, v38
	v_mul_f32_e32 v49, 0xbec3ef15, v40
	v_fmac_f32_e32 v49, 0x3f3504f3, v41
	v_fmac_f32_e32 v49, 0xbf6c835e, v42
	v_add_f32_e32 v49, v49, v43
	v_fmac_f32_e32 v49, 0xbf6c835e, v44
; __device__ __forceinline__ bf16_t f2bf(float f) { return (bf16_t)(cvt_pk_bf16(f, 0.f) & 0xffffu); }
; __device__ __forceinline__ void dft16_phase(const Ctx& X, const bf16_t* HN, bf16_t* GT) {
;     ...
;                 for (int e = 0; e < 8; ++e) { float re = 0.f, im = 0.f;
; #pragma unroll
;                     for (int a = 0; a < 16; ++a) { const unsigned wv = xin[a][e >> 1]; const float x = (e & 1) ? bf2f(wv >> 16) : bf2f(wv & 0xffffu); re += x * cw[a]; im -= x * sw[a]; }
;                     const float orr = re * tc - im * ts, oi = re * ts + im * tc;
;                     tile[((kl * 2 + 0) * 64 + cchunk * 8 + e) * 72 + i] = f2bf(orr); tile[((kl * 2 + 1) * 64 + cchunk * 8 + e) * 72 + i] = f2bf(oi); } }
	v_fmac_f32_e32 v49, 0x3f3504f3, v45
	v_fmac_f32_e32 v49, 0xbec3ef15, v46
	v_mul_f32_e32 v50, v49, v222
	v_fmac_f32_e32 v50, v48, v214
	v_mul_f32_e32 v51, v48, v222
	v_fma_f32 v51, v49, v214, -v51
	v_cvt_pk_bf16_f32 v52, v50, v51
	ds_write_b16 v4, v52 offset:27648
	ds_write_b16_d16_hi v4, v52 offset:32256
	v_add_f32_e32 v48, v16, v24
	v_sub_f32_e32 v48, v48, v32
	v_add_f32_e32 v48, v48, v33
	v_sub_f32_e32 v48, v48, v34
	v_add_f32_e32 v48, v48, v35
	v_sub_f32_e32 v48, v48, v36
	v_add_f32_e32 v48, v48, v37
	v_sub_f32_e32 v48, v48, v38
	v_mul_f32_e32 v50, v48, v215
	v_mul_f32_e32 v51, v48, v223
	v_sub_f32_e32 v51, 0, v51
	v_cvt_pk_bf16_f32 v52, v50, v51
	ds_write_b16 v4, v52 offset:36864
	ds_write_b16_d16_hi v4, v52 offset:41472
	v_and_b32_e32 v16, 0xffff0000, v66
	v_and_b32_e32 v17, 0xffff0000, v70
	v_and_b32_e32 v18, 0xffff0000, v74
	v_and_b32_e32 v19, 0xffff0000, v78
	v_and_b32_e32 v20, 0xffff0000, v82
	v_and_b32_e32 v21, 0xffff0000, v86
	v_and_b32_e32 v22, 0xffff0000, v90
	v_and_b32_e32 v23, 0xffff0000, v94
	v_and_b32_e32 v24, 0xffff0000, v98
	v_and_b32_e32 v25, 0xffff0000, v102
	v_and_b32_e32 v26, 0xffff0000, v106
	v_and_b32_e32 v27, 0xffff0000, v110
	v_and_b32_e32 v28, 0xffff0000, v114
	v_and_b32_e32 v29, 0xffff0000, v118
	v_and_b32_e32 v30, 0xffff0000, v122
	v_and_b32_e32 v31, 0xffff0000, v126
	v_add_f32_e32 v32, v17, v31
	v_sub_f32_e32 v40, v17, v31
	v_add_f32_e32 v33, v18, v30
	v_sub_f32_e32 v41, v18, v30
	v_add_f32_e32 v34, v19, v29
	v_sub_f32_e32 v42, v19, v29
	v_add_f32_e32 v35, v20, v28
	v_sub_f32_e32 v43, v20, v28
	v_add_f32_e32 v36, v21, v27
	v_sub_f32_e32 v44, v21, v27
	v_add_f32_e32 v37, v22, v26
	v_sub_f32_e32 v45, v22, v26
	v_add_f32_e32 v38, v23, v25
	v_sub_f32_e32 v46, v23, v25
	v_add_f32_e32 v48, v16, v24
	v_add_f32_e32 v48, v48, v32
	v_add_f32_e32 v48, v48, v33
	v_add_f32_e32 v48, v48, v34
	v_add_f32_e32 v48, v48, v35
	v_add_f32_e32 v48, v48, v36
	v_add_f32_e32 v48, v48, v37
	v_add_f32_e32 v48, v48, v38
	v_cvt_pk_bf16_f32 v52, v48, 0
	ds_write_b16 v3, v52 offset:144
	ds_write_b16_d16_hi v3, v52 offset:4752
	v_sub_f32_e32 v48, v16, v24
	v_fmac_f32_e32 v48, 0x3f6c835e, v32
	v_fmac_f32_e32 v48, 0x3f3504f3, v33
	v_fmac_f32_e32 v48, 0x3ec3ef15, v34
	v_fmac_f32_e32 v48, 0xbec3ef15, v36
	v_fmac_f32_e32 v48, 0xbf3504f3, v37
	v_fmac_f32_e32 v48, 0xbf6c835e, v38
	v_mul_f32_e32 v49, 0xbec3ef15, v40
	v_fmac_f32_e32 v49, 0xbf3504f3, v41
	v_fmac_f32_e32 v49, 0xbf6c835e, v42
	v_sub_f32_e32 v49, v49, v43
	v_fmac_f32_e32 v49, 0xbf6c835e, v44
	v_fmac_f32_e32 v49, 0xbf3504f3, v45
	v_fmac_f32_e32 v49, 0xbec3ef15, v46
	v_mul_f32_e32 v50, v49, v216
	v_fmac_f32_e32 v50, v48, v208
	v_mul_f32_e32 v51, v48, v216
	v_fma_f32 v51, v49, v208, -v51
	v_cvt_pk_bf16_f32 v52, v50, v51
	ds_write_b16 v3, v52 offset:9360
	ds_write_b16_d16_hi v3, v52 offset:13968
	v_add_f32_e32 v48, v16, v24
	v_fmac_f32_e32 v48, 0x3f3504f3, v32
	v_fmac_f32_e32 v48, 0xbf3504f3, v34
	v_sub_f32_e32 v48, v48, v35
	v_fmac_f32_e32 v48, 0xbf3504f3, v36
	v_fmac_f32_e32 v48, 0x3f3504f3, v38
	v_mul_f32_e32 v49, 0xbf3504f3, v40
	v_sub_f32_e32 v49, v49, v41
	v_fmac_f32_e32 v49, 0xbf3504f3, v42
	v_fmac_f32_e32 v49, 0x3f3504f3, v44
	v_add_f32_e32 v49, v49, v45
	v_fmac_f32_e32 v49, 0x3f3504f3, v46
	v_mul_f32_e32 v50, v49, v217
	v_fmac_f32_e32 v50, v48, v209
	v_mul_f32_e32 v51, v48, v217
	v_fma_f32 v51, v49, v209, -v51
	v_cvt_pk_bf16_f32 v52, v50, v51
	ds_write_b16 v3, v52 offset:18576
	ds_write_b16_d16_hi v3, v52 offset:23184
	v_sub_f32_e32 v48, v16, v24
	v_fmac_f32_e32 v48, 0x3ec3ef15, v32
	v_fmac_f32_e32 v48, 0xbf3504f3, v33
	v_fmac_f32_e32 v48, 0xbf6c835e, v34
	v_fmac_f32_e32 v48, 0x3f6c835e, v36
	v_fmac_f32_e32 v48, 0x3f3504f3, v37
	v_fmac_f32_e32 v48, 0xbec3ef15, v38
	v_mul_f32_e32 v49, 0xbf6c835e, v40
	v_fmac_f32_e32 v49, 0xbf3504f3, v41
	v_fmac_f32_e32 v49, 0x3ec3ef15, v42
	v_add_f32_e32 v49, v49, v43
	v_fmac_f32_e32 v49, 0x3ec3ef15, v44
	v_fmac_f32_e32 v49, 0xbf3504f3, v45
	v_fmac_f32_e32 v49, 0xbf6c835e, v46
	v_mul_f32_e32 v50, v49, v218
	v_fmac_f32_e32 v50, v48, v210
	v_mul_f32_e32 v51, v48, v218
	v_fma_f32 v51, v49, v210, -v51
	v_cvt_pk_bf16_f32 v52, v50, v51
	ds_write_b16 v3, v52 offset:27792
	ds_write_b16_d16_hi v3, v52 offset:32400
	v_add_f32_e32 v48, v16, v24
	v_sub_f32_e32 v48, v48, v33
	v_add_f32_e32 v48, v48, v35
	v_sub_f32_e32 v48, v48, v37
	v_sub_f32_e32 v49, 0, v40
	v_add_f32_e32 v49, v49, v42
	v_sub_f32_e32 v49, v49, v44
	v_add_f32_e32 v49, v49, v46
	v_mul_f32_e32 v50, v49, v219
	v_fmac_f32_e32 v50, v48, v211
	v_mul_f32_e32 v51, v48, v219
	v_fma_f32 v51, v49, v211, -v51
	v_cvt_pk_bf16_f32 v52, v50, v51
	ds_write_b16 v4, v52 offset:144
	ds_write_b16_d16_hi v4, v52 offset:4752
	v_sub_f32_e32 v48, v16, v24
	v_fmac_f32_e32 v48, 0xbec3ef15, v32
	v_fmac_f32_e32 v48, 0xbf3504f3, v33
	v_fmac_f32_e32 v48, 0x3f6c835e, v34
	v_fmac_f32_e32 v48, 0xbf6c835e, v36
	v_fmac_f32_e32 v48, 0x3f3504f3, v37
	v_fmac_f32_e32 v48, 0x3ec3ef15, v38
	v_mul_f32_e32 v49, 0xbf6c835e, v40
	v_fmac_f32_e32 v49, 0x3f3504f3, v41
	v_fmac_f32_e32 v49, 0x3ec3ef15, v42
	v_sub_f32_e32 v49, v49, v43
	v_fmac_f32_e32 v49, 0x3ec3ef15, v44
	v_fmac_f32_e32 v49, 0x3f3504f3, v45
	v_fmac_f32_e32 v49, 0xbf6c835e, v46
	v_mul_f32_e32 v50, v49, v220
	v_fmac_f32_e32 v50, v48, v212
	v_mul_f32_e32 v51, v48, v220
	v_fma_f32 v51, v49, v212, -v51
	v_cvt_pk_bf16_f32 v52, v50, v51
	ds_write_b16 v4, v52 offset:9360
	ds_write_b16_d16_hi v4, v52 offset:13968
	v_add_f32_e32 v48, v16, v24
	v_fmac_f32_e32 v48, 0xbf3504f3, v32
	v_fmac_f32_e32 v48, 0x3f3504f3, v34
	v_sub_f32_e32 v48, v48, v35
	v_fmac_f32_e32 v48, 0x3f3504f3, v36
	v_fmac_f32_e32 v48, 0xbf3504f3, v38
	v_mul_f32_e32 v49, 0xbf3504f3, v40
	v_add_f32_e32 v49, v49, v41
; __device__ __forceinline__ bf16_t f2bf(float f) { return (bf16_t)(cvt_pk_bf16(f, 0.f) & 0xffffu); }
; __device__ __forceinline__ void dft16_phase(const Ctx& X, const bf16_t* HN, bf16_t* GT) {
;     ...
;                 for (int e = 0; e < 8; ++e) { float re = 0.f, im = 0.f;
; #pragma unroll
;                     for (int a = 0; a < 16; ++a) { const unsigned wv = xin[a][e >> 1]; const float x = (e & 1) ? bf2f(wv >> 16) : bf2f(wv & 0xffffu); re += x * cw[a]; im -= x * sw[a]; }
;                     const float orr = re * tc - im * ts, oi = re * ts + im * tc;
;                     tile[((kl * 2 + 0) * 64 + cchunk * 8 + e) * 72 + i] = f2bf(orr); tile[((kl * 2 + 1) * 64 + cchunk * 8 + e) * 72 + i] = f2bf(oi); } }
	v_fmac_f32_e32 v49, 0xbf3504f3, v42
	v_fmac_f32_e32 v49, 0x3f3504f3, v44
	v_sub_f32_e32 v49, v49, v45
	v_fmac_f32_e32 v49, 0x3f3504f3, v46
	v_mul_f32_e32 v50, v49, v221
	v_fmac_f32_e32 v50, v48, v213
	v_mul_f32_e32 v51, v48, v221
	v_fma_f32 v51, v49, v213, -v51
	v_cvt_pk_bf16_f32 v52, v50, v51
	ds_write_b16 v4, v52 offset:18576
	ds_write_b16_d16_hi v4, v52 offset:23184
	v_sub_f32_e32 v48, v16, v24
	v_fmac_f32_e32 v48, 0xbf6c835e, v32
	v_fmac_f32_e32 v48, 0x3f3504f3, v33
	v_fmac_f32_e32 v48, 0xbec3ef15, v34
	v_fmac_f32_e32 v48, 0x3ec3ef15, v36
	v_fmac_f32_e32 v48, 0xbf3504f3, v37
	v_fmac_f32_e32 v48, 0x3f6c835e, v38
	v_mul_f32_e32 v49, 0xbec3ef15, v40
	v_fmac_f32_e32 v49, 0x3f3504f3, v41
	v_fmac_f32_e32 v49, 0xbf6c835e, v42
	v_add_f32_e32 v49, v49, v43
	v_fmac_f32_e32 v49, 0xbf6c835e, v44
	v_fmac_f32_e32 v49, 0x3f3504f3, v45
	v_fmac_f32_e32 v49, 0xbec3ef15, v46
	v_mul_f32_e32 v50, v49, v222
	v_fmac_f32_e32 v50, v48, v214
	v_mul_f32_e32 v51, v48, v222
	v_fma_f32 v51, v49, v214, -v51
	v_cvt_pk_bf16_f32 v52, v50, v51
	ds_write_b16 v4, v52 offset:27792
	ds_write_b16_d16_hi v4, v52 offset:32400
	v_add_f32_e32 v48, v16, v24
	v_sub_f32_e32 v48, v48, v32
	v_add_f32_e32 v48, v48, v33
	v_sub_f32_e32 v48, v48, v34
	v_add_f32_e32 v48, v48, v35
	v_sub_f32_e32 v48, v48, v36
	v_add_f32_e32 v48, v48, v37
	v_sub_f32_e32 v48, v48, v38
	v_mul_f32_e32 v50, v48, v215
	v_mul_f32_e32 v51, v48, v223
	v_sub_f32_e32 v51, 0, v51
	v_cvt_pk_bf16_f32 v52, v50, v51
	ds_write_b16 v4, v52 offset:37008
	ds_write_b16_d16_hi v4, v52 offset:41616
	v_lshlrev_b32_e32 v16, 16, v67
	v_lshlrev_b32_e32 v17, 16, v71
	v_lshlrev_b32_e32 v18, 16, v75
	v_lshlrev_b32_e32 v19, 16, v79
	v_lshlrev_b32_e32 v20, 16, v83
	v_lshlrev_b32_e32 v21, 16, v87
	v_lshlrev_b32_e32 v22, 16, v91
	v_lshlrev_b32_e32 v23, 16, v95
	v_lshlrev_b32_e32 v24, 16, v99
	v_lshlrev_b32_e32 v25, 16, v103
	v_lshlrev_b32_e32 v26, 16, v107
	v_lshlrev_b32_e32 v27, 16, v111
	v_lshlrev_b32_e32 v28, 16, v115
	v_lshlrev_b32_e32 v29, 16, v119
	v_lshlrev_b32_e32 v30, 16, v123
	v_lshlrev_b32_e32 v31, 16, v127
	v_add_f32_e32 v32, v17, v31
	v_sub_f32_e32 v40, v17, v31
	v_add_f32_e32 v33, v18, v30
	v_sub_f32_e32 v41, v18, v30
	v_add_f32_e32 v34, v19, v29
	v_sub_f32_e32 v42, v19, v29
	v_add_f32_e32 v35, v20, v28
	v_sub_f32_e32 v43, v20, v28
	v_add_f32_e32 v36, v21, v27
	v_sub_f32_e32 v44, v21, v27
	v_add_f32_e32 v37, v22, v26
	v_sub_f32_e32 v45, v22, v26
	v_add_f32_e32 v38, v23, v25
	v_sub_f32_e32 v46, v23, v25
	v_add_f32_e32 v48, v16, v24
	v_add_f32_e32 v48, v48, v32
	v_add_f32_e32 v48, v48, v33
	v_add_f32_e32 v48, v48, v34
	v_add_f32_e32 v48, v48, v35
	v_add_f32_e32 v48, v48, v36
	v_add_f32_e32 v48, v48, v37
	v_add_f32_e32 v48, v48, v38
	v_cvt_pk_bf16_f32 v52, v48, 0
	ds_write_b16 v3, v52 offset:288
	ds_write_b16_d16_hi v3, v52 offset:4896
	v_sub_f32_e32 v48, v16, v24
	v_fmac_f32_e32 v48, 0x3f6c835e, v32
	v_fmac_f32_e32 v48, 0x3f3504f3, v33
	v_fmac_f32_e32 v48, 0x3ec3ef15, v34
	v_fmac_f32_e32 v48, 0xbec3ef15, v36
	v_fmac_f32_e32 v48, 0xbf3504f3, v37
	v_fmac_f32_e32 v48, 0xbf6c835e, v38
	v_mul_f32_e32 v49, 0xbec3ef15, v40
	v_fmac_f32_e32 v49, 0xbf3504f3, v41
	v_fmac_f32_e32 v49, 0xbf6c835e, v42
	v_sub_f32_e32 v49, v49, v43
	v_fmac_f32_e32 v49, 0xbf6c835e, v44
	v_fmac_f32_e32 v49, 0xbf3504f3, v45
	v_fmac_f32_e32 v49, 0xbec3ef15, v46
	v_mul_f32_e32 v50, v49, v216
	v_fmac_f32_e32 v50, v48, v208
	v_mul_f32_e32 v51, v48, v216
	v_fma_f32 v51, v49, v208, -v51
	v_cvt_pk_bf16_f32 v52, v50, v51
	ds_write_b16 v3, v52 offset:9504
	ds_write_b16_d16_hi v3, v52 offset:14112
	v_add_f32_e32 v48, v16, v24
	v_fmac_f32_e32 v48, 0x3f3504f3, v32
	v_fmac_f32_e32 v48, 0xbf3504f3, v34
	v_sub_f32_e32 v48, v48, v35
	v_fmac_f32_e32 v48, 0xbf3504f3, v36
	v_fmac_f32_e32 v48, 0x3f3504f3, v38
	v_mul_f32_e32 v49, 0xbf3504f3, v40
	v_sub_f32_e32 v49, v49, v41
	v_fmac_f32_e32 v49, 0xbf3504f3, v42
	v_fmac_f32_e32 v49, 0x3f3504f3, v44
	v_add_f32_e32 v49, v49, v45
	v_fmac_f32_e32 v49, 0x3f3504f3, v46
	v_mul_f32_e32 v50, v49, v217
	v_fmac_f32_e32 v50, v48, v209
	v_mul_f32_e32 v51, v48, v217
	v_fma_f32 v51, v49, v209, -v51
	v_cvt_pk_bf16_f32 v52, v50, v51
	ds_write_b16 v3, v52 offset:18720
	ds_write_b16_d16_hi v3, v52 offset:23328
	v_sub_f32_e32 v48, v16, v24
	v_fmac_f32_e32 v48, 0x3ec3ef15, v32
	v_fmac_f32_e32 v48, 0xbf3504f3, v33
	v_fmac_f32_e32 v48, 0xbf6c835e, v34
	v_fmac_f32_e32 v48, 0x3f6c835e, v36
	v_fmac_f32_e32 v48, 0x3f3504f3, v37
	v_fmac_f32_e32 v48, 0xbec3ef15, v38
	v_mul_f32_e32 v49, 0xbf6c835e, v40
	v_fmac_f32_e32 v49, 0xbf3504f3, v41
	v_fmac_f32_e32 v49, 0x3ec3ef15, v42
	v_add_f32_e32 v49, v49, v43
	v_fmac_f32_e32 v49, 0x3ec3ef15, v44
	v_fmac_f32_e32 v49, 0xbf3504f3, v45
	v_fmac_f32_e32 v49, 0xbf6c835e, v46
	v_mul_f32_e32 v50, v49, v218
	v_fmac_f32_e32 v50, v48, v210
	v_mul_f32_e32 v51, v48, v218
	v_fma_f32 v51, v49, v210, -v51
	v_cvt_pk_bf16_f32 v52, v50, v51
	ds_write_b16 v3, v52 offset:27936
	ds_write_b16_d16_hi v3, v52 offset:32544
	v_add_f32_e32 v48, v16, v24
	v_sub_f32_e32 v48, v48, v33
	v_add_f32_e32 v48, v48, v35
	v_sub_f32_e32 v48, v48, v37
	v_sub_f32_e32 v49, 0, v40
	v_add_f32_e32 v49, v49, v42
	v_sub_f32_e32 v49, v49, v44
	v_add_f32_e32 v49, v49, v46
	v_mul_f32_e32 v50, v49, v219
	v_fmac_f32_e32 v50, v48, v211
	v_mul_f32_e32 v51, v48, v219
	v_fma_f32 v51, v49, v211, -v51
	v_cvt_pk_bf16_f32 v52, v50, v51
	ds_write_b16 v4, v52 offset:288
	ds_write_b16_d16_hi v4, v52 offset:4896
	v_sub_f32_e32 v48, v16, v24
	v_fmac_f32_e32 v48, 0xbec3ef15, v32
	v_fmac_f32_e32 v48, 0xbf3504f3, v33
	v_fmac_f32_e32 v48, 0x3f6c835e, v34
	v_fmac_f32_e32 v48, 0xbf6c835e, v36
	v_fmac_f32_e32 v48, 0x3f3504f3, v37
	v_fmac_f32_e32 v48, 0x3ec3ef15, v38
	v_mul_f32_e32 v49, 0xbf6c835e, v40
; __device__ __forceinline__ bf16_t f2bf(float f) { return (bf16_t)(cvt_pk_bf16(f, 0.f) & 0xffffu); }
; __device__ __forceinline__ void dft16_phase(const Ctx& X, const bf16_t* HN, bf16_t* GT) {
;     ...
;                 for (int e = 0; e < 8; ++e) { float re = 0.f, im = 0.f;
; #pragma unroll
;                     for (int a = 0; a < 16; ++a) { const unsigned wv = xin[a][e >> 1]; const float x = (e & 1) ? bf2f(wv >> 16) : bf2f(wv & 0xffffu); re += x * cw[a]; im -= x * sw[a]; }
;                     const float orr = re * tc - im * ts, oi = re * ts + im * tc;
;                     tile[((kl * 2 + 0) * 64 + cchunk * 8 + e) * 72 + i] = f2bf(orr); tile[((kl * 2 + 1) * 64 + cchunk * 8 + e) * 72 + i] = f2bf(oi); } }
	v_fmac_f32_e32 v49, 0x3f3504f3, v41
	v_fmac_f32_e32 v49, 0x3ec3ef15, v42
	v_sub_f32_e32 v49, v49, v43
	v_fmac_f32_e32 v49, 0x3ec3ef15, v44
	v_fmac_f32_e32 v49, 0x3f3504f3, v45
	v_fmac_f32_e32 v49, 0xbf6c835e, v46
	v_mul_f32_e32 v50, v49, v220
	v_fmac_f32_e32 v50, v48, v212
	v_mul_f32_e32 v51, v48, v220
	v_fma_f32 v51, v49, v212, -v51
	v_cvt_pk_bf16_f32 v52, v50, v51
	ds_write_b16 v4, v52 offset:9504
	ds_write_b16_d16_hi v4, v52 offset:14112
	v_add_f32_e32 v48, v16, v24
	v_fmac_f32_e32 v48, 0xbf3504f3, v32
	v_fmac_f32_e32 v48, 0x3f3504f3, v34
	v_sub_f32_e32 v48, v48, v35
	v_fmac_f32_e32 v48, 0x3f3504f3, v36
	v_fmac_f32_e32 v48, 0xbf3504f3, v38
	v_mul_f32_e32 v49, 0xbf3504f3, v40
	v_add_f32_e32 v49, v49, v41
	v_fmac_f32_e32 v49, 0xbf3504f3, v42
	v_fmac_f32_e32 v49, 0x3f3504f3, v44
	v_sub_f32_e32 v49, v49, v45
	v_fmac_f32_e32 v49, 0x3f3504f3, v46
	v_mul_f32_e32 v50, v49, v221
	v_fmac_f32_e32 v50, v48, v213
	v_mul_f32_e32 v51, v48, v221
	v_fma_f32 v51, v49, v213, -v51
	v_cvt_pk_bf16_f32 v52, v50, v51
	ds_write_b16 v4, v52 offset:18720
	ds_write_b16_d16_hi v4, v52 offset:23328
	v_sub_f32_e32 v48, v16, v24
	v_fmac_f32_e32 v48, 0xbf6c835e, v32
	v_fmac_f32_e32 v48, 0x3f3504f3, v33
	v_fmac_f32_e32 v48, 0xbec3ef15, v34
	v_fmac_f32_e32 v48, 0x3ec3ef15, v36
	v_fmac_f32_e32 v48, 0xbf3504f3, v37
	v_fmac_f32_e32 v48, 0x3f6c835e, v38
	v_mul_f32_e32 v49, 0xbec3ef15, v40
	v_fmac_f32_e32 v49, 0x3f3504f3, v41
	v_fmac_f32_e32 v49, 0xbf6c835e, v42
	v_add_f32_e32 v49, v49, v43
	v_fmac_f32_e32 v49, 0xbf6c835e, v44
	v_fmac_f32_e32 v49, 0x3f3504f3, v45
	v_fmac_f32_e32 v49, 0xbec3ef15, v46
	v_mul_f32_e32 v50, v49, v222
	v_fmac_f32_e32 v50, v48, v214
	v_mul_f32_e32 v51, v48, v222
	v_fma_f32 v51, v49, v214, -v51
	v_cvt_pk_bf16_f32 v52, v50, v51
	ds_write_b16 v4, v52 offset:27936
	ds_write_b16_d16_hi v4, v52 offset:32544
	v_add_f32_e32 v48, v16, v24
	v_sub_f32_e32 v48, v48, v32
	v_add_f32_e32 v48, v48, v33
	v_sub_f32_e32 v48, v48, v34
	v_add_f32_e32 v48, v48, v35
	v_sub_f32_e32 v48, v48, v36
	v_add_f32_e32 v48, v48, v37
	v_sub_f32_e32 v48, v48, v38
	v_mul_f32_e32 v50, v48, v215
	v_mul_f32_e32 v51, v48, v223
	v_sub_f32_e32 v51, 0, v51
	v_cvt_pk_bf16_f32 v52, v50, v51
	ds_write_b16 v4, v52 offset:37152
	ds_write_b16_d16_hi v4, v52 offset:41760
	v_and_b32_e32 v16, 0xffff0000, v67
	v_and_b32_e32 v17, 0xffff0000, v71
	v_and_b32_e32 v18, 0xffff0000, v75
	v_and_b32_e32 v19, 0xffff0000, v79
	v_and_b32_e32 v20, 0xffff0000, v83
	v_and_b32_e32 v21, 0xffff0000, v87
	v_and_b32_e32 v22, 0xffff0000, v91
	v_and_b32_e32 v23, 0xffff0000, v95
	v_and_b32_e32 v24, 0xffff0000, v99
	v_and_b32_e32 v25, 0xffff0000, v103
	v_and_b32_e32 v26, 0xffff0000, v107
	v_and_b32_e32 v27, 0xffff0000, v111
	v_and_b32_e32 v28, 0xffff0000, v115
	v_and_b32_e32 v29, 0xffff0000, v119
	v_and_b32_e32 v30, 0xffff0000, v123
	v_and_b32_e32 v31, 0xffff0000, v127
	v_add_f32_e32 v32, v17, v31
	v_sub_f32_e32 v40, v17, v31
	v_add_f32_e32 v33, v18, v30
	v_sub_f32_e32 v41, v18, v30
	v_add_f32_e32 v34, v19, v29
	v_sub_f32_e32 v42, v19, v29
	v_add_f32_e32 v35, v20, v28
	v_sub_f32_e32 v43, v20, v28
	v_add_f32_e32 v36, v21, v27
	v_sub_f32_e32 v44, v21, v27
	v_add_f32_e32 v37, v22, v26
	v_sub_f32_e32 v45, v22, v26
	v_add_f32_e32 v38, v23, v25
	v_sub_f32_e32 v46, v23, v25
	v_add_f32_e32 v48, v16, v24
	v_add_f32_e32 v48, v48, v32
	v_add_f32_e32 v48, v48, v33
	v_add_f32_e32 v48, v48, v34
	v_add_f32_e32 v48, v48, v35
	v_add_f32_e32 v48, v48, v36
	v_add_f32_e32 v48, v48, v37
	v_add_f32_e32 v48, v48, v38
	v_cvt_pk_bf16_f32 v52, v48, 0
	ds_write_b16 v3, v52 offset:432
	ds_write_b16_d16_hi v3, v52 offset:5040
	v_sub_f32_e32 v48, v16, v24
	v_fmac_f32_e32 v48, 0x3f6c835e, v32
	v_fmac_f32_e32 v48, 0x3f3504f3, v33
	v_fmac_f32_e32 v48, 0x3ec3ef15, v34
	v_fmac_f32_e32 v48, 0xbec3ef15, v36
	v_fmac_f32_e32 v48, 0xbf3504f3, v37
	v_fmac_f32_e32 v48, 0xbf6c835e, v38
	v_mul_f32_e32 v49, 0xbec3ef15, v40
	v_fmac_f32_e32 v49, 0xbf3504f3, v41
	v_fmac_f32_e32 v49, 0xbf6c835e, v42
	v_sub_f32_e32 v49, v49, v43
	v_fmac_f32_e32 v49, 0xbf6c835e, v44
	v_fmac_f32_e32 v49, 0xbf3504f3, v45
	v_fmac_f32_e32 v49, 0xbec3ef15, v46
	v_mul_f32_e32 v50, v49, v216
	v_fmac_f32_e32 v50, v48, v208
	v_mul_f32_e32 v51, v48, v216
	v_fma_f32 v51, v49, v208, -v51
	v_cvt_pk_bf16_f32 v52, v50, v51
	ds_write_b16 v3, v52 offset:9648
	ds_write_b16_d16_hi v3, v52 offset:14256
	v_add_f32_e32 v48, v16, v24
	v_fmac_f32_e32 v48, 0x3f3504f3, v32
	v_fmac_f32_e32 v48, 0xbf3504f3, v34
	v_sub_f32_e32 v48, v48, v35
	v_fmac_f32_e32 v48, 0xbf3504f3, v36
	v_fmac_f32_e32 v48, 0x3f3504f3, v38
	v_mul_f32_e32 v49, 0xbf3504f3, v40
	v_sub_f32_e32 v49, v49, v41
	v_fmac_f32_e32 v49, 0xbf3504f3, v42
	v_fmac_f32_e32 v49, 0x3f3504f3, v44
	v_add_f32_e32 v49, v49, v45
	v_fmac_f32_e32 v49, 0x3f3504f3, v46
	v_mul_f32_e32 v50, v49, v217
	v_fmac_f32_e32 v50, v48, v209
	v_mul_f32_e32 v51, v48, v217
	v_fma_f32 v51, v49, v209, -v51
	v_cvt_pk_bf16_f32 v52, v50, v51
	ds_write_b16 v3, v52 offset:18864
	ds_write_b16_d16_hi v3, v52 offset:23472
	v_sub_f32_e32 v48, v16, v24
	v_fmac_f32_e32 v48, 0x3ec3ef15, v32
	v_fmac_f32_e32 v48, 0xbf3504f3, v33
	v_fmac_f32_e32 v48, 0xbf6c835e, v34
	v_fmac_f32_e32 v48, 0x3f6c835e, v36
	v_fmac_f32_e32 v48, 0x3f3504f3, v37
	v_fmac_f32_e32 v48, 0xbec3ef15, v38
	v_mul_f32_e32 v49, 0xbf6c835e, v40
	v_fmac_f32_e32 v49, 0xbf3504f3, v41
	v_fmac_f32_e32 v49, 0x3ec3ef15, v42
	v_add_f32_e32 v49, v49, v43
	v_fmac_f32_e32 v49, 0x3ec3ef15, v44
	v_fmac_f32_e32 v49, 0xbf3504f3, v45
	v_fmac_f32_e32 v49, 0xbf6c835e, v46
	v_mul_f32_e32 v50, v49, v218
	v_fmac_f32_e32 v50, v48, v210
	v_mul_f32_e32 v51, v48, v218
	v_fma_f32 v51, v49, v210, -v51
	v_cvt_pk_bf16_f32 v52, v50, v51
	ds_write_b16 v3, v52 offset:28080
; __device__ __forceinline__ bf16_t f2bf(float f) { return (bf16_t)(cvt_pk_bf16(f, 0.f) & 0xffffu); }
; __device__ __forceinline__ void dft16_phase(const Ctx& X, const bf16_t* HN, bf16_t* GT) {
;     ...
;         for (int a = 0; a < 16; ++a) xin[a] = *(const u32x4*)(HN + (size_t)(b * 4096 + 256 * a + b0 + i) * 1024 + ch0 + cchunk * 8);
;         const int bp = b0 + i;
; #pragma unroll 1
;         for (int kq = 0; kq < 3; ++kq) {
;             __syncthreads();
; #pragma unroll 1
;             for (int kl = 0; kl < 4; ++kl) { const int ka = kq * 4 + kl; if (ka > 8) break;
;                 const float tang = (float)(bp * ka) * (1.0f / 2048.0f); const float tc = cospif(tang), ts = -sinpif(tang);
;                 float cw[16], sw[16];
; #pragma unroll
;                 for (int a = 0; a < 16; ++a) { const int m = (a * ka) & 15; cw[a] = T16[m]; sw[a] = T16[16 + m]; }
; #pragma unroll
;                 for (int e = 0; e < 8; ++e) { float re = 0.f, im = 0.f;
; #pragma unroll
;                     for (int a = 0; a < 16; ++a) { const unsigned wv = xin[a][e >> 1]; const float x = (e & 1) ? bf2f(wv >> 16) : bf2f(wv & 0xffffu); re += x * cw[a]; im -= x * sw[a]; }
;                     const float orr = re * tc - im * ts, oi = re * ts + im * tc;
;                     tile[((kl * 2 + 0) * 64 + cchunk * 8 + e) * 72 + i] = f2bf(orr); tile[((kl * 2 + 1) * 64 + cchunk * 8 + e) * 72 + i] = f2bf(oi); } }
;             __syncthreads();
; #pragma unroll
;             for (int q = 0; q < 8; ++q) { const int cid = q * 512 + X.tid, row = cid >> 3, c8 = cid & 7, kl = row >> 7, ri = (row >> 6) & 1, ch = row & 63;
;                 if (kq * 4 + kl > 8) continue;
;                 const u32x4 v = *(const u32x4*)(tile + row * 72 + c8 * 8);
;                 *(u32x4*)(GT + ((size_t)(b * 9 + kq * 4 + kl) * 1024 + ch0 + ch) * 512 + ri * 256 + b0 + c8 * 8) = v; }
	ds_write_b16_d16_hi v3, v52 offset:32688
	v_add_f32_e32 v48, v16, v24
	v_sub_f32_e32 v48, v48, v33
	v_add_f32_e32 v48, v48, v35
	v_sub_f32_e32 v48, v48, v37
	v_sub_f32_e32 v49, 0, v40
	v_add_f32_e32 v49, v49, v42
	v_sub_f32_e32 v49, v49, v44
	v_add_f32_e32 v49, v49, v46
	v_mul_f32_e32 v50, v49, v219
	v_fmac_f32_e32 v50, v48, v211
	v_mul_f32_e32 v51, v48, v219
	v_fma_f32 v51, v49, v211, -v51
	v_cvt_pk_bf16_f32 v52, v50, v51
	ds_write_b16 v4, v52 offset:432
	ds_write_b16_d16_hi v4, v52 offset:5040
	v_sub_f32_e32 v48, v16, v24
	v_fmac_f32_e32 v48, 0xbec3ef15, v32
	v_fmac_f32_e32 v48, 0xbf3504f3, v33
	v_fmac_f32_e32 v48, 0x3f6c835e, v34
	v_fmac_f32_e32 v48, 0xbf6c835e, v36
	v_fmac_f32_e32 v48, 0x3f3504f3, v37
	v_fmac_f32_e32 v48, 0x3ec3ef15, v38
	v_mul_f32_e32 v49, 0xbf6c835e, v40
	v_fmac_f32_e32 v49, 0x3f3504f3, v41
	v_fmac_f32_e32 v49, 0x3ec3ef15, v42
	v_sub_f32_e32 v49, v49, v43
	v_fmac_f32_e32 v49, 0x3ec3ef15, v44
	v_fmac_f32_e32 v49, 0x3f3504f3, v45
	v_fmac_f32_e32 v49, 0xbf6c835e, v46
	v_mul_f32_e32 v50, v49, v220
	v_fmac_f32_e32 v50, v48, v212
	v_mul_f32_e32 v51, v48, v220
	v_fma_f32 v51, v49, v212, -v51
	v_cvt_pk_bf16_f32 v52, v50, v51
	ds_write_b16 v4, v52 offset:9648
	ds_write_b16_d16_hi v4, v52 offset:14256
	v_add_f32_e32 v48, v16, v24
	v_fmac_f32_e32 v48, 0xbf3504f3, v32
	v_fmac_f32_e32 v48, 0x3f3504f3, v34
	v_sub_f32_e32 v48, v48, v35
	v_fmac_f32_e32 v48, 0x3f3504f3, v36
	v_fmac_f32_e32 v48, 0xbf3504f3, v38
	v_mul_f32_e32 v49, 0xbf3504f3, v40
	v_add_f32_e32 v49, v49, v41
	v_fmac_f32_e32 v49, 0xbf3504f3, v42
	v_fmac_f32_e32 v49, 0x3f3504f3, v44
	v_sub_f32_e32 v49, v49, v45
	v_fmac_f32_e32 v49, 0x3f3504f3, v46
	v_mul_f32_e32 v50, v49, v221
	v_fmac_f32_e32 v50, v48, v213
	v_mul_f32_e32 v51, v48, v221
	v_fma_f32 v51, v49, v213, -v51
	v_cvt_pk_bf16_f32 v52, v50, v51
	ds_write_b16 v4, v52 offset:18864
	ds_write_b16_d16_hi v4, v52 offset:23472
	v_sub_f32_e32 v48, v16, v24
	v_fmac_f32_e32 v48, 0xbf6c835e, v32
	v_fmac_f32_e32 v48, 0x3f3504f3, v33
	v_fmac_f32_e32 v48, 0xbec3ef15, v34
	v_fmac_f32_e32 v48, 0x3ec3ef15, v36
	v_fmac_f32_e32 v48, 0xbf3504f3, v37
	v_fmac_f32_e32 v48, 0x3f6c835e, v38
	v_mul_f32_e32 v49, 0xbec3ef15, v40
	v_fmac_f32_e32 v49, 0x3f3504f3, v41
	v_fmac_f32_e32 v49, 0xbf6c835e, v42
	v_add_f32_e32 v49, v49, v43
	v_fmac_f32_e32 v49, 0xbf6c835e, v44
	v_fmac_f32_e32 v49, 0x3f3504f3, v45
	v_fmac_f32_e32 v49, 0xbec3ef15, v46
	v_mul_f32_e32 v50, v49, v222
	v_fmac_f32_e32 v50, v48, v214
	v_mul_f32_e32 v51, v48, v222
	v_fma_f32 v51, v49, v214, -v51
	v_cvt_pk_bf16_f32 v52, v50, v51
	ds_write_b16 v4, v52 offset:28080
	ds_write_b16_d16_hi v4, v52 offset:32688
	v_add_f32_e32 v48, v16, v24
	v_sub_f32_e32 v48, v48, v32
	v_add_f32_e32 v48, v48, v33
	v_sub_f32_e32 v48, v48, v34
	v_add_f32_e32 v48, v48, v35
	v_sub_f32_e32 v48, v48, v36
	v_add_f32_e32 v48, v48, v37
	v_sub_f32_e32 v48, v48, v38
	v_mul_f32_e32 v50, v48, v215
	v_mul_f32_e32 v51, v48, v223
	v_sub_f32_e32 v51, 0, v51
	v_cvt_pk_bf16_f32 v52, v50, v51
	ds_write_b16 v4, v52 offset:37296
	ds_write_b16_d16_hi v4, v52 offset:41904
	s_waitcnt lgkmcnt(0)
	s_barrier
	s_add_u32 s8, s26, 4096
	s_addc_u32 s9, s27, 0
	ds_read_b128 v[20:23], v5 offset:0
	s_waitcnt lgkmcnt(0)
	global_store_dwordx4 v7, v[20:23], s[8:9]
	s_add_u32 s8, s8, 0x100000
	s_addc_u32 s9, s9, 0
	ds_read_b128 v[24:27], v5 offset:9216
	s_waitcnt lgkmcnt(0)
	global_store_dwordx4 v7, v[24:27], s[8:9]
	s_add_u32 s8, s8, 0x100000
	s_addc_u32 s9, s9, 0
	ds_read_b128 v[28:31], v5 offset:18432
	s_waitcnt lgkmcnt(0)
	global_store_dwordx4 v7, v[28:31], s[8:9]
	s_add_u32 s8, s8, 0x100000
	s_addc_u32 s9, s9, 0
	ds_read_b128 v[32:35], v5 offset:27648
	s_waitcnt lgkmcnt(0)
	global_store_dwordx4 v7, v[32:35], s[8:9]
	s_add_u32 s8, s8, 0x100000
	s_addc_u32 s9, s9, 0
	ds_read_b128 v[20:23], v6 offset:0
	s_waitcnt lgkmcnt(0)
	global_store_dwordx4 v7, v[20:23], s[8:9]
	s_add_u32 s8, s8, 0x100000
	s_addc_u32 s9, s9, 0
	ds_read_b128 v[24:27], v6 offset:9216
	s_waitcnt lgkmcnt(0)
	global_store_dwordx4 v7, v[24:27], s[8:9]
	s_add_u32 s8, s8, 0x100000
	s_addc_u32 s9, s9, 0
	ds_read_b128 v[28:31], v6 offset:18432
	s_waitcnt lgkmcnt(0)
	global_store_dwordx4 v7, v[28:31], s[8:9]
	s_add_u32 s8, s8, 0x100000
	s_addc_u32 s9, s9, 0
	ds_read_b128 v[32:35], v6 offset:27648
	s_waitcnt lgkmcnt(0)
	global_store_dwordx4 v7, v[32:35], s[8:9]
	s_add_u32 s8, s8, 0x100000
	s_addc_u32 s9, s9, 0
	ds_read_b128 v[20:23], v6 offset:36864
	s_waitcnt lgkmcnt(0)
	global_store_dwordx4 v7, v[20:23], s[8:9]
	s_waitcnt vmcnt(18)
	v_add_u32_e32 v10, s38, v1
	v_cvt_f32_u32_e32 v10, v10
	v_mul_f32_e32 v11, 0x39800000, v10
	v_cos_f32_e32 v208, v11
	v_sin_f32_e32 v216, v11
	v_mul_f32_e32 v11, 0x3a000000, v10
	v_cos_f32_e32 v209, v11
	v_sin_f32_e32 v217, v11
	v_mul_f32_e32 v11, 0x3a400000, v10
	v_cos_f32_e32 v210, v11
	v_sin_f32_e32 v218, v11
	v_mul_f32_e32 v11, 0x3a800000, v10
	v_cos_f32_e32 v211, v11
	v_sin_f32_e32 v219, v11
	v_mul_f32_e32 v11, 0x3aa00000, v10
	v_cos_f32_e32 v212, v11
	v_sin_f32_e32 v220, v11
	v_mul_f32_e32 v11, 0x3ac00000, v10
	v_cos_f32_e32 v213, v11
	v_sin_f32_e32 v221, v11
	v_mul_f32_e32 v11, 0x3ae00000, v10
	v_cos_f32_e32 v214, v11
	v_sin_f32_e32 v222, v11
	v_mul_f32_e32 v11, 0x3b000000, v10
	v_cos_f32_e32 v215, v11
	v_sin_f32_e32 v223, v11
	s_barrier
; __device__ __forceinline__ bf16_t f2bf(float f) { return (bf16_t)(cvt_pk_bf16(f, 0.f) & 0xffffu); }
; __device__ __forceinline__ void dft16_phase(const Ctx& X, const bf16_t* HN, bf16_t* GT) {
;     ...
;                 for (int e = 0; e < 8; ++e) { float re = 0.f, im = 0.f;
; #pragma unroll
;                     for (int a = 0; a < 16; ++a) { const unsigned wv = xin[a][e >> 1]; const float x = (e & 1) ? bf2f(wv >> 16) : bf2f(wv & 0xffffu); re += x * cw[a]; im -= x * sw[a]; }
;                     const float orr = re * tc - im * ts, oi = re * ts + im * tc;
;                     tile[((kl * 2 + 0) * 64 + cchunk * 8 + e) * 72 + i] = f2bf(orr); tile[((kl * 2 + 1) * 64 + cchunk * 8 + e) * 72 + i] = f2bf(oi); } }
	v_lshlrev_b32_e32 v16, 16, v128
	v_lshlrev_b32_e32 v17, 16, v132
	v_lshlrev_b32_e32 v18, 16, v136
	v_lshlrev_b32_e32 v19, 16, v140
	v_lshlrev_b32_e32 v20, 16, v144
	v_lshlrev_b32_e32 v21, 16, v148
	v_lshlrev_b32_e32 v22, 16, v152
	v_lshlrev_b32_e32 v23, 16, v156
	v_lshlrev_b32_e32 v24, 16, v160
	v_lshlrev_b32_e32 v25, 16, v164
	v_lshlrev_b32_e32 v26, 16, v168
	v_lshlrev_b32_e32 v27, 16, v172
	v_lshlrev_b32_e32 v28, 16, v176
	v_lshlrev_b32_e32 v29, 16, v180
	v_lshlrev_b32_e32 v30, 16, v184
	v_lshlrev_b32_e32 v31, 16, v188
	v_add_f32_e32 v32, v17, v31
	v_sub_f32_e32 v40, v17, v31
	v_add_f32_e32 v33, v18, v30
	v_sub_f32_e32 v41, v18, v30
	v_add_f32_e32 v34, v19, v29
	v_sub_f32_e32 v42, v19, v29
	v_add_f32_e32 v35, v20, v28
	v_sub_f32_e32 v43, v20, v28
	v_add_f32_e32 v36, v21, v27
	v_sub_f32_e32 v44, v21, v27
	v_add_f32_e32 v37, v22, v26
	v_sub_f32_e32 v45, v22, v26
	v_add_f32_e32 v38, v23, v25
	v_sub_f32_e32 v46, v23, v25
	v_add_f32_e32 v48, v16, v24
	v_add_f32_e32 v48, v48, v32
	v_add_f32_e32 v48, v48, v33
	v_add_f32_e32 v48, v48, v34
	v_add_f32_e32 v48, v48, v35
	v_add_f32_e32 v48, v48, v36
	v_add_f32_e32 v48, v48, v37
	v_add_f32_e32 v48, v48, v38
	v_cvt_pk_bf16_f32 v52, v48, 0
	ds_write_b16 v3, v52 offset:0
	ds_write_b16_d16_hi v3, v52 offset:4608
	v_sub_f32_e32 v48, v16, v24
	v_fmac_f32_e32 v48, 0x3f6c835e, v32
	v_fmac_f32_e32 v48, 0x3f3504f3, v33
	v_fmac_f32_e32 v48, 0x3ec3ef15, v34
	v_fmac_f32_e32 v48, 0xbec3ef15, v36
	v_fmac_f32_e32 v48, 0xbf3504f3, v37
	v_fmac_f32_e32 v48, 0xbf6c835e, v38
	v_mul_f32_e32 v49, 0xbec3ef15, v40
	v_fmac_f32_e32 v49, 0xbf3504f3, v41
	v_fmac_f32_e32 v49, 0xbf6c835e, v42
	v_sub_f32_e32 v49, v49, v43
	v_fmac_f32_e32 v49, 0xbf6c835e, v44
	v_fmac_f32_e32 v49, 0xbf3504f3, v45
	v_fmac_f32_e32 v49, 0xbec3ef15, v46
	v_mul_f32_e32 v50, v49, v216
	v_fmac_f32_e32 v50, v48, v208
	v_mul_f32_e32 v51, v48, v216
	v_fma_f32 v51, v49, v208, -v51
	v_cvt_pk_bf16_f32 v52, v50, v51
	ds_write_b16 v3, v52 offset:9216
	ds_write_b16_d16_hi v3, v52 offset:13824
	v_add_f32_e32 v48, v16, v24
	v_fmac_f32_e32 v48, 0x3f3504f3, v32
	v_fmac_f32_e32 v48, 0xbf3504f3, v34
	v_sub_f32_e32 v48, v48, v35
	v_fmac_f32_e32 v48, 0xbf3504f3, v36
	v_fmac_f32_e32 v48, 0x3f3504f3, v38
	v_mul_f32_e32 v49, 0xbf3504f3, v40
	v_sub_f32_e32 v49, v49, v41
	v_fmac_f32_e32 v49, 0xbf3504f3, v42
	v_fmac_f32_e32 v49, 0x3f3504f3, v44
	v_add_f32_e32 v49, v49, v45
	v_fmac_f32_e32 v49, 0x3f3504f3, v46
	v_mul_f32_e32 v50, v49, v217
	v_fmac_f32_e32 v50, v48, v209
	v_mul_f32_e32 v51, v48, v217
	v_fma_f32 v51, v49, v209, -v51
	v_cvt_pk_bf16_f32 v52, v50, v51
	ds_write_b16 v3, v52 offset:18432
	ds_write_b16_d16_hi v3, v52 offset:23040
	v_sub_f32_e32 v48, v16, v24
	v_fmac_f32_e32 v48, 0x3ec3ef15, v32
	v_fmac_f32_e32 v48, 0xbf3504f3, v33
	v_fmac_f32_e32 v48, 0xbf6c835e, v34
	v_fmac_f32_e32 v48, 0x3f6c835e, v36
	v_fmac_f32_e32 v48, 0x3f3504f3, v37
	v_fmac_f32_e32 v48, 0xbec3ef15, v38
	v_mul_f32_e32 v49, 0xbf6c835e, v40
	v_fmac_f32_e32 v49, 0xbf3504f3, v41
	v_fmac_f32_e32 v49, 0x3ec3ef15, v42
	v_add_f32_e32 v49, v49, v43
	v_fmac_f32_e32 v49, 0x3ec3ef15, v44
	v_fmac_f32_e32 v49, 0xbf3504f3, v45
	v_fmac_f32_e32 v49, 0xbf6c835e, v46
	v_mul_f32_e32 v50, v49, v218
	v_fmac_f32_e32 v50, v48, v210
	v_mul_f32_e32 v51, v48, v218
	v_fma_f32 v51, v49, v210, -v51
	v_cvt_pk_bf16_f32 v52, v50, v51
	ds_write_b16 v3, v52 offset:27648
	ds_write_b16_d16_hi v3, v52 offset:32256
	v_add_f32_e32 v48, v16, v24
	v_sub_f32_e32 v48, v48, v33
	v_add_f32_e32 v48, v48, v35
	v_sub_f32_e32 v48, v48, v37
	v_sub_f32_e32 v49, 0, v40
	v_add_f32_e32 v49, v49, v42
	v_sub_f32_e32 v49, v49, v44
	v_add_f32_e32 v49, v49, v46
	v_mul_f32_e32 v50, v49, v219
	v_fmac_f32_e32 v50, v48, v211
	v_mul_f32_e32 v51, v48, v219
	v_fma_f32 v51, v49, v211, -v51
	v_cvt_pk_bf16_f32 v52, v50, v51
	ds_write_b16 v4, v52 offset:0
	ds_write_b16_d16_hi v4, v52 offset:4608
	v_sub_f32_e32 v48, v16, v24
	v_fmac_f32_e32 v48, 0xbec3ef15, v32
	v_fmac_f32_e32 v48, 0xbf3504f3, v33
	v_fmac_f32_e32 v48, 0x3f6c835e, v34
	v_fmac_f32_e32 v48, 0xbf6c835e, v36
	v_fmac_f32_e32 v48, 0x3f3504f3, v37
	v_fmac_f32_e32 v48, 0x3ec3ef15, v38
	v_mul_f32_e32 v49, 0xbf6c835e, v40
	v_fmac_f32_e32 v49, 0x3f3504f3, v41
	v_fmac_f32_e32 v49, 0x3ec3ef15, v42
	v_sub_f32_e32 v49, v49, v43
	v_fmac_f32_e32 v49, 0x3ec3ef15, v44
	v_fmac_f32_e32 v49, 0x3f3504f3, v45
	v_fmac_f32_e32 v49, 0xbf6c835e, v46
	v_mul_f32_e32 v50, v49, v220
	v_fmac_f32_e32 v50, v48, v212
	v_mul_f32_e32 v51, v48, v220
	v_fma_f32 v51, v49, v212, -v51
	v_cvt_pk_bf16_f32 v52, v50, v51
	ds_write_b16 v4, v52 offset:9216
	ds_write_b16_d16_hi v4, v52 offset:13824
	v_add_f32_e32 v48, v16, v24
	v_fmac_f32_e32 v48, 0xbf3504f3, v32
	v_fmac_f32_e32 v48, 0x3f3504f3, v34
	v_sub_f32_e32 v48, v48, v35
	v_fmac_f32_e32 v48, 0x3f3504f3, v36
	v_fmac_f32_e32 v48, 0xbf3504f3, v38
	v_mul_f32_e32 v49, 0xbf3504f3, v40
	v_add_f32_e32 v49, v49, v41
	v_fmac_f32_e32 v49, 0xbf3504f3, v42
	v_fmac_f32_e32 v49, 0x3f3504f3, v44
	v_sub_f32_e32 v49, v49, v45
	v_fmac_f32_e32 v49, 0x3f3504f3, v46
	v_mul_f32_e32 v50, v49, v221
	v_fmac_f32_e32 v50, v48, v213
	v_mul_f32_e32 v51, v48, v221
	v_fma_f32 v51, v49, v213, -v51
	v_cvt_pk_bf16_f32 v52, v50, v51
	ds_write_b16 v4, v52 offset:18432
	ds_write_b16_d16_hi v4, v52 offset:23040
	v_sub_f32_e32 v48, v16, v24
	v_fmac_f32_e32 v48, 0xbf6c835e, v32
	v_fmac_f32_e32 v48, 0x3f3504f3, v33
	v_fmac_f32_e32 v48, 0xbec3ef15, v34
	v_fmac_f32_e32 v48, 0x3ec3ef15, v36
	v_fmac_f32_e32 v48, 0xbf3504f3, v37
	v_fmac_f32_e32 v48, 0x3f6c835e, v38
	v_mul_f32_e32 v49, 0xbec3ef15, v40
	v_fmac_f32_e32 v49, 0x3f3504f3, v41
	v_fmac_f32_e32 v49, 0xbf6c835e, v42
	v_add_f32_e32 v49, v49, v43
	v_fmac_f32_e32 v49, 0xbf6c835e, v44
; __device__ __forceinline__ bf16_t f2bf(float f) { return (bf16_t)(cvt_pk_bf16(f, 0.f) & 0xffffu); }
; __device__ __forceinline__ void dft16_phase(const Ctx& X, const bf16_t* HN, bf16_t* GT) {
;     ...
;                 for (int e = 0; e < 8; ++e) { float re = 0.f, im = 0.f;
; #pragma unroll
;                     for (int a = 0; a < 16; ++a) { const unsigned wv = xin[a][e >> 1]; const float x = (e & 1) ? bf2f(wv >> 16) : bf2f(wv & 0xffffu); re += x * cw[a]; im -= x * sw[a]; }
;                     const float orr = re * tc - im * ts, oi = re * ts + im * tc;
;                     tile[((kl * 2 + 0) * 64 + cchunk * 8 + e) * 72 + i] = f2bf(orr); tile[((kl * 2 + 1) * 64 + cchunk * 8 + e) * 72 + i] = f2bf(oi); } }
	v_fmac_f32_e32 v49, 0x3f3504f3, v45
	v_fmac_f32_e32 v49, 0xbec3ef15, v46
	v_mul_f32_e32 v50, v49, v222
	v_fmac_f32_e32 v50, v48, v214
	v_mul_f32_e32 v51, v48, v222
	v_fma_f32 v51, v49, v214, -v51
	v_cvt_pk_bf16_f32 v52, v50, v51
	ds_write_b16 v4, v52 offset:27648
	ds_write_b16_d16_hi v4, v52 offset:32256
	v_add_f32_e32 v48, v16, v24
	v_sub_f32_e32 v48, v48, v32
	v_add_f32_e32 v48, v48, v33
	v_sub_f32_e32 v48, v48, v34
	v_add_f32_e32 v48, v48, v35
	v_sub_f32_e32 v48, v48, v36
	v_add_f32_e32 v48, v48, v37
	v_sub_f32_e32 v48, v48, v38
	v_mul_f32_e32 v50, v48, v215
	v_mul_f32_e32 v51, v48, v223
	v_sub_f32_e32 v51, 0, v51
	v_cvt_pk_bf16_f32 v52, v50, v51
	ds_write_b16 v4, v52 offset:36864
	ds_write_b16_d16_hi v4, v52 offset:41472
	v_and_b32_e32 v16, 0xffff0000, v128
	v_and_b32_e32 v17, 0xffff0000, v132
	v_and_b32_e32 v18, 0xffff0000, v136
	v_and_b32_e32 v19, 0xffff0000, v140
	v_and_b32_e32 v20, 0xffff0000, v144
	v_and_b32_e32 v21, 0xffff0000, v148
	v_and_b32_e32 v22, 0xffff0000, v152
	v_and_b32_e32 v23, 0xffff0000, v156
	v_and_b32_e32 v24, 0xffff0000, v160
	v_and_b32_e32 v25, 0xffff0000, v164
	v_and_b32_e32 v26, 0xffff0000, v168
	v_and_b32_e32 v27, 0xffff0000, v172
	v_and_b32_e32 v28, 0xffff0000, v176
	v_and_b32_e32 v29, 0xffff0000, v180
	v_and_b32_e32 v30, 0xffff0000, v184
	v_and_b32_e32 v31, 0xffff0000, v188
	v_add_f32_e32 v32, v17, v31
	v_sub_f32_e32 v40, v17, v31
	v_add_f32_e32 v33, v18, v30
	v_sub_f32_e32 v41, v18, v30
	v_add_f32_e32 v34, v19, v29
	v_sub_f32_e32 v42, v19, v29
	v_add_f32_e32 v35, v20, v28
	v_sub_f32_e32 v43, v20, v28
	v_add_f32_e32 v36, v21, v27
	v_sub_f32_e32 v44, v21, v27
	v_add_f32_e32 v37, v22, v26
	v_sub_f32_e32 v45, v22, v26
	v_add_f32_e32 v38, v23, v25
	v_sub_f32_e32 v46, v23, v25
	v_add_f32_e32 v48, v16, v24
	v_add_f32_e32 v48, v48, v32
	v_add_f32_e32 v48, v48, v33
	v_add_f32_e32 v48, v48, v34
	v_add_f32_e32 v48, v48, v35
	v_add_f32_e32 v48, v48, v36
	v_add_f32_e32 v48, v48, v37
	v_add_f32_e32 v48, v48, v38
	v_cvt_pk_bf16_f32 v52, v48, 0
	ds_write_b16 v3, v52 offset:144
	ds_write_b16_d16_hi v3, v52 offset:4752
	v_sub_f32_e32 v48, v16, v24
	v_fmac_f32_e32 v48, 0x3f6c835e, v32
	v_fmac_f32_e32 v48, 0x3f3504f3, v33
	v_fmac_f32_e32 v48, 0x3ec3ef15, v34
	v_fmac_f32_e32 v48, 0xbec3ef15, v36
	v_fmac_f32_e32 v48, 0xbf3504f3, v37
	v_fmac_f32_e32 v48, 0xbf6c835e, v38
	v_mul_f32_e32 v49, 0xbec3ef15, v40
	v_fmac_f32_e32 v49, 0xbf3504f3, v41
	v_fmac_f32_e32 v49, 0xbf6c835e, v42
	v_sub_f32_e32 v49, v49, v43
	v_fmac_f32_e32 v49, 0xbf6c835e, v44
	v_fmac_f32_e32 v49, 0xbf3504f3, v45
	v_fmac_f32_e32 v49, 0xbec3ef15, v46
	v_mul_f32_e32 v50, v49, v216
	v_fmac_f32_e32 v50, v48, v208
	v_mul_f32_e32 v51, v48, v216
	v_fma_f32 v51, v49, v208, -v51
	v_cvt_pk_bf16_f32 v52, v50, v51
	ds_write_b16 v3, v52 offset:9360
	ds_write_b16_d16_hi v3, v52 offset:13968
	v_add_f32_e32 v48, v16, v24
	v_fmac_f32_e32 v48, 0x3f3504f3, v32
	v_fmac_f32_e32 v48, 0xbf3504f3, v34
	v_sub_f32_e32 v48, v48, v35
	v_fmac_f32_e32 v48, 0xbf3504f3, v36
	v_fmac_f32_e32 v48, 0x3f3504f3, v38
	v_mul_f32_e32 v49, 0xbf3504f3, v40
	v_sub_f32_e32 v49, v49, v41
	v_fmac_f32_e32 v49, 0xbf3504f3, v42
	v_fmac_f32_e32 v49, 0x3f3504f3, v44
	v_add_f32_e32 v49, v49, v45
	v_fmac_f32_e32 v49, 0x3f3504f3, v46
	v_mul_f32_e32 v50, v49, v217
	v_fmac_f32_e32 v50, v48, v209
	v_mul_f32_e32 v51, v48, v217
	v_fma_f32 v51, v49, v209, -v51
	v_cvt_pk_bf16_f32 v52, v50, v51
	ds_write_b16 v3, v52 offset:18576
	ds_write_b16_d16_hi v3, v52 offset:23184
	v_sub_f32_e32 v48, v16, v24
	v_fmac_f32_e32 v48, 0x3ec3ef15, v32
	v_fmac_f32_e32 v48, 0xbf3504f3, v33
	v_fmac_f32_e32 v48, 0xbf6c835e, v34
	v_fmac_f32_e32 v48, 0x3f6c835e, v36
	v_fmac_f32_e32 v48, 0x3f3504f3, v37
	v_fmac_f32_e32 v48, 0xbec3ef15, v38
	v_mul_f32_e32 v49, 0xbf6c835e, v40
	v_fmac_f32_e32 v49, 0xbf3504f3, v41
	v_fmac_f32_e32 v49, 0x3ec3ef15, v42
	v_add_f32_e32 v49, v49, v43
	v_fmac_f32_e32 v49, 0x3ec3ef15, v44
	v_fmac_f32_e32 v49, 0xbf3504f3, v45
	v_fmac_f32_e32 v49, 0xbf6c835e, v46
	v_mul_f32_e32 v50, v49, v218
	v_fmac_f32_e32 v50, v48, v210
	v_mul_f32_e32 v51, v48, v218
	v_fma_f32 v51, v49, v210, -v51
	v_cvt_pk_bf16_f32 v52, v50, v51
	ds_write_b16 v3, v52 offset:27792
	ds_write_b16_d16_hi v3, v52 offset:32400
	v_add_f32_e32 v48, v16, v24
	v_sub_f32_e32 v48, v48, v33
	v_add_f32_e32 v48, v48, v35
	v_sub_f32_e32 v48, v48, v37
	v_sub_f32_e32 v49, 0, v40
	v_add_f32_e32 v49, v49, v42
	v_sub_f32_e32 v49, v49, v44
	v_add_f32_e32 v49, v49, v46
	v_mul_f32_e32 v50, v49, v219
	v_fmac_f32_e32 v50, v48, v211
	v_mul_f32_e32 v51, v48, v219
	v_fma_f32 v51, v49, v211, -v51
	v_cvt_pk_bf16_f32 v52, v50, v51
	ds_write_b16 v4, v52 offset:144
	ds_write_b16_d16_hi v4, v52 offset:4752
	v_sub_f32_e32 v48, v16, v24
	v_fmac_f32_e32 v48, 0xbec3ef15, v32
	v_fmac_f32_e32 v48, 0xbf3504f3, v33
	v_fmac_f32_e32 v48, 0x3f6c835e, v34
	v_fmac_f32_e32 v48, 0xbf6c835e, v36
	v_fmac_f32_e32 v48, 0x3f3504f3, v37
	v_fmac_f32_e32 v48, 0x3ec3ef15, v38
	v_mul_f32_e32 v49, 0xbf6c835e, v40
	v_fmac_f32_e32 v49, 0x3f3504f3, v41
	v_fmac_f32_e32 v49, 0x3ec3ef15, v42
	v_sub_f32_e32 v49, v49, v43
	v_fmac_f32_e32 v49, 0x3ec3ef15, v44
	v_fmac_f32_e32 v49, 0x3f3504f3, v45
	v_fmac_f32_e32 v49, 0xbf6c835e, v46
	v_mul_f32_e32 v50, v49, v220
	v_fmac_f32_e32 v50, v48, v212
	v_mul_f32_e32 v51, v48, v220
	v_fma_f32 v51, v49, v212, -v51
	v_cvt_pk_bf16_f32 v52, v50, v51
	ds_write_b16 v4, v52 offset:9360
	ds_write_b16_d16_hi v4, v52 offset:13968
	v_add_f32_e32 v48, v16, v24
	v_fmac_f32_e32 v48, 0xbf3504f3, v32
	v_fmac_f32_e32 v48, 0x3f3504f3, v34
	v_sub_f32_e32 v48, v48, v35
	v_fmac_f32_e32 v48, 0x3f3504f3, v36
	v_fmac_f32_e32 v48, 0xbf3504f3, v38
	v_mul_f32_e32 v49, 0xbf3504f3, v40
	v_add_f32_e32 v49, v49, v41
; __device__ __forceinline__ bf16_t f2bf(float f) { return (bf16_t)(cvt_pk_bf16(f, 0.f) & 0xffffu); }
; __device__ __forceinline__ void dft16_phase(const Ctx& X, const bf16_t* HN, bf16_t* GT) {
;     ...
;                 for (int e = 0; e < 8; ++e) { float re = 0.f, im = 0.f;
; #pragma unroll
;                     for (int a = 0; a < 16; ++a) { const unsigned wv = xin[a][e >> 1]; const float x = (e & 1) ? bf2f(wv >> 16) : bf2f(wv & 0xffffu); re += x * cw[a]; im -= x * sw[a]; }
;                     const float orr = re * tc - im * ts, oi = re * ts + im * tc;
;                     tile[((kl * 2 + 0) * 64 + cchunk * 8 + e) * 72 + i] = f2bf(orr); tile[((kl * 2 + 1) * 64 + cchunk * 8 + e) * 72 + i] = f2bf(oi); } }
	v_fmac_f32_e32 v49, 0xbf3504f3, v42
	v_fmac_f32_e32 v49, 0x3f3504f3, v44
	v_sub_f32_e32 v49, v49, v45
	v_fmac_f32_e32 v49, 0x3f3504f3, v46
	v_mul_f32_e32 v50, v49, v221
	v_fmac_f32_e32 v50, v48, v213
	v_mul_f32_e32 v51, v48, v221
	v_fma_f32 v51, v49, v213, -v51
	v_cvt_pk_bf16_f32 v52, v50, v51
	ds_write_b16 v4, v52 offset:18576
	ds_write_b16_d16_hi v4, v52 offset:23184
	v_sub_f32_e32 v48, v16, v24
	v_fmac_f32_e32 v48, 0xbf6c835e, v32
	v_fmac_f32_e32 v48, 0x3f3504f3, v33
	v_fmac_f32_e32 v48, 0xbec3ef15, v34
	v_fmac_f32_e32 v48, 0x3ec3ef15, v36
	v_fmac_f32_e32 v48, 0xbf3504f3, v37
	v_fmac_f32_e32 v48, 0x3f6c835e, v38
	v_mul_f32_e32 v49, 0xbec3ef15, v40
	v_fmac_f32_e32 v49, 0x3f3504f3, v41
	v_fmac_f32_e32 v49, 0xbf6c835e, v42
	v_add_f32_e32 v49, v49, v43
	v_fmac_f32_e32 v49, 0xbf6c835e, v44
	v_fmac_f32_e32 v49, 0x3f3504f3, v45
	v_fmac_f32_e32 v49, 0xbec3ef15, v46
	v_mul_f32_e32 v50, v49, v222
	v_fmac_f32_e32 v50, v48, v214
	v_mul_f32_e32 v51, v48, v222
	v_fma_f32 v51, v49, v214, -v51
	v_cvt_pk_bf16_f32 v52, v50, v51
	ds_write_b16 v4, v52 offset:27792
	ds_write_b16_d16_hi v4, v52 offset:32400
	v_add_f32_e32 v48, v16, v24
	v_sub_f32_e32 v48, v48, v32
	v_add_f32_e32 v48, v48, v33
	v_sub_f32_e32 v48, v48, v34
	v_add_f32_e32 v48, v48, v35
	v_sub_f32_e32 v48, v48, v36
	v_add_f32_e32 v48, v48, v37
	v_sub_f32_e32 v48, v48, v38
	v_mul_f32_e32 v50, v48, v215
	v_mul_f32_e32 v51, v48, v223
	v_sub_f32_e32 v51, 0, v51
	v_cvt_pk_bf16_f32 v52, v50, v51
	ds_write_b16 v4, v52 offset:37008
	ds_write_b16_d16_hi v4, v52 offset:41616
	v_lshlrev_b32_e32 v16, 16, v129
	v_lshlrev_b32_e32 v17, 16, v133
	v_lshlrev_b32_e32 v18, 16, v137
	v_lshlrev_b32_e32 v19, 16, v141
	v_lshlrev_b32_e32 v20, 16, v145
	v_lshlrev_b32_e32 v21, 16, v149
	v_lshlrev_b32_e32 v22, 16, v153
	v_lshlrev_b32_e32 v23, 16, v157
	v_lshlrev_b32_e32 v24, 16, v161
	v_lshlrev_b32_e32 v25, 16, v165
	v_lshlrev_b32_e32 v26, 16, v169
	v_lshlrev_b32_e32 v27, 16, v173
	v_lshlrev_b32_e32 v28, 16, v177
	v_lshlrev_b32_e32 v29, 16, v181
	v_lshlrev_b32_e32 v30, 16, v185
	v_lshlrev_b32_e32 v31, 16, v189
	v_add_f32_e32 v32, v17, v31
	v_sub_f32_e32 v40, v17, v31
	v_add_f32_e32 v33, v18, v30
	v_sub_f32_e32 v41, v18, v30
	v_add_f32_e32 v34, v19, v29
	v_sub_f32_e32 v42, v19, v29
	v_add_f32_e32 v35, v20, v28
	v_sub_f32_e32 v43, v20, v28
	v_add_f32_e32 v36, v21, v27
	v_sub_f32_e32 v44, v21, v27
	v_add_f32_e32 v37, v22, v26
	v_sub_f32_e32 v45, v22, v26
	v_add_f32_e32 v38, v23, v25
	v_sub_f32_e32 v46, v23, v25
	v_add_f32_e32 v48, v16, v24
	v_add_f32_e32 v48, v48, v32
	v_add_f32_e32 v48, v48, v33
	v_add_f32_e32 v48, v48, v34
	v_add_f32_e32 v48, v48, v35
	v_add_f32_e32 v48, v48, v36
	v_add_f32_e32 v48, v48, v37
	v_add_f32_e32 v48, v48, v38
	v_cvt_pk_bf16_f32 v52, v48, 0
	ds_write_b16 v3, v52 offset:288
	ds_write_b16_d16_hi v3, v52 offset:4896
	v_sub_f32_e32 v48, v16, v24
	v_fmac_f32_e32 v48, 0x3f6c835e, v32
	v_fmac_f32_e32 v48, 0x3f3504f3, v33
	v_fmac_f32_e32 v48, 0x3ec3ef15, v34
	v_fmac_f32_e32 v48, 0xbec3ef15, v36
	v_fmac_f32_e32 v48, 0xbf3504f3, v37
	v_fmac_f32_e32 v48, 0xbf6c835e, v38
	v_mul_f32_e32 v49, 0xbec3ef15, v40
	v_fmac_f32_e32 v49, 0xbf3504f3, v41
	v_fmac_f32_e32 v49, 0xbf6c835e, v42
	v_sub_f32_e32 v49, v49, v43
	v_fmac_f32_e32 v49, 0xbf6c835e, v44
	v_fmac_f32_e32 v49, 0xbf3504f3, v45
	v_fmac_f32_e32 v49, 0xbec3ef15, v46
	v_mul_f32_e32 v50, v49, v216
	v_fmac_f32_e32 v50, v48, v208
	v_mul_f32_e32 v51, v48, v216
	v_fma_f32 v51, v49, v208, -v51
	v_cvt_pk_bf16_f32 v52, v50, v51
	ds_write_b16 v3, v52 offset:9504
	ds_write_b16_d16_hi v3, v52 offset:14112
	v_add_f32_e32 v48, v16, v24
	v_fmac_f32_e32 v48, 0x3f3504f3, v32
	v_fmac_f32_e32 v48, 0xbf3504f3, v34
	v_sub_f32_e32 v48, v48, v35
	v_fmac_f32_e32 v48, 0xbf3504f3, v36
	v_fmac_f32_e32 v48, 0x3f3504f3, v38
	v_mul_f32_e32 v49, 0xbf3504f3, v40
	v_sub_f32_e32 v49, v49, v41
	v_fmac_f32_e32 v49, 0xbf3504f3, v42
	v_fmac_f32_e32 v49, 0x3f3504f3, v44
	v_add_f32_e32 v49, v49, v45
	v_fmac_f32_e32 v49, 0x3f3504f3, v46
	v_mul_f32_e32 v50, v49, v217
	v_fmac_f32_e32 v50, v48, v209
	v_mul_f32_e32 v51, v48, v217
	v_fma_f32 v51, v49, v209, -v51
	v_cvt_pk_bf16_f32 v52, v50, v51
	ds_write_b16 v3, v52 offset:18720
	ds_write_b16_d16_hi v3, v52 offset:23328
	v_sub_f32_e32 v48, v16, v24
	v_fmac_f32_e32 v48, 0x3ec3ef15, v32
	v_fmac_f32_e32 v48, 0xbf3504f3, v33
	v_fmac_f32_e32 v48, 0xbf6c835e, v34
	v_fmac_f32_e32 v48, 0x3f6c835e, v36
	v_fmac_f32_e32 v48, 0x3f3504f3, v37
	v_fmac_f32_e32 v48, 0xbec3ef15, v38
	v_mul_f32_e32 v49, 0xbf6c835e, v40
	v_fmac_f32_e32 v49, 0xbf3504f3, v41
	v_fmac_f32_e32 v49, 0x3ec3ef15, v42
	v_add_f32_e32 v49, v49, v43
	v_fmac_f32_e32 v49, 0x3ec3ef15, v44
	v_fmac_f32_e32 v49, 0xbf3504f3, v45
	v_fmac_f32_e32 v49, 0xbf6c835e, v46
	v_mul_f32_e32 v50, v49, v218
	v_fmac_f32_e32 v50, v48, v210
	v_mul_f32_e32 v51, v48, v218
	v_fma_f32 v51, v49, v210, -v51
	v_cvt_pk_bf16_f32 v52, v50, v51
	ds_write_b16 v3, v52 offset:27936
	ds_write_b16_d16_hi v3, v52 offset:32544
	v_add_f32_e32 v48, v16, v24
	v_sub_f32_e32 v48, v48, v33
	v_add_f32_e32 v48, v48, v35
	v_sub_f32_e32 v48, v48, v37
	v_sub_f32_e32 v49, 0, v40
	v_add_f32_e32 v49, v49, v42
	v_sub_f32_e32 v49, v49, v44
	v_add_f32_e32 v49, v49, v46
	v_mul_f32_e32 v50, v49, v219
	v_fmac_f32_e32 v50, v48, v211
	v_mul_f32_e32 v51, v48, v219
	v_fma_f32 v51, v49, v211, -v51
	v_cvt_pk_bf16_f32 v52, v50, v51
	ds_write_b16 v4, v52 offset:288
	ds_write_b16_d16_hi v4, v52 offset:4896
	v_sub_f32_e32 v48, v16, v24
	v_fmac_f32_e32 v48, 0xbec3ef15, v32
	v_fmac_f32_e32 v48, 0xbf3504f3, v33
	v_fmac_f32_e32 v48, 0x3f6c835e, v34
	v_fmac_f32_e32 v48, 0xbf6c835e, v36
	v_fmac_f32_e32 v48, 0x3f3504f3, v37
	v_fmac_f32_e32 v48, 0x3ec3ef15, v38
; __device__ __forceinline__ bf16_t f2bf(float f) { return (bf16_t)(cvt_pk_bf16(f, 0.f) & 0xffffu); }
; __device__ __forceinline__ void dft16_phase(const Ctx& X, const bf16_t* HN, bf16_t* GT) {
;     ...
;                 for (int e = 0; e < 8; ++e) { float re = 0.f, im = 0.f;
; #pragma unroll
;                     for (int a = 0; a < 16; ++a) { const unsigned wv = xin[a][e >> 1]; const float x = (e & 1) ? bf2f(wv >> 16) : bf2f(wv & 0xffffu); re += x * cw[a]; im -= x * sw[a]; }
;                     const float orr = re * tc - im * ts, oi = re * ts + im * tc;
;                     tile[((kl * 2 + 0) * 64 + cchunk * 8 + e) * 72 + i] = f2bf(orr); tile[((kl * 2 + 1) * 64 + cchunk * 8 + e) * 72 + i] = f2bf(oi); } }
	v_mul_f32_e32 v49, 0xbf6c835e, v40
	v_fmac_f32_e32 v49, 0x3f3504f3, v41
	v_fmac_f32_e32 v49, 0x3ec3ef15, v42
	v_sub_f32_e32 v49, v49, v43
	v_fmac_f32_e32 v49, 0x3ec3ef15, v44
	v_fmac_f32_e32 v49, 0x3f3504f3, v45
	v_fmac_f32_e32 v49, 0xbf6c835e, v46
	v_mul_f32_e32 v50, v49, v220
	v_fmac_f32_e32 v50, v48, v212
	v_mul_f32_e32 v51, v48, v220
	v_fma_f32 v51, v49, v212, -v51
	v_cvt_pk_bf16_f32 v52, v50, v51
	ds_write_b16 v4, v52 offset:9504
	ds_write_b16_d16_hi v4, v52 offset:14112
	v_add_f32_e32 v48, v16, v24
	v_fmac_f32_e32 v48, 0xbf3504f3, v32
	v_fmac_f32_e32 v48, 0x3f3504f3, v34
	v_sub_f32_e32 v48, v48, v35
	v_fmac_f32_e32 v48, 0x3f3504f3, v36
	v_fmac_f32_e32 v48, 0xbf3504f3, v38
	v_mul_f32_e32 v49, 0xbf3504f3, v40
	v_add_f32_e32 v49, v49, v41
	v_fmac_f32_e32 v49, 0xbf3504f3, v42
	v_fmac_f32_e32 v49, 0x3f3504f3, v44
	v_sub_f32_e32 v49, v49, v45
	v_fmac_f32_e32 v49, 0x3f3504f3, v46
	v_mul_f32_e32 v50, v49, v221
	v_fmac_f32_e32 v50, v48, v213
	v_mul_f32_e32 v51, v48, v221
	v_fma_f32 v51, v49, v213, -v51
	v_cvt_pk_bf16_f32 v52, v50, v51
	ds_write_b16 v4, v52 offset:18720
	ds_write_b16_d16_hi v4, v52 offset:23328
	v_sub_f32_e32 v48, v16, v24
	v_fmac_f32_e32 v48, 0xbf6c835e, v32
	v_fmac_f32_e32 v48, 0x3f3504f3, v33
	v_fmac_f32_e32 v48, 0xbec3ef15, v34
	v_fmac_f32_e32 v48, 0x3ec3ef15, v36
	v_fmac_f32_e32 v48, 0xbf3504f3, v37
	v_fmac_f32_e32 v48, 0x3f6c835e, v38
	v_mul_f32_e32 v49, 0xbec3ef15, v40
	v_fmac_f32_e32 v49, 0x3f3504f3, v41
	v_fmac_f32_e32 v49, 0xbf6c835e, v42
	v_add_f32_e32 v49, v49, v43
	v_fmac_f32_e32 v49, 0xbf6c835e, v44
	v_fmac_f32_e32 v49, 0x3f3504f3, v45
	v_fmac_f32_e32 v49, 0xbec3ef15, v46
	v_mul_f32_e32 v50, v49, v222
	v_fmac_f32_e32 v50, v48, v214
	v_mul_f32_e32 v51, v48, v222
	v_fma_f32 v51, v49, v214, -v51
	v_cvt_pk_bf16_f32 v52, v50, v51
	ds_write_b16 v4, v52 offset:27936
	ds_write_b16_d16_hi v4, v52 offset:32544
	v_add_f32_e32 v48, v16, v24
	v_sub_f32_e32 v48, v48, v32
	v_add_f32_e32 v48, v48, v33
	v_sub_f32_e32 v48, v48, v34
	v_add_f32_e32 v48, v48, v35
	v_sub_f32_e32 v48, v48, v36
	v_add_f32_e32 v48, v48, v37
	v_sub_f32_e32 v48, v48, v38
	v_mul_f32_e32 v50, v48, v215
	v_mul_f32_e32 v51, v48, v223
	v_sub_f32_e32 v51, 0, v51
	v_cvt_pk_bf16_f32 v52, v50, v51
	ds_write_b16 v4, v52 offset:37152
	ds_write_b16_d16_hi v4, v52 offset:41760
	v_and_b32_e32 v16, 0xffff0000, v129
	v_and_b32_e32 v17, 0xffff0000, v133
	v_and_b32_e32 v18, 0xffff0000, v137
	v_and_b32_e32 v19, 0xffff0000, v141
	v_and_b32_e32 v20, 0xffff0000, v145
	v_and_b32_e32 v21, 0xffff0000, v149
	v_and_b32_e32 v22, 0xffff0000, v153
	v_and_b32_e32 v23, 0xffff0000, v157
	v_and_b32_e32 v24, 0xffff0000, v161
	v_and_b32_e32 v25, 0xffff0000, v165
	v_and_b32_e32 v26, 0xffff0000, v169
	v_and_b32_e32 v27, 0xffff0000, v173
	v_and_b32_e32 v28, 0xffff0000, v177
	v_and_b32_e32 v29, 0xffff0000, v181
	v_and_b32_e32 v30, 0xffff0000, v185
	v_and_b32_e32 v31, 0xffff0000, v189
	v_add_f32_e32 v32, v17, v31
	v_sub_f32_e32 v40, v17, v31
	v_add_f32_e32 v33, v18, v30
	v_sub_f32_e32 v41, v18, v30
	v_add_f32_e32 v34, v19, v29
	v_sub_f32_e32 v42, v19, v29
	v_add_f32_e32 v35, v20, v28
	v_sub_f32_e32 v43, v20, v28
	v_add_f32_e32 v36, v21, v27
	v_sub_f32_e32 v44, v21, v27
	v_add_f32_e32 v37, v22, v26
	v_sub_f32_e32 v45, v22, v26
	v_add_f32_e32 v38, v23, v25
	v_sub_f32_e32 v46, v23, v25
	v_add_f32_e32 v48, v16, v24
	v_add_f32_e32 v48, v48, v32
	v_add_f32_e32 v48, v48, v33
	v_add_f32_e32 v48, v48, v34
	v_add_f32_e32 v48, v48, v35
	v_add_f32_e32 v48, v48, v36
	v_add_f32_e32 v48, v48, v37
	v_add_f32_e32 v48, v48, v38
	v_cvt_pk_bf16_f32 v52, v48, 0
	ds_write_b16 v3, v52 offset:432
	ds_write_b16_d16_hi v3, v52 offset:5040
	v_sub_f32_e32 v48, v16, v24
	v_fmac_f32_e32 v48, 0x3f6c835e, v32
	v_fmac_f32_e32 v48, 0x3f3504f3, v33
	v_fmac_f32_e32 v48, 0x3ec3ef15, v34
	v_fmac_f32_e32 v48, 0xbec3ef15, v36
	v_fmac_f32_e32 v48, 0xbf3504f3, v37
	v_fmac_f32_e32 v48, 0xbf6c835e, v38
	v_mul_f32_e32 v49, 0xbec3ef15, v40
	v_fmac_f32_e32 v49, 0xbf3504f3, v41
	v_fmac_f32_e32 v49, 0xbf6c835e, v42
	v_sub_f32_e32 v49, v49, v43
	v_fmac_f32_e32 v49, 0xbf6c835e, v44
	v_fmac_f32_e32 v49, 0xbf3504f3, v45
	v_fmac_f32_e32 v49, 0xbec3ef15, v46
	v_mul_f32_e32 v50, v49, v216
	v_fmac_f32_e32 v50, v48, v208
	v_mul_f32_e32 v51, v48, v216
	v_fma_f32 v51, v49, v208, -v51
	v_cvt_pk_bf16_f32 v52, v50, v51
	ds_write_b16 v3, v52 offset:9648
	ds_write_b16_d16_hi v3, v52 offset:14256
	v_add_f32_e32 v48, v16, v24
	v_fmac_f32_e32 v48, 0x3f3504f3, v32
	v_fmac_f32_e32 v48, 0xbf3504f3, v34
	v_sub_f32_e32 v48, v48, v35
	v_fmac_f32_e32 v48, 0xbf3504f3, v36
	v_fmac_f32_e32 v48, 0x3f3504f3, v38
	v_mul_f32_e32 v49, 0xbf3504f3, v40
	v_sub_f32_e32 v49, v49, v41
	v_fmac_f32_e32 v49, 0xbf3504f3, v42
	v_fmac_f32_e32 v49, 0x3f3504f3, v44
	v_add_f32_e32 v49, v49, v45
	v_fmac_f32_e32 v49, 0x3f3504f3, v46
	v_mul_f32_e32 v50, v49, v217
	v_fmac_f32_e32 v50, v48, v209
	v_mul_f32_e32 v51, v48, v217
	v_fma_f32 v51, v49, v209, -v51
	v_cvt_pk_bf16_f32 v52, v50, v51
	ds_write_b16 v3, v52 offset:18864
	ds_write_b16_d16_hi v3, v52 offset:23472
	v_sub_f32_e32 v48, v16, v24
	v_fmac_f32_e32 v48, 0x3ec3ef15, v32
	v_fmac_f32_e32 v48, 0xbf3504f3, v33
	v_fmac_f32_e32 v48, 0xbf6c835e, v34
	v_fmac_f32_e32 v48, 0x3f6c835e, v36
	v_fmac_f32_e32 v48, 0x3f3504f3, v37
	v_fmac_f32_e32 v48, 0xbec3ef15, v38
	v_mul_f32_e32 v49, 0xbf6c835e, v40
	v_fmac_f32_e32 v49, 0xbf3504f3, v41
	v_fmac_f32_e32 v49, 0x3ec3ef15, v42
	v_add_f32_e32 v49, v49, v43
	v_fmac_f32_e32 v49, 0x3ec3ef15, v44
	v_fmac_f32_e32 v49, 0xbf3504f3, v45
	v_fmac_f32_e32 v49, 0xbf6c835e, v46
	v_mul_f32_e32 v50, v49, v218
	v_fmac_f32_e32 v50, v48, v210
	v_mul_f32_e32 v51, v48, v218
	v_fma_f32 v51, v49, v210, -v51
; __device__ __forceinline__ bf16_t f2bf(float f) { return (bf16_t)(cvt_pk_bf16(f, 0.f) & 0xffffu); }
; __device__ __forceinline__ void dft16_phase(const Ctx& X, const bf16_t* HN, bf16_t* GT) {
;     ...
;                 for (int e = 0; e < 8; ++e) { float re = 0.f, im = 0.f;
; #pragma unroll
;                     for (int a = 0; a < 16; ++a) { const unsigned wv = xin[a][e >> 1]; const float x = (e & 1) ? bf2f(wv >> 16) : bf2f(wv & 0xffffu); re += x * cw[a]; im -= x * sw[a]; }
;                     const float orr = re * tc - im * ts, oi = re * ts + im * tc;
;                     tile[((kl * 2 + 0) * 64 + cchunk * 8 + e) * 72 + i] = f2bf(orr); tile[((kl * 2 + 1) * 64 + cchunk * 8 + e) * 72 + i] = f2bf(oi); } }
;             __syncthreads();
; #pragma unroll
;             for (int q = 0; q < 8; ++q) { const int cid = q * 512 + X.tid, row = cid >> 3, c8 = cid & 7, kl = row >> 7, ri = (row >> 6) & 1, ch = row & 63;
;                 if (kq * 4 + kl > 8) continue;
;                 const u32x4 v = *(const u32x4*)(tile + row * 72 + c8 * 8);
;                 *(u32x4*)(GT + ((size_t)(b * 9 + kq * 4 + kl) * 1024 + ch0 + ch) * 512 + ri * 256 + b0 + c8 * 8) = v; }
	v_cvt_pk_bf16_f32 v52, v50, v51
	ds_write_b16 v3, v52 offset:28080
	ds_write_b16_d16_hi v3, v52 offset:32688
	v_add_f32_e32 v48, v16, v24
	v_sub_f32_e32 v48, v48, v33
	v_add_f32_e32 v48, v48, v35
	v_sub_f32_e32 v48, v48, v37
	v_sub_f32_e32 v49, 0, v40
	v_add_f32_e32 v49, v49, v42
	v_sub_f32_e32 v49, v49, v44
	v_add_f32_e32 v49, v49, v46
	v_mul_f32_e32 v50, v49, v219
	v_fmac_f32_e32 v50, v48, v211
	v_mul_f32_e32 v51, v48, v219
	v_fma_f32 v51, v49, v211, -v51
	v_cvt_pk_bf16_f32 v52, v50, v51
	ds_write_b16 v4, v52 offset:432
	ds_write_b16_d16_hi v4, v52 offset:5040
	v_sub_f32_e32 v48, v16, v24
	v_fmac_f32_e32 v48, 0xbec3ef15, v32
	v_fmac_f32_e32 v48, 0xbf3504f3, v33
	v_fmac_f32_e32 v48, 0x3f6c835e, v34
	v_fmac_f32_e32 v48, 0xbf6c835e, v36
	v_fmac_f32_e32 v48, 0x3f3504f3, v37
	v_fmac_f32_e32 v48, 0x3ec3ef15, v38
	v_mul_f32_e32 v49, 0xbf6c835e, v40
	v_fmac_f32_e32 v49, 0x3f3504f3, v41
	v_fmac_f32_e32 v49, 0x3ec3ef15, v42
	v_sub_f32_e32 v49, v49, v43
	v_fmac_f32_e32 v49, 0x3ec3ef15, v44
	v_fmac_f32_e32 v49, 0x3f3504f3, v45
	v_fmac_f32_e32 v49, 0xbf6c835e, v46
	v_mul_f32_e32 v50, v49, v220
	v_fmac_f32_e32 v50, v48, v212
	v_mul_f32_e32 v51, v48, v220
	v_fma_f32 v51, v49, v212, -v51
	v_cvt_pk_bf16_f32 v52, v50, v51
	ds_write_b16 v4, v52 offset:9648
	ds_write_b16_d16_hi v4, v52 offset:14256
	v_add_f32_e32 v48, v16, v24
	v_fmac_f32_e32 v48, 0xbf3504f3, v32
	v_fmac_f32_e32 v48, 0x3f3504f3, v34
	v_sub_f32_e32 v48, v48, v35
	v_fmac_f32_e32 v48, 0x3f3504f3, v36
	v_fmac_f32_e32 v48, 0xbf3504f3, v38
	v_mul_f32_e32 v49, 0xbf3504f3, v40
	v_add_f32_e32 v49, v49, v41
	v_fmac_f32_e32 v49, 0xbf3504f3, v42
	v_fmac_f32_e32 v49, 0x3f3504f3, v44
	v_sub_f32_e32 v49, v49, v45
	v_fmac_f32_e32 v49, 0x3f3504f3, v46
	v_mul_f32_e32 v50, v49, v221
	v_fmac_f32_e32 v50, v48, v213
	v_mul_f32_e32 v51, v48, v221
	v_fma_f32 v51, v49, v213, -v51
	v_cvt_pk_bf16_f32 v52, v50, v51
	ds_write_b16 v4, v52 offset:18864
	ds_write_b16_d16_hi v4, v52 offset:23472
	v_sub_f32_e32 v48, v16, v24
	v_fmac_f32_e32 v48, 0xbf6c835e, v32
	v_fmac_f32_e32 v48, 0x3f3504f3, v33
	v_fmac_f32_e32 v48, 0xbec3ef15, v34
	v_fmac_f32_e32 v48, 0x3ec3ef15, v36
	v_fmac_f32_e32 v48, 0xbf3504f3, v37
	v_fmac_f32_e32 v48, 0x3f6c835e, v38
	v_mul_f32_e32 v49, 0xbec3ef15, v40
	v_fmac_f32_e32 v49, 0x3f3504f3, v41
	v_fmac_f32_e32 v49, 0xbf6c835e, v42
	v_add_f32_e32 v49, v49, v43
	v_fmac_f32_e32 v49, 0xbf6c835e, v44
	v_fmac_f32_e32 v49, 0x3f3504f3, v45
	v_fmac_f32_e32 v49, 0xbec3ef15, v46
	v_mul_f32_e32 v50, v49, v222
	v_fmac_f32_e32 v50, v48, v214
	v_mul_f32_e32 v51, v48, v222
	v_fma_f32 v51, v49, v214, -v51
	v_cvt_pk_bf16_f32 v52, v50, v51
	ds_write_b16 v4, v52 offset:28080
	ds_write_b16_d16_hi v4, v52 offset:32688
	v_add_f32_e32 v48, v16, v24
	v_sub_f32_e32 v48, v48, v32
	v_add_f32_e32 v48, v48, v33
	v_sub_f32_e32 v48, v48, v34
	v_add_f32_e32 v48, v48, v35
	v_sub_f32_e32 v48, v48, v36
	v_add_f32_e32 v48, v48, v37
	v_sub_f32_e32 v48, v48, v38
	v_mul_f32_e32 v50, v48, v215
	v_mul_f32_e32 v51, v48, v223
	v_sub_f32_e32 v51, 0, v51
	v_cvt_pk_bf16_f32 v52, v50, v51
	ds_write_b16 v4, v52 offset:37296
	ds_write_b16_d16_hi v4, v52 offset:41904
	s_waitcnt lgkmcnt(0)
	s_barrier
	s_add_u32 s8, s36, 0
	s_addc_u32 s9, s37, 0
	ds_read_b128 v[20:23], v5 offset:0
	s_waitcnt lgkmcnt(0)
	global_store_dwordx4 v7, v[20:23], s[8:9]
	s_add_u32 s8, s8, 0x100000
	s_addc_u32 s9, s9, 0
	ds_read_b128 v[24:27], v5 offset:9216
	s_waitcnt lgkmcnt(0)
	global_store_dwordx4 v7, v[24:27], s[8:9]
	s_add_u32 s8, s8, 0x100000
	s_addc_u32 s9, s9, 0
	ds_read_b128 v[28:31], v5 offset:18432
	s_waitcnt lgkmcnt(0)
	global_store_dwordx4 v7, v[28:31], s[8:9]
	s_add_u32 s8, s8, 0x100000
	s_addc_u32 s9, s9, 0
	ds_read_b128 v[32:35], v5 offset:27648
	s_waitcnt lgkmcnt(0)
	global_store_dwordx4 v7, v[32:35], s[8:9]
	s_add_u32 s8, s8, 0x100000
	s_addc_u32 s9, s9, 0
	ds_read_b128 v[20:23], v6 offset:0
	s_waitcnt lgkmcnt(0)
	global_store_dwordx4 v7, v[20:23], s[8:9]
	s_add_u32 s8, s8, 0x100000
	s_addc_u32 s9, s9, 0
	ds_read_b128 v[24:27], v6 offset:9216
	s_waitcnt lgkmcnt(0)
	global_store_dwordx4 v7, v[24:27], s[8:9]
	s_add_u32 s8, s8, 0x100000
	s_addc_u32 s9, s9, 0
	ds_read_b128 v[28:31], v6 offset:18432
	s_waitcnt lgkmcnt(0)
	global_store_dwordx4 v7, v[28:31], s[8:9]
	s_add_u32 s8, s8, 0x100000
	s_addc_u32 s9, s9, 0
	ds_read_b128 v[32:35], v6 offset:27648
	s_waitcnt lgkmcnt(0)
	global_store_dwordx4 v7, v[32:35], s[8:9]
	s_add_u32 s8, s8, 0x100000
	s_addc_u32 s9, s9, 0
	ds_read_b128 v[20:23], v6 offset:36864
	s_waitcnt lgkmcnt(0)
	global_store_dwordx4 v7, v[20:23], s[8:9]
	s_barrier
; __device__ __forceinline__ bf16_t f2bf(float f) { return (bf16_t)(cvt_pk_bf16(f, 0.f) & 0xffffu); }
; __device__ __forceinline__ void dft16_phase(const Ctx& X, const bf16_t* HN, bf16_t* GT) {
;     ...
;                 for (int e = 0; e < 8; ++e) { float re = 0.f, im = 0.f;
; #pragma unroll
;                     for (int a = 0; a < 16; ++a) { const unsigned wv = xin[a][e >> 1]; const float x = (e & 1) ? bf2f(wv >> 16) : bf2f(wv & 0xffffu); re += x * cw[a]; im -= x * sw[a]; }
;                     const float orr = re * tc - im * ts, oi = re * ts + im * tc;
;                     tile[((kl * 2 + 0) * 64 + cchunk * 8 + e) * 72 + i] = f2bf(orr); tile[((kl * 2 + 1) * 64 + cchunk * 8 + e) * 72 + i] = f2bf(oi); } }
	v_lshlrev_b32_e32 v16, 16, v130
	v_lshlrev_b32_e32 v17, 16, v134
	v_lshlrev_b32_e32 v18, 16, v138
	v_lshlrev_b32_e32 v19, 16, v142
	v_lshlrev_b32_e32 v20, 16, v146
	v_lshlrev_b32_e32 v21, 16, v150
	v_lshlrev_b32_e32 v22, 16, v154
	v_lshlrev_b32_e32 v23, 16, v158
	v_lshlrev_b32_e32 v24, 16, v162
	v_lshlrev_b32_e32 v25, 16, v166
	v_lshlrev_b32_e32 v26, 16, v170
	v_lshlrev_b32_e32 v27, 16, v174
	v_lshlrev_b32_e32 v28, 16, v178
	v_lshlrev_b32_e32 v29, 16, v182
	v_lshlrev_b32_e32 v30, 16, v186
	v_lshlrev_b32_e32 v31, 16, v190
	v_add_f32_e32 v32, v17, v31
	v_sub_f32_e32 v40, v17, v31
	v_add_f32_e32 v33, v18, v30
	v_sub_f32_e32 v41, v18, v30
	v_add_f32_e32 v34, v19, v29
	v_sub_f32_e32 v42, v19, v29
	v_add_f32_e32 v35, v20, v28
	v_sub_f32_e32 v43, v20, v28
	v_add_f32_e32 v36, v21, v27
	v_sub_f32_e32 v44, v21, v27
	v_add_f32_e32 v37, v22, v26
	v_sub_f32_e32 v45, v22, v26
	v_add_f32_e32 v38, v23, v25
	v_sub_f32_e32 v46, v23, v25
	v_add_f32_e32 v48, v16, v24
	v_add_f32_e32 v48, v48, v32
	v_add_f32_e32 v48, v48, v33
	v_add_f32_e32 v48, v48, v34
	v_add_f32_e32 v48, v48, v35
	v_add_f32_e32 v48, v48, v36
	v_add_f32_e32 v48, v48, v37
	v_add_f32_e32 v48, v48, v38
	v_cvt_pk_bf16_f32 v52, v48, 0
	ds_write_b16 v3, v52 offset:0
	ds_write_b16_d16_hi v3, v52 offset:4608
	v_sub_f32_e32 v48, v16, v24
	v_fmac_f32_e32 v48, 0x3f6c835e, v32
	v_fmac_f32_e32 v48, 0x3f3504f3, v33
	v_fmac_f32_e32 v48, 0x3ec3ef15, v34
	v_fmac_f32_e32 v48, 0xbec3ef15, v36
	v_fmac_f32_e32 v48, 0xbf3504f3, v37
	v_fmac_f32_e32 v48, 0xbf6c835e, v38
	v_mul_f32_e32 v49, 0xbec3ef15, v40
	v_fmac_f32_e32 v49, 0xbf3504f3, v41
	v_fmac_f32_e32 v49, 0xbf6c835e, v42
	v_sub_f32_e32 v49, v49, v43
	v_fmac_f32_e32 v49, 0xbf6c835e, v44
	v_fmac_f32_e32 v49, 0xbf3504f3, v45
	v_fmac_f32_e32 v49, 0xbec3ef15, v46
	v_mul_f32_e32 v50, v49, v216
	v_fmac_f32_e32 v50, v48, v208
	v_mul_f32_e32 v51, v48, v216
	v_fma_f32 v51, v49, v208, -v51
	v_cvt_pk_bf16_f32 v52, v50, v51
	ds_write_b16 v3, v52 offset:9216
	ds_write_b16_d16_hi v3, v52 offset:13824
	v_add_f32_e32 v48, v16, v24
	v_fmac_f32_e32 v48, 0x3f3504f3, v32
	v_fmac_f32_e32 v48, 0xbf3504f3, v34
	v_sub_f32_e32 v48, v48, v35
	v_fmac_f32_e32 v48, 0xbf3504f3, v36
	v_fmac_f32_e32 v48, 0x3f3504f3, v38
	v_mul_f32_e32 v49, 0xbf3504f3, v40
	v_sub_f32_e32 v49, v49, v41
	v_fmac_f32_e32 v49, 0xbf3504f3, v42
	v_fmac_f32_e32 v49, 0x3f3504f3, v44
	v_add_f32_e32 v49, v49, v45
	v_fmac_f32_e32 v49, 0x3f3504f3, v46
	v_mul_f32_e32 v50, v49, v217
	v_fmac_f32_e32 v50, v48, v209
	v_mul_f32_e32 v51, v48, v217
	v_fma_f32 v51, v49, v209, -v51
	v_cvt_pk_bf16_f32 v52, v50, v51
	ds_write_b16 v3, v52 offset:18432
	ds_write_b16_d16_hi v3, v52 offset:23040
	v_sub_f32_e32 v48, v16, v24
	v_fmac_f32_e32 v48, 0x3ec3ef15, v32
	v_fmac_f32_e32 v48, 0xbf3504f3, v33
	v_fmac_f32_e32 v48, 0xbf6c835e, v34
	v_fmac_f32_e32 v48, 0x3f6c835e, v36
	v_fmac_f32_e32 v48, 0x3f3504f3, v37
	v_fmac_f32_e32 v48, 0xbec3ef15, v38
	v_mul_f32_e32 v49, 0xbf6c835e, v40
	v_fmac_f32_e32 v49, 0xbf3504f3, v41
	v_fmac_f32_e32 v49, 0x3ec3ef15, v42
	v_add_f32_e32 v49, v49, v43
	v_fmac_f32_e32 v49, 0x3ec3ef15, v44
	v_fmac_f32_e32 v49, 0xbf3504f3, v45
	v_fmac_f32_e32 v49, 0xbf6c835e, v46
	v_mul_f32_e32 v50, v49, v218
	v_fmac_f32_e32 v50, v48, v210
	v_mul_f32_e32 v51, v48, v218
	v_fma_f32 v51, v49, v210, -v51
	v_cvt_pk_bf16_f32 v52, v50, v51
	ds_write_b16 v3, v52 offset:27648
	ds_write_b16_d16_hi v3, v52 offset:32256
	v_add_f32_e32 v48, v16, v24
	v_sub_f32_e32 v48, v48, v33
	v_add_f32_e32 v48, v48, v35
	v_sub_f32_e32 v48, v48, v37
	v_sub_f32_e32 v49, 0, v40
	v_add_f32_e32 v49, v49, v42
	v_sub_f32_e32 v49, v49, v44
	v_add_f32_e32 v49, v49, v46
	v_mul_f32_e32 v50, v49, v219
	v_fmac_f32_e32 v50, v48, v211
	v_mul_f32_e32 v51, v48, v219
	v_fma_f32 v51, v49, v211, -v51
	v_cvt_pk_bf16_f32 v52, v50, v51
	ds_write_b16 v4, v52 offset:0
	ds_write_b16_d16_hi v4, v52 offset:4608
	v_sub_f32_e32 v48, v16, v24
	v_fmac_f32_e32 v48, 0xbec3ef15, v32
	v_fmac_f32_e32 v48, 0xbf3504f3, v33
	v_fmac_f32_e32 v48, 0x3f6c835e, v34
	v_fmac_f32_e32 v48, 0xbf6c835e, v36
	v_fmac_f32_e32 v48, 0x3f3504f3, v37
	v_fmac_f32_e32 v48, 0x3ec3ef15, v38
	v_mul_f32_e32 v49, 0xbf6c835e, v40
	v_fmac_f32_e32 v49, 0x3f3504f3, v41
	v_fmac_f32_e32 v49, 0x3ec3ef15, v42
	v_sub_f32_e32 v49, v49, v43
	v_fmac_f32_e32 v49, 0x3ec3ef15, v44
	v_fmac_f32_e32 v49, 0x3f3504f3, v45
	v_fmac_f32_e32 v49, 0xbf6c835e, v46
	v_mul_f32_e32 v50, v49, v220
	v_fmac_f32_e32 v50, v48, v212
	v_mul_f32_e32 v51, v48, v220
	v_fma_f32 v51, v49, v212, -v51
	v_cvt_pk_bf16_f32 v52, v50, v51
	ds_write_b16 v4, v52 offset:9216
	ds_write_b16_d16_hi v4, v52 offset:13824
	v_add_f32_e32 v48, v16, v24
	v_fmac_f32_e32 v48, 0xbf3504f3, v32
	v_fmac_f32_e32 v48, 0x3f3504f3, v34
	v_sub_f32_e32 v48, v48, v35
	v_fmac_f32_e32 v48, 0x3f3504f3, v36
	v_fmac_f32_e32 v48, 0xbf3504f3, v38
	v_mul_f32_e32 v49, 0xbf3504f3, v40
	v_add_f32_e32 v49, v49, v41
	v_fmac_f32_e32 v49, 0xbf3504f3, v42
	v_fmac_f32_e32 v49, 0x3f3504f3, v44
	v_sub_f32_e32 v49, v49, v45
	v_fmac_f32_e32 v49, 0x3f3504f3, v46
	v_mul_f32_e32 v50, v49, v221
	v_fmac_f32_e32 v50, v48, v213
	v_mul_f32_e32 v51, v48, v221
	v_fma_f32 v51, v49, v213, -v51
	v_cvt_pk_bf16_f32 v52, v50, v51
	ds_write_b16 v4, v52 offset:18432
	ds_write_b16_d16_hi v4, v52 offset:23040
	v_sub_f32_e32 v48, v16, v24
	v_fmac_f32_e32 v48, 0xbf6c835e, v32
	v_fmac_f32_e32 v48, 0x3f3504f3, v33
	v_fmac_f32_e32 v48, 0xbec3ef15, v34
	v_fmac_f32_e32 v48, 0x3ec3ef15, v36
	v_fmac_f32_e32 v48, 0xbf3504f3, v37
	v_fmac_f32_e32 v48, 0x3f6c835e, v38
	v_mul_f32_e32 v49, 0xbec3ef15, v40
	v_fmac_f32_e32 v49, 0x3f3504f3, v41
	v_fmac_f32_e32 v49, 0xbf6c835e, v42
	v_add_f32_e32 v49, v49, v43
	v_fmac_f32_e32 v49, 0xbf6c835e, v44
; __device__ __forceinline__ bf16_t f2bf(float f) { return (bf16_t)(cvt_pk_bf16(f, 0.f) & 0xffffu); }
; __device__ __forceinline__ void dft16_phase(const Ctx& X, const bf16_t* HN, bf16_t* GT) {
;     ...
;                 for (int e = 0; e < 8; ++e) { float re = 0.f, im = 0.f;
; #pragma unroll
;                     for (int a = 0; a < 16; ++a) { const unsigned wv = xin[a][e >> 1]; const float x = (e & 1) ? bf2f(wv >> 16) : bf2f(wv & 0xffffu); re += x * cw[a]; im -= x * sw[a]; }
;                     const float orr = re * tc - im * ts, oi = re * ts + im * tc;
;                     tile[((kl * 2 + 0) * 64 + cchunk * 8 + e) * 72 + i] = f2bf(orr); tile[((kl * 2 + 1) * 64 + cchunk * 8 + e) * 72 + i] = f2bf(oi); } }
	v_fmac_f32_e32 v49, 0x3f3504f3, v45
	v_fmac_f32_e32 v49, 0xbec3ef15, v46
	v_mul_f32_e32 v50, v49, v222
	v_fmac_f32_e32 v50, v48, v214
	v_mul_f32_e32 v51, v48, v222
	v_fma_f32 v51, v49, v214, -v51
	v_cvt_pk_bf16_f32 v52, v50, v51
	ds_write_b16 v4, v52 offset:27648
	ds_write_b16_d16_hi v4, v52 offset:32256
	v_add_f32_e32 v48, v16, v24
	v_sub_f32_e32 v48, v48, v32
	v_add_f32_e32 v48, v48, v33
	v_sub_f32_e32 v48, v48, v34
	v_add_f32_e32 v48, v48, v35
	v_sub_f32_e32 v48, v48, v36
	v_add_f32_e32 v48, v48, v37
	v_sub_f32_e32 v48, v48, v38
	v_mul_f32_e32 v50, v48, v215
	v_mul_f32_e32 v51, v48, v223
	v_sub_f32_e32 v51, 0, v51
	v_cvt_pk_bf16_f32 v52, v50, v51
	ds_write_b16 v4, v52 offset:36864
	ds_write_b16_d16_hi v4, v52 offset:41472
	v_and_b32_e32 v16, 0xffff0000, v130
	v_and_b32_e32 v17, 0xffff0000, v134
	v_and_b32_e32 v18, 0xffff0000, v138
	v_and_b32_e32 v19, 0xffff0000, v142
	v_and_b32_e32 v20, 0xffff0000, v146
	v_and_b32_e32 v21, 0xffff0000, v150
	v_and_b32_e32 v22, 0xffff0000, v154
	v_and_b32_e32 v23, 0xffff0000, v158
	v_and_b32_e32 v24, 0xffff0000, v162
	v_and_b32_e32 v25, 0xffff0000, v166
	v_and_b32_e32 v26, 0xffff0000, v170
	v_and_b32_e32 v27, 0xffff0000, v174
	v_and_b32_e32 v28, 0xffff0000, v178
	v_and_b32_e32 v29, 0xffff0000, v182
	v_and_b32_e32 v30, 0xffff0000, v186
	v_and_b32_e32 v31, 0xffff0000, v190
	v_add_f32_e32 v32, v17, v31
	v_sub_f32_e32 v40, v17, v31
	v_add_f32_e32 v33, v18, v30
	v_sub_f32_e32 v41, v18, v30
	v_add_f32_e32 v34, v19, v29
	v_sub_f32_e32 v42, v19, v29
	v_add_f32_e32 v35, v20, v28
	v_sub_f32_e32 v43, v20, v28
	v_add_f32_e32 v36, v21, v27
	v_sub_f32_e32 v44, v21, v27
	v_add_f32_e32 v37, v22, v26
	v_sub_f32_e32 v45, v22, v26
	v_add_f32_e32 v38, v23, v25
	v_sub_f32_e32 v46, v23, v25
	v_add_f32_e32 v48, v16, v24
	v_add_f32_e32 v48, v48, v32
	v_add_f32_e32 v48, v48, v33
	v_add_f32_e32 v48, v48, v34
	v_add_f32_e32 v48, v48, v35
	v_add_f32_e32 v48, v48, v36
	v_add_f32_e32 v48, v48, v37
	v_add_f32_e32 v48, v48, v38
	v_cvt_pk_bf16_f32 v52, v48, 0
	ds_write_b16 v3, v52 offset:144
	ds_write_b16_d16_hi v3, v52 offset:4752
	v_sub_f32_e32 v48, v16, v24
	v_fmac_f32_e32 v48, 0x3f6c835e, v32
	v_fmac_f32_e32 v48, 0x3f3504f3, v33
	v_fmac_f32_e32 v48, 0x3ec3ef15, v34
	v_fmac_f32_e32 v48, 0xbec3ef15, v36
	v_fmac_f32_e32 v48, 0xbf3504f3, v37
	v_fmac_f32_e32 v48, 0xbf6c835e, v38
	v_mul_f32_e32 v49, 0xbec3ef15, v40
	v_fmac_f32_e32 v49, 0xbf3504f3, v41
	v_fmac_f32_e32 v49, 0xbf6c835e, v42
	v_sub_f32_e32 v49, v49, v43
	v_fmac_f32_e32 v49, 0xbf6c835e, v44
	v_fmac_f32_e32 v49, 0xbf3504f3, v45
	v_fmac_f32_e32 v49, 0xbec3ef15, v46
	v_mul_f32_e32 v50, v49, v216
	v_fmac_f32_e32 v50, v48, v208
	v_mul_f32_e32 v51, v48, v216
	v_fma_f32 v51, v49, v208, -v51
	v_cvt_pk_bf16_f32 v52, v50, v51
	ds_write_b16 v3, v52 offset:9360
	ds_write_b16_d16_hi v3, v52 offset:13968
	v_add_f32_e32 v48, v16, v24
	v_fmac_f32_e32 v48, 0x3f3504f3, v32
	v_fmac_f32_e32 v48, 0xbf3504f3, v34
	v_sub_f32_e32 v48, v48, v35
	v_fmac_f32_e32 v48, 0xbf3504f3, v36
	v_fmac_f32_e32 v48, 0x3f3504f3, v38
	v_mul_f32_e32 v49, 0xbf3504f3, v40
	v_sub_f32_e32 v49, v49, v41
	v_fmac_f32_e32 v49, 0xbf3504f3, v42
	v_fmac_f32_e32 v49, 0x3f3504f3, v44
	v_add_f32_e32 v49, v49, v45
	v_fmac_f32_e32 v49, 0x3f3504f3, v46
	v_mul_f32_e32 v50, v49, v217
	v_fmac_f32_e32 v50, v48, v209
	v_mul_f32_e32 v51, v48, v217
	v_fma_f32 v51, v49, v209, -v51
	v_cvt_pk_bf16_f32 v52, v50, v51
	ds_write_b16 v3, v52 offset:18576
	ds_write_b16_d16_hi v3, v52 offset:23184
	v_sub_f32_e32 v48, v16, v24
	v_fmac_f32_e32 v48, 0x3ec3ef15, v32
	v_fmac_f32_e32 v48, 0xbf3504f3, v33
	v_fmac_f32_e32 v48, 0xbf6c835e, v34
	v_fmac_f32_e32 v48, 0x3f6c835e, v36
	v_fmac_f32_e32 v48, 0x3f3504f3, v37
	v_fmac_f32_e32 v48, 0xbec3ef15, v38
	v_mul_f32_e32 v49, 0xbf6c835e, v40
	v_fmac_f32_e32 v49, 0xbf3504f3, v41
	v_fmac_f32_e32 v49, 0x3ec3ef15, v42
	v_add_f32_e32 v49, v49, v43
	v_fmac_f32_e32 v49, 0x3ec3ef15, v44
	v_fmac_f32_e32 v49, 0xbf3504f3, v45
	v_fmac_f32_e32 v49, 0xbf6c835e, v46
	v_mul_f32_e32 v50, v49, v218
	v_fmac_f32_e32 v50, v48, v210
	v_mul_f32_e32 v51, v48, v218
	v_fma_f32 v51, v49, v210, -v51
	v_cvt_pk_bf16_f32 v52, v50, v51
	ds_write_b16 v3, v52 offset:27792
	ds_write_b16_d16_hi v3, v52 offset:32400
	v_add_f32_e32 v48, v16, v24
	v_sub_f32_e32 v48, v48, v33
	v_add_f32_e32 v48, v48, v35
	v_sub_f32_e32 v48, v48, v37
	v_sub_f32_e32 v49, 0, v40
	v_add_f32_e32 v49, v49, v42
	v_sub_f32_e32 v49, v49, v44
	v_add_f32_e32 v49, v49, v46
	v_mul_f32_e32 v50, v49, v219
	v_fmac_f32_e32 v50, v48, v211
	v_mul_f32_e32 v51, v48, v219
	v_fma_f32 v51, v49, v211, -v51
	v_cvt_pk_bf16_f32 v52, v50, v51
	ds_write_b16 v4, v52 offset:144
	ds_write_b16_d16_hi v4, v52 offset:4752
	v_sub_f32_e32 v48, v16, v24
	v_fmac_f32_e32 v48, 0xbec3ef15, v32
	v_fmac_f32_e32 v48, 0xbf3504f3, v33
	v_fmac_f32_e32 v48, 0x3f6c835e, v34
	v_fmac_f32_e32 v48, 0xbf6c835e, v36
	v_fmac_f32_e32 v48, 0x3f3504f3, v37
	v_fmac_f32_e32 v48, 0x3ec3ef15, v38
	v_mul_f32_e32 v49, 0xbf6c835e, v40
	v_fmac_f32_e32 v49, 0x3f3504f3, v41
	v_fmac_f32_e32 v49, 0x3ec3ef15, v42
	v_sub_f32_e32 v49, v49, v43
	v_fmac_f32_e32 v49, 0x3ec3ef15, v44
	v_fmac_f32_e32 v49, 0x3f3504f3, v45
	v_fmac_f32_e32 v49, 0xbf6c835e, v46
	v_mul_f32_e32 v50, v49, v220
	v_fmac_f32_e32 v50, v48, v212
	v_mul_f32_e32 v51, v48, v220
	v_fma_f32 v51, v49, v212, -v51
	v_cvt_pk_bf16_f32 v52, v50, v51
	ds_write_b16 v4, v52 offset:9360
	ds_write_b16_d16_hi v4, v52 offset:13968
	v_add_f32_e32 v48, v16, v24
	v_fmac_f32_e32 v48, 0xbf3504f3, v32
	v_fmac_f32_e32 v48, 0x3f3504f3, v34
	v_sub_f32_e32 v48, v48, v35
	v_fmac_f32_e32 v48, 0x3f3504f3, v36
	v_fmac_f32_e32 v48, 0xbf3504f3, v38
	v_mul_f32_e32 v49, 0xbf3504f3, v40
	v_add_f32_e32 v49, v49, v41
; __device__ __forceinline__ bf16_t f2bf(float f) { return (bf16_t)(cvt_pk_bf16(f, 0.f) & 0xffffu); }
; __device__ __forceinline__ void dft16_phase(const Ctx& X, const bf16_t* HN, bf16_t* GT) {
;     ...
;                 for (int e = 0; e < 8; ++e) { float re = 0.f, im = 0.f;
; #pragma unroll
;                     for (int a = 0; a < 16; ++a) { const unsigned wv = xin[a][e >> 1]; const float x = (e & 1) ? bf2f(wv >> 16) : bf2f(wv & 0xffffu); re += x * cw[a]; im -= x * sw[a]; }
;                     const float orr = re * tc - im * ts, oi = re * ts + im * tc;
;                     tile[((kl * 2 + 0) * 64 + cchunk * 8 + e) * 72 + i] = f2bf(orr); tile[((kl * 2 + 1) * 64 + cchunk * 8 + e) * 72 + i] = f2bf(oi); } }
	v_fmac_f32_e32 v49, 0xbf3504f3, v42
	v_fmac_f32_e32 v49, 0x3f3504f3, v44
	v_sub_f32_e32 v49, v49, v45
	v_fmac_f32_e32 v49, 0x3f3504f3, v46
	v_mul_f32_e32 v50, v49, v221
	v_fmac_f32_e32 v50, v48, v213
	v_mul_f32_e32 v51, v48, v221
	v_fma_f32 v51, v49, v213, -v51
	v_cvt_pk_bf16_f32 v52, v50, v51
	ds_write_b16 v4, v52 offset:18576
	ds_write_b16_d16_hi v4, v52 offset:23184
	v_sub_f32_e32 v48, v16, v24
	v_fmac_f32_e32 v48, 0xbf6c835e, v32
	v_fmac_f32_e32 v48, 0x3f3504f3, v33
	v_fmac_f32_e32 v48, 0xbec3ef15, v34
	v_fmac_f32_e32 v48, 0x3ec3ef15, v36
	v_fmac_f32_e32 v48, 0xbf3504f3, v37
	v_fmac_f32_e32 v48, 0x3f6c835e, v38
	v_mul_f32_e32 v49, 0xbec3ef15, v40
	v_fmac_f32_e32 v49, 0x3f3504f3, v41
	v_fmac_f32_e32 v49, 0xbf6c835e, v42
	v_add_f32_e32 v49, v49, v43
	v_fmac_f32_e32 v49, 0xbf6c835e, v44
	v_fmac_f32_e32 v49, 0x3f3504f3, v45
	v_fmac_f32_e32 v49, 0xbec3ef15, v46
	v_mul_f32_e32 v50, v49, v222
	v_fmac_f32_e32 v50, v48, v214
	v_mul_f32_e32 v51, v48, v222
	v_fma_f32 v51, v49, v214, -v51
	v_cvt_pk_bf16_f32 v52, v50, v51
	ds_write_b16 v4, v52 offset:27792
	ds_write_b16_d16_hi v4, v52 offset:32400
	v_add_f32_e32 v48, v16, v24
	v_sub_f32_e32 v48, v48, v32
	v_add_f32_e32 v48, v48, v33
	v_sub_f32_e32 v48, v48, v34
	v_add_f32_e32 v48, v48, v35
	v_sub_f32_e32 v48, v48, v36
	v_add_f32_e32 v48, v48, v37
	v_sub_f32_e32 v48, v48, v38
	v_mul_f32_e32 v50, v48, v215
	v_mul_f32_e32 v51, v48, v223
	v_sub_f32_e32 v51, 0, v51
	v_cvt_pk_bf16_f32 v52, v50, v51
	ds_write_b16 v4, v52 offset:37008
	ds_write_b16_d16_hi v4, v52 offset:41616
	v_lshlrev_b32_e32 v16, 16, v131
	v_lshlrev_b32_e32 v17, 16, v135
	v_lshlrev_b32_e32 v18, 16, v139
	v_lshlrev_b32_e32 v19, 16, v143
	v_lshlrev_b32_e32 v20, 16, v147
	v_lshlrev_b32_e32 v21, 16, v151
	v_lshlrev_b32_e32 v22, 16, v155
	v_lshlrev_b32_e32 v23, 16, v159
	v_lshlrev_b32_e32 v24, 16, v163
	v_lshlrev_b32_e32 v25, 16, v167
	v_lshlrev_b32_e32 v26, 16, v171
	v_lshlrev_b32_e32 v27, 16, v175
	v_lshlrev_b32_e32 v28, 16, v179
	v_lshlrev_b32_e32 v29, 16, v183
	v_lshlrev_b32_e32 v30, 16, v187
	v_lshlrev_b32_e32 v31, 16, v191
	v_add_f32_e32 v32, v17, v31
	v_sub_f32_e32 v40, v17, v31
	v_add_f32_e32 v33, v18, v30
	v_sub_f32_e32 v41, v18, v30
	v_add_f32_e32 v34, v19, v29
	v_sub_f32_e32 v42, v19, v29
	v_add_f32_e32 v35, v20, v28
	v_sub_f32_e32 v43, v20, v28
	v_add_f32_e32 v36, v21, v27
	v_sub_f32_e32 v44, v21, v27
	v_add_f32_e32 v37, v22, v26
	v_sub_f32_e32 v45, v22, v26
	v_add_f32_e32 v38, v23, v25
	v_sub_f32_e32 v46, v23, v25
	v_add_f32_e32 v48, v16, v24
	v_add_f32_e32 v48, v48, v32
	v_add_f32_e32 v48, v48, v33
	v_add_f32_e32 v48, v48, v34
	v_add_f32_e32 v48, v48, v35
	v_add_f32_e32 v48, v48, v36
	v_add_f32_e32 v48, v48, v37
	v_add_f32_e32 v48, v48, v38
	v_cvt_pk_bf16_f32 v52, v48, 0
	ds_write_b16 v3, v52 offset:288
	ds_write_b16_d16_hi v3, v52 offset:4896
	v_sub_f32_e32 v48, v16, v24
	v_fmac_f32_e32 v48, 0x3f6c835e, v32
	v_fmac_f32_e32 v48, 0x3f3504f3, v33
	v_fmac_f32_e32 v48, 0x3ec3ef15, v34
	v_fmac_f32_e32 v48, 0xbec3ef15, v36
	v_fmac_f32_e32 v48, 0xbf3504f3, v37
	v_fmac_f32_e32 v48, 0xbf6c835e, v38
	v_mul_f32_e32 v49, 0xbec3ef15, v40
	v_fmac_f32_e32 v49, 0xbf3504f3, v41
	v_fmac_f32_e32 v49, 0xbf6c835e, v42
	v_sub_f32_e32 v49, v49, v43
	v_fmac_f32_e32 v49, 0xbf6c835e, v44
	v_fmac_f32_e32 v49, 0xbf3504f3, v45
	v_fmac_f32_e32 v49, 0xbec3ef15, v46
	v_mul_f32_e32 v50, v49, v216
	v_fmac_f32_e32 v50, v48, v208
	v_mul_f32_e32 v51, v48, v216
	v_fma_f32 v51, v49, v208, -v51
	v_cvt_pk_bf16_f32 v52, v50, v51
	ds_write_b16 v3, v52 offset:9504
	ds_write_b16_d16_hi v3, v52 offset:14112
	v_add_f32_e32 v48, v16, v24
	v_fmac_f32_e32 v48, 0x3f3504f3, v32
	v_fmac_f32_e32 v48, 0xbf3504f3, v34
	v_sub_f32_e32 v48, v48, v35
	v_fmac_f32_e32 v48, 0xbf3504f3, v36
	v_fmac_f32_e32 v48, 0x3f3504f3, v38
	v_mul_f32_e32 v49, 0xbf3504f3, v40
	v_sub_f32_e32 v49, v49, v41
	v_fmac_f32_e32 v49, 0xbf3504f3, v42
	v_fmac_f32_e32 v49, 0x3f3504f3, v44
	v_add_f32_e32 v49, v49, v45
	v_fmac_f32_e32 v49, 0x3f3504f3, v46
	v_mul_f32_e32 v50, v49, v217
	v_fmac_f32_e32 v50, v48, v209
	v_mul_f32_e32 v51, v48, v217
	v_fma_f32 v51, v49, v209, -v51
	v_cvt_pk_bf16_f32 v52, v50, v51
	ds_write_b16 v3, v52 offset:18720
	ds_write_b16_d16_hi v3, v52 offset:23328
	v_sub_f32_e32 v48, v16, v24
	v_fmac_f32_e32 v48, 0x3ec3ef15, v32
	v_fmac_f32_e32 v48, 0xbf3504f3, v33
	v_fmac_f32_e32 v48, 0xbf6c835e, v34
	v_fmac_f32_e32 v48, 0x3f6c835e, v36
	v_fmac_f32_e32 v48, 0x3f3504f3, v37
	v_fmac_f32_e32 v48, 0xbec3ef15, v38
	v_mul_f32_e32 v49, 0xbf6c835e, v40
	v_fmac_f32_e32 v49, 0xbf3504f3, v41
	v_fmac_f32_e32 v49, 0x3ec3ef15, v42
	v_add_f32_e32 v49, v49, v43
	v_fmac_f32_e32 v49, 0x3ec3ef15, v44
	v_fmac_f32_e32 v49, 0xbf3504f3, v45
	v_fmac_f32_e32 v49, 0xbf6c835e, v46
	v_mul_f32_e32 v50, v49, v218
	v_fmac_f32_e32 v50, v48, v210
	v_mul_f32_e32 v51, v48, v218
	v_fma_f32 v51, v49, v210, -v51
	v_cvt_pk_bf16_f32 v52, v50, v51
	ds_write_b16 v3, v52 offset:27936
	ds_write_b16_d16_hi v3, v52 offset:32544
	v_add_f32_e32 v48, v16, v24
	v_sub_f32_e32 v48, v48, v33
	v_add_f32_e32 v48, v48, v35
	v_sub_f32_e32 v48, v48, v37
	v_sub_f32_e32 v49, 0, v40
	v_add_f32_e32 v49, v49, v42
	v_sub_f32_e32 v49, v49, v44
	v_add_f32_e32 v49, v49, v46
	v_mul_f32_e32 v50, v49, v219
	v_fmac_f32_e32 v50, v48, v211
	v_mul_f32_e32 v51, v48, v219
	v_fma_f32 v51, v49, v211, -v51
	v_cvt_pk_bf16_f32 v52, v50, v51
	ds_write_b16 v4, v52 offset:288
	ds_write_b16_d16_hi v4, v52 offset:4896
	v_sub_f32_e32 v48, v16, v24
	v_fmac_f32_e32 v48, 0xbec3ef15, v32
	v_fmac_f32_e32 v48, 0xbf3504f3, v33
	v_fmac_f32_e32 v48, 0x3f6c835e, v34
	v_fmac_f32_e32 v48, 0xbf6c835e, v36
	v_fmac_f32_e32 v48, 0x3f3504f3, v37
	v_fmac_f32_e32 v48, 0x3ec3ef15, v38
; __device__ __forceinline__ bf16_t f2bf(float f) { return (bf16_t)(cvt_pk_bf16(f, 0.f) & 0xffffu); }
; __device__ __forceinline__ void dft16_phase(const Ctx& X, const bf16_t* HN, bf16_t* GT) {
;     ...
;                 for (int e = 0; e < 8; ++e) { float re = 0.f, im = 0.f;
; #pragma unroll
;                     for (int a = 0; a < 16; ++a) { const unsigned wv = xin[a][e >> 1]; const float x = (e & 1) ? bf2f(wv >> 16) : bf2f(wv & 0xffffu); re += x * cw[a]; im -= x * sw[a]; }
;                     const float orr = re * tc - im * ts, oi = re * ts + im * tc;
;                     tile[((kl * 2 + 0) * 64 + cchunk * 8 + e) * 72 + i] = f2bf(orr); tile[((kl * 2 + 1) * 64 + cchunk * 8 + e) * 72 + i] = f2bf(oi); } }
	v_mul_f32_e32 v49, 0xbf6c835e, v40
	v_fmac_f32_e32 v49, 0x3f3504f3, v41
	v_fmac_f32_e32 v49, 0x3ec3ef15, v42
	v_sub_f32_e32 v49, v49, v43
	v_fmac_f32_e32 v49, 0x3ec3ef15, v44
	v_fmac_f32_e32 v49, 0x3f3504f3, v45
	v_fmac_f32_e32 v49, 0xbf6c835e, v46
	v_mul_f32_e32 v50, v49, v220
	v_fmac_f32_e32 v50, v48, v212
	v_mul_f32_e32 v51, v48, v220
	v_fma_f32 v51, v49, v212, -v51
	v_cvt_pk_bf16_f32 v52, v50, v51
	ds_write_b16 v4, v52 offset:9504
	ds_write_b16_d16_hi v4, v52 offset:14112
	v_add_f32_e32 v48, v16, v24
	v_fmac_f32_e32 v48, 0xbf3504f3, v32
	v_fmac_f32_e32 v48, 0x3f3504f3, v34
	v_sub_f32_e32 v48, v48, v35
	v_fmac_f32_e32 v48, 0x3f3504f3, v36
	v_fmac_f32_e32 v48, 0xbf3504f3, v38
	v_mul_f32_e32 v49, 0xbf3504f3, v40
	v_add_f32_e32 v49, v49, v41
	v_fmac_f32_e32 v49, 0xbf3504f3, v42
	v_fmac_f32_e32 v49, 0x3f3504f3, v44
	v_sub_f32_e32 v49, v49, v45
	v_fmac_f32_e32 v49, 0x3f3504f3, v46
	v_mul_f32_e32 v50, v49, v221
	v_fmac_f32_e32 v50, v48, v213
	v_mul_f32_e32 v51, v48, v221
	v_fma_f32 v51, v49, v213, -v51
	v_cvt_pk_bf16_f32 v52, v50, v51
	ds_write_b16 v4, v52 offset:18720
	ds_write_b16_d16_hi v4, v52 offset:23328
	v_sub_f32_e32 v48, v16, v24
	v_fmac_f32_e32 v48, 0xbf6c835e, v32
	v_fmac_f32_e32 v48, 0x3f3504f3, v33
	v_fmac_f32_e32 v48, 0xbec3ef15, v34
	v_fmac_f32_e32 v48, 0x3ec3ef15, v36
	v_fmac_f32_e32 v48, 0xbf3504f3, v37
	v_fmac_f32_e32 v48, 0x3f6c835e, v38
	v_mul_f32_e32 v49, 0xbec3ef15, v40
	v_fmac_f32_e32 v49, 0x3f3504f3, v41
	v_fmac_f32_e32 v49, 0xbf6c835e, v42
	v_add_f32_e32 v49, v49, v43
	v_fmac_f32_e32 v49, 0xbf6c835e, v44
	v_fmac_f32_e32 v49, 0x3f3504f3, v45
	v_fmac_f32_e32 v49, 0xbec3ef15, v46
	v_mul_f32_e32 v50, v49, v222
	v_fmac_f32_e32 v50, v48, v214
	v_mul_f32_e32 v51, v48, v222
	v_fma_f32 v51, v49, v214, -v51
	v_cvt_pk_bf16_f32 v52, v50, v51
	ds_write_b16 v4, v52 offset:27936
	ds_write_b16_d16_hi v4, v52 offset:32544
	v_add_f32_e32 v48, v16, v24
	v_sub_f32_e32 v48, v48, v32
	v_add_f32_e32 v48, v48, v33
	v_sub_f32_e32 v48, v48, v34
	v_add_f32_e32 v48, v48, v35
	v_sub_f32_e32 v48, v48, v36
	v_add_f32_e32 v48, v48, v37
	v_sub_f32_e32 v48, v48, v38
	v_mul_f32_e32 v50, v48, v215
	v_mul_f32_e32 v51, v48, v223
	v_sub_f32_e32 v51, 0, v51
	v_cvt_pk_bf16_f32 v52, v50, v51
	ds_write_b16 v4, v52 offset:37152
	ds_write_b16_d16_hi v4, v52 offset:41760
	v_and_b32_e32 v16, 0xffff0000, v131
	v_and_b32_e32 v17, 0xffff0000, v135
	v_and_b32_e32 v18, 0xffff0000, v139
	v_and_b32_e32 v19, 0xffff0000, v143
	v_and_b32_e32 v20, 0xffff0000, v147
	v_and_b32_e32 v21, 0xffff0000, v151
	v_and_b32_e32 v22, 0xffff0000, v155
	v_and_b32_e32 v23, 0xffff0000, v159
	v_and_b32_e32 v24, 0xffff0000, v163
	v_and_b32_e32 v25, 0xffff0000, v167
	v_and_b32_e32 v26, 0xffff0000, v171
	v_and_b32_e32 v27, 0xffff0000, v175
	v_and_b32_e32 v28, 0xffff0000, v179
	v_and_b32_e32 v29, 0xffff0000, v183
	v_and_b32_e32 v30, 0xffff0000, v187
	v_and_b32_e32 v31, 0xffff0000, v191
	v_add_f32_e32 v32, v17, v31
	v_sub_f32_e32 v40, v17, v31
	v_add_f32_e32 v33, v18, v30
	v_sub_f32_e32 v41, v18, v30
	v_add_f32_e32 v34, v19, v29
	v_sub_f32_e32 v42, v19, v29
	v_add_f32_e32 v35, v20, v28
	v_sub_f32_e32 v43, v20, v28
	v_add_f32_e32 v36, v21, v27
	v_sub_f32_e32 v44, v21, v27
	v_add_f32_e32 v37, v22, v26
	v_sub_f32_e32 v45, v22, v26
	v_add_f32_e32 v38, v23, v25
	v_sub_f32_e32 v46, v23, v25
	v_add_f32_e32 v48, v16, v24
	v_add_f32_e32 v48, v48, v32
	v_add_f32_e32 v48, v48, v33
	v_add_f32_e32 v48, v48, v34
	v_add_f32_e32 v48, v48, v35
	v_add_f32_e32 v48, v48, v36
	v_add_f32_e32 v48, v48, v37
	v_add_f32_e32 v48, v48, v38
	v_cvt_pk_bf16_f32 v52, v48, 0
	ds_write_b16 v3, v52 offset:432
	ds_write_b16_d16_hi v3, v52 offset:5040
	v_sub_f32_e32 v48, v16, v24
	v_fmac_f32_e32 v48, 0x3f6c835e, v32
	v_fmac_f32_e32 v48, 0x3f3504f3, v33
	v_fmac_f32_e32 v48, 0x3ec3ef15, v34
	v_fmac_f32_e32 v48, 0xbec3ef15, v36
	v_fmac_f32_e32 v48, 0xbf3504f3, v37
	v_fmac_f32_e32 v48, 0xbf6c835e, v38
	v_mul_f32_e32 v49, 0xbec3ef15, v40
	v_fmac_f32_e32 v49, 0xbf3504f3, v41
	v_fmac_f32_e32 v49, 0xbf6c835e, v42
	v_sub_f32_e32 v49, v49, v43
	v_fmac_f32_e32 v49, 0xbf6c835e, v44
	v_fmac_f32_e32 v49, 0xbf3504f3, v45
	v_fmac_f32_e32 v49, 0xbec3ef15, v46
	v_mul_f32_e32 v50, v49, v216
	v_fmac_f32_e32 v50, v48, v208
	v_mul_f32_e32 v51, v48, v216
	v_fma_f32 v51, v49, v208, -v51
	v_cvt_pk_bf16_f32 v52, v50, v51
	ds_write_b16 v3, v52 offset:9648
	ds_write_b16_d16_hi v3, v52 offset:14256
	v_add_f32_e32 v48, v16, v24
	v_fmac_f32_e32 v48, 0x3f3504f3, v32
	v_fmac_f32_e32 v48, 0xbf3504f3, v34
	v_sub_f32_e32 v48, v48, v35
	v_fmac_f32_e32 v48, 0xbf3504f3, v36
	v_fmac_f32_e32 v48, 0x3f3504f3, v38
	v_mul_f32_e32 v49, 0xbf3504f3, v40
	v_sub_f32_e32 v49, v49, v41
	v_fmac_f32_e32 v49, 0xbf3504f3, v42
	v_fmac_f32_e32 v49, 0x3f3504f3, v44
	v_add_f32_e32 v49, v49, v45
	v_fmac_f32_e32 v49, 0x3f3504f3, v46
	v_mul_f32_e32 v50, v49, v217
	v_fmac_f32_e32 v50, v48, v209
	v_mul_f32_e32 v51, v48, v217
	v_fma_f32 v51, v49, v209, -v51
	v_cvt_pk_bf16_f32 v52, v50, v51
	ds_write_b16 v3, v52 offset:18864
	ds_write_b16_d16_hi v3, v52 offset:23472
	v_sub_f32_e32 v48, v16, v24
	v_fmac_f32_e32 v48, 0x3ec3ef15, v32
; __device__ __forceinline__ bf16_t f2bf(float f) { return (bf16_t)(cvt_pk_bf16(f, 0.f) & 0xffffu); }
; __device__ __forceinline__ void dft16_phase(const Ctx& X, const bf16_t* HN, bf16_t* GT) {
;     ...
;                 for (int e = 0; e < 8; ++e) { float re = 0.f, im = 0.f;
; #pragma unroll
;                     for (int a = 0; a < 16; ++a) { const unsigned wv = xin[a][e >> 1]; const float x = (e & 1) ? bf2f(wv >> 16) : bf2f(wv & 0xffffu); re += x * cw[a]; im -= x * sw[a]; }
;                     const float orr = re * tc - im * ts, oi = re * ts + im * tc;
;                     tile[((kl * 2 + 0) * 64 + cchunk * 8 + e) * 72 + i] = f2bf(orr); tile[((kl * 2 + 1) * 64 + cchunk * 8 + e) * 72 + i] = f2bf(oi); } }
;             __syncthreads();
; #pragma unroll
;             for (int q = 0; q < 8; ++q) { const int cid = q * 512 + X.tid, row = cid >> 3, c8 = cid & 7, kl = row >> 7, ri = (row >> 6) & 1, ch = row & 63;
;                 if (kq * 4 + kl > 8) continue;
;                 const u32x4 v = *(const u32x4*)(tile + row * 72 + c8 * 8);
;                 *(u32x4*)(GT + ((size_t)(b * 9 + kq * 4 + kl) * 1024 + ch0 + ch) * 512 + ri * 256 + b0 + c8 * 8) = v; }
	v_fmac_f32_e32 v48, 0xbf3504f3, v33
	v_fmac_f32_e32 v48, 0xbf6c835e, v34
	v_fmac_f32_e32 v48, 0x3f6c835e, v36
	v_fmac_f32_e32 v48, 0x3f3504f3, v37
	v_fmac_f32_e32 v48, 0xbec3ef15, v38
	v_mul_f32_e32 v49, 0xbf6c835e, v40
	v_fmac_f32_e32 v49, 0xbf3504f3, v41
	v_fmac_f32_e32 v49, 0x3ec3ef15, v42
	v_add_f32_e32 v49, v49, v43
	v_fmac_f32_e32 v49, 0x3ec3ef15, v44
	v_fmac_f32_e32 v49, 0xbf3504f3, v45
	v_fmac_f32_e32 v49, 0xbf6c835e, v46
	v_mul_f32_e32 v50, v49, v218
	v_fmac_f32_e32 v50, v48, v210
	v_mul_f32_e32 v51, v48, v218
	v_fma_f32 v51, v49, v210, -v51
	v_cvt_pk_bf16_f32 v52, v50, v51
	ds_write_b16 v3, v52 offset:28080
	ds_write_b16_d16_hi v3, v52 offset:32688
	v_add_f32_e32 v48, v16, v24
	v_sub_f32_e32 v48, v48, v33
	v_add_f32_e32 v48, v48, v35
	v_sub_f32_e32 v48, v48, v37
	v_sub_f32_e32 v49, 0, v40
	v_add_f32_e32 v49, v49, v42
	v_sub_f32_e32 v49, v49, v44
	v_add_f32_e32 v49, v49, v46
	v_mul_f32_e32 v50, v49, v219
	v_fmac_f32_e32 v50, v48, v211
	v_mul_f32_e32 v51, v48, v219
	v_fma_f32 v51, v49, v211, -v51
	v_cvt_pk_bf16_f32 v52, v50, v51
	ds_write_b16 v4, v52 offset:432
	ds_write_b16_d16_hi v4, v52 offset:5040
	v_sub_f32_e32 v48, v16, v24
	v_fmac_f32_e32 v48, 0xbec3ef15, v32
	v_fmac_f32_e32 v48, 0xbf3504f3, v33
	v_fmac_f32_e32 v48, 0x3f6c835e, v34
	v_fmac_f32_e32 v48, 0xbf6c835e, v36
	v_fmac_f32_e32 v48, 0x3f3504f3, v37
	v_fmac_f32_e32 v48, 0x3ec3ef15, v38
	v_mul_f32_e32 v49, 0xbf6c835e, v40
	v_fmac_f32_e32 v49, 0x3f3504f3, v41
	v_fmac_f32_e32 v49, 0x3ec3ef15, v42
	v_sub_f32_e32 v49, v49, v43
	v_fmac_f32_e32 v49, 0x3ec3ef15, v44
	v_fmac_f32_e32 v49, 0x3f3504f3, v45
	v_fmac_f32_e32 v49, 0xbf6c835e, v46
	v_mul_f32_e32 v50, v49, v220
	v_fmac_f32_e32 v50, v48, v212
	v_mul_f32_e32 v51, v48, v220
	v_fma_f32 v51, v49, v212, -v51
	v_cvt_pk_bf16_f32 v52, v50, v51
	ds_write_b16 v4, v52 offset:9648
	ds_write_b16_d16_hi v4, v52 offset:14256
	v_add_f32_e32 v48, v16, v24
	v_fmac_f32_e32 v48, 0xbf3504f3, v32
	v_fmac_f32_e32 v48, 0x3f3504f3, v34
	v_sub_f32_e32 v48, v48, v35
	v_fmac_f32_e32 v48, 0x3f3504f3, v36
	v_fmac_f32_e32 v48, 0xbf3504f3, v38
	v_mul_f32_e32 v49, 0xbf3504f3, v40
	v_add_f32_e32 v49, v49, v41
	v_fmac_f32_e32 v49, 0xbf3504f3, v42
	v_fmac_f32_e32 v49, 0x3f3504f3, v44
	v_sub_f32_e32 v49, v49, v45
	v_fmac_f32_e32 v49, 0x3f3504f3, v46
	v_mul_f32_e32 v50, v49, v221
	v_fmac_f32_e32 v50, v48, v213
	v_mul_f32_e32 v51, v48, v221
	v_fma_f32 v51, v49, v213, -v51
	v_cvt_pk_bf16_f32 v52, v50, v51
	ds_write_b16 v4, v52 offset:18864
	ds_write_b16_d16_hi v4, v52 offset:23472
	v_sub_f32_e32 v48, v16, v24
	v_fmac_f32_e32 v48, 0xbf6c835e, v32
	v_fmac_f32_e32 v48, 0x3f3504f3, v33
	v_fmac_f32_e32 v48, 0xbec3ef15, v34
	v_fmac_f32_e32 v48, 0x3ec3ef15, v36
	v_fmac_f32_e32 v48, 0xbf3504f3, v37
	v_fmac_f32_e32 v48, 0x3f6c835e, v38
	v_mul_f32_e32 v49, 0xbec3ef15, v40
	v_fmac_f32_e32 v49, 0x3f3504f3, v41
	v_fmac_f32_e32 v49, 0xbf6c835e, v42
	v_add_f32_e32 v49, v49, v43
	v_fmac_f32_e32 v49, 0xbf6c835e, v44
	v_fmac_f32_e32 v49, 0x3f3504f3, v45
	v_fmac_f32_e32 v49, 0xbec3ef15, v46
	v_mul_f32_e32 v50, v49, v222
	v_fmac_f32_e32 v50, v48, v214
	v_mul_f32_e32 v51, v48, v222
	v_fma_f32 v51, v49, v214, -v51
	v_cvt_pk_bf16_f32 v52, v50, v51
	ds_write_b16 v4, v52 offset:28080
	ds_write_b16_d16_hi v4, v52 offset:32688
	v_add_f32_e32 v48, v16, v24
	v_sub_f32_e32 v48, v48, v32
	v_add_f32_e32 v48, v48, v33
	v_sub_f32_e32 v48, v48, v34
	v_add_f32_e32 v48, v48, v35
	v_sub_f32_e32 v48, v48, v36
	v_add_f32_e32 v48, v48, v37
	v_sub_f32_e32 v48, v48, v38
	v_mul_f32_e32 v50, v48, v215
	v_mul_f32_e32 v51, v48, v223
	v_sub_f32_e32 v51, 0, v51
	v_cvt_pk_bf16_f32 v52, v50, v51
	ds_write_b16 v4, v52 offset:37296
	ds_write_b16_d16_hi v4, v52 offset:41904
	s_waitcnt lgkmcnt(0)
	s_barrier
	s_add_u32 s8, s36, 4096
	s_addc_u32 s9, s37, 0
	ds_read_b128 v[20:23], v5 offset:0
	s_waitcnt lgkmcnt(0)
	global_store_dwordx4 v7, v[20:23], s[8:9]
	s_add_u32 s8, s8, 0x100000
	s_addc_u32 s9, s9, 0
	ds_read_b128 v[24:27], v5 offset:9216
	s_waitcnt lgkmcnt(0)
	global_store_dwordx4 v7, v[24:27], s[8:9]
	s_add_u32 s8, s8, 0x100000
	s_addc_u32 s9, s9, 0
	ds_read_b128 v[28:31], v5 offset:18432
	s_waitcnt lgkmcnt(0)
	global_store_dwordx4 v7, v[28:31], s[8:9]
	s_add_u32 s8, s8, 0x100000
	s_addc_u32 s9, s9, 0
	ds_read_b128 v[32:35], v5 offset:27648
	s_waitcnt lgkmcnt(0)
	global_store_dwordx4 v7, v[32:35], s[8:9]
	s_add_u32 s8, s8, 0x100000
	s_addc_u32 s9, s9, 0
	ds_read_b128 v[20:23], v6 offset:0
	s_waitcnt lgkmcnt(0)
	global_store_dwordx4 v7, v[20:23], s[8:9]
	s_add_u32 s8, s8, 0x100000
	s_addc_u32 s9, s9, 0
	ds_read_b128 v[24:27], v6 offset:9216
	s_waitcnt lgkmcnt(0)
	global_store_dwordx4 v7, v[24:27], s[8:9]
	s_add_u32 s8, s8, 0x100000
	s_addc_u32 s9, s9, 0
	ds_read_b128 v[28:31], v6 offset:18432
	s_waitcnt lgkmcnt(0)
	global_store_dwordx4 v7, v[28:31], s[8:9]
	s_add_u32 s8, s8, 0x100000
	s_addc_u32 s9, s9, 0
	ds_read_b128 v[32:35], v6 offset:27648
	s_waitcnt lgkmcnt(0)
	global_store_dwordx4 v7, v[32:35], s[8:9]
	s_add_u32 s8, s8, 0x100000
	s_addc_u32 s9, s9, 0
	ds_read_b128 v[20:23], v6 offset:36864
	s_waitcnt lgkmcnt(0)
	global_store_dwordx4 v7, v[20:23], s[8:9]
